# GEMM K-loops phases 4/8: m0/readfirstlane prep of the stage loads hoisted above the post-MMA barrier (as the compiler did for phases 3/7)
# baseline (speedup 1.0000x reference)
; #define STAGE(P, BASE, br, kt) STAGET(tid_, P, BASE, br, kt)
; #define LDA(dst, b, h) UFOR(m, 4) UFOR(k, 2) \
;     dst[m][k] = *reinterpret_cast<const bf16x8*>((char*)SA(b, h) + lds_byte(wr * 64 + m * 16 + fr, k * 32 + fq * 8))
; #define LDB(dst, b, h) UFOR(n, 2) UFOR(k, 2) \
;     dst[n][k] = *reinterpret_cast<const bf16x8*>((char*)SB(b, h) + lds_byte(wc * 32 + n * 16 + fr, k * 32 + fq * 8))
; #define MMA(ai, bj, At, Bq) do { __builtin_amdgcn_s_setprio(1); \
;     UFOR(m, 4) UFOR(n, 2) UFOR(k, 2) \
;       acc[ai][bj][m][n] = __builtin_amdgcn_mfma_f32_16x16x32_bf16(Bq[n][k], At[m][k], acc[ai][bj][m][n], 0, 0, 0); \
;     __builtin_amdgcn_s_setprio(0); } while (0)
; #define WAIT_V(n) asm volatile("s_waitcnt vmcnt(" #n ")" ::: "memory")
; #define WAIT_L(n) asm volatile("s_waitcnt lgkmcnt(" #n ")" ::: "memory")
; #define BAR __builtin_amdgcn_s_barrier()
; #define SCHED __builtin_amdgcn_sched_barrier(0)
; template <int EPI, int K, int KL> ...
;     ...
;     LDB(B0, 0, 0); SCHED; LDA(At, 0, 0); STAGE(SA(1, 1), A, brow + HALF, t + 1);
;     WAIT_L(8); BAR; WAIT_L(0); MMA(0, 0, At, B0); BAR; SCHED;
;     LDB(B1, 0, 1); STAGE(SB(0, 0), Bt, bcol, t + 2);
;     BAR; WAIT_L(0); MMA(0, 1, At, B1); BAR;
;     LDA(At, 0, 1); STAGE(SA(0, 0), A, brow, t + 2);
;     BAR; WAIT_L(0); MMA(1, 0, At, B0); BAR; SCHED;
;     STAGE(SB(0, 1), Bt, bcol + HALF, t + 2);
;     WAIT_V(6); BAR; MMA(1, 1, At, B1); BAR;
.LBB0_236:
	ds_read_b128 v[174:177], v170
	ds_read_b128 v[178:181], v170 offset:1024
	ds_read_b128 v[182:185], v170 offset:2048
	ds_read_b128 v[186:189], v170 offset:3072
	ds_read_b128 v[190:193], v162
	ds_read_b128 v[194:197], v162 offset:1024
	ds_read_b128 v[198:201], v161
	ds_read_b128 v[202:205], v161 offset:1024
	ds_read_b128 v[218:221], v160
	ds_read_b128 v[222:225], v160 offset:1024
	ds_read_b128 v[226:229], v159
	ds_read_b128 v[230:233], v159 offset:1024
	v_add_u32_e32 v171, 0xc000, v157
	v_lshl_add_u64 v[136:137], s[92:93], 0, v[150:151]
	v_readfirstlane_b32 s18, v171
	v_lshl_add_u64 v[138:139], v[136:137], 0, s[88:89]
	s_mov_b32 m0, s18
	v_add_u32_e32 v172, 0xe000, v157
	global_load_lds_dwordx4 v[138:139], off
	v_lshl_add_u64 v[138:139], s[92:93], 0, v[152:153]
	v_readfirstlane_b32 s18, v172
	v_lshl_add_u64 v[208:209], v[138:139], 0, s[88:89]
	s_mov_b32 m0, s18
	s_nop 0
	global_load_lds_dwordx4 v[208:209], off
	s_waitcnt lgkmcnt(8)
	s_barrier
	s_waitcnt lgkmcnt(0)
	s_waitcnt lgkmcnt(0)
	v_mfma_f32_16x16x32_bf16 v[124:127], v[174:177], v[190:193], v[124:127]
	v_mfma_f32_16x16x32_bf16 v[120:123], v[182:185], v[190:193], v[120:123]
	v_mfma_f32_16x16x32_bf16 v[116:119], v[174:177], v[198:201], v[116:119]
	v_mfma_f32_16x16x32_bf16 v[112:115], v[182:185], v[198:201], v[112:115]
	v_mfma_f32_16x16x32_bf16 v[108:111], v[174:177], v[218:221], v[108:111]
	v_mfma_f32_16x16x32_bf16 v[104:107], v[182:185], v[218:221], v[104:107]
	v_mfma_f32_16x16x32_bf16 v[100:103], v[174:177], v[226:229], v[100:103]
	v_mfma_f32_16x16x32_bf16 v[96:99], v[182:185], v[226:229], v[96:99]
	v_mfma_f32_16x16x32_bf16 v[124:127], v[178:181], v[194:197], v[124:127]
	v_mfma_f32_16x16x32_bf16 v[120:123], v[186:189], v[194:197], v[120:123]
	v_mfma_f32_16x16x32_bf16 v[116:119], v[178:181], v[202:205], v[116:119]
	v_mfma_f32_16x16x32_bf16 v[112:115], v[186:189], v[202:205], v[112:115]
	v_mfma_f32_16x16x32_bf16 v[108:111], v[178:181], v[222:225], v[108:111]
	v_mfma_f32_16x16x32_bf16 v[104:107], v[186:189], v[222:225], v[104:107]
	v_mfma_f32_16x16x32_bf16 v[100:103], v[178:181], v[230:233], v[100:103]
	v_mfma_f32_16x16x32_bf16 v[96:99], v[186:189], v[230:233], v[96:99]
	s_barrier
	ds_read_b128 v[234:237], v168
	ds_read_b128 v[238:241], v168 offset:1024
	ds_read_b128 v[242:245], v168 offset:2048
	ds_read_b128 v[246:249], v168 offset:3072
	v_lshl_add_u64 v[208:209], s[92:93], 0, v[146:147]
	v_readfirstlane_b32 s18, v156
	v_lshl_add_u64 v[210:211], v[208:209], 0, s[52:53]
	s_mov_b32 m0, s18
	v_add_u32_e32 v134, 0x2000, v156
	global_load_lds_dwordx4 v[210:211], off
	v_lshl_add_u64 v[210:211], s[92:93], 0, v[148:149]
	v_readfirstlane_b32 s18, v134
	v_lshl_add_u64 v[214:215], v[210:211], 0, s[52:53]
	s_mov_b32 m0, s18
	s_nop 0
	global_load_lds_dwordx4 v[214:215], off
	s_barrier
	s_waitcnt lgkmcnt(0)
	s_waitcnt lgkmcnt(0)
	v_mfma_f32_16x16x32_bf16 v[92:95], v[234:237], v[190:193], v[92:95]
	v_mfma_f32_16x16x32_bf16 v[88:91], v[242:245], v[190:193], v[88:91]
	v_mfma_f32_16x16x32_bf16 v[84:87], v[234:237], v[198:201], v[84:87]
	v_mfma_f32_16x16x32_bf16 v[80:83], v[242:245], v[198:201], v[80:83]
	v_mfma_f32_16x16x32_bf16 v[76:79], v[234:237], v[218:221], v[76:79]
	v_mfma_f32_16x16x32_bf16 v[72:75], v[242:245], v[218:221], v[72:75]
	v_mfma_f32_16x16x32_bf16 v[68:71], v[234:237], v[226:229], v[68:71]
	v_mfma_f32_16x16x32_bf16 v[64:67], v[242:245], v[226:229], v[64:67]
	v_mfma_f32_16x16x32_bf16 v[92:95], v[238:241], v[194:197], v[92:95]
	v_mfma_f32_16x16x32_bf16 v[88:91], v[246:249], v[194:197], v[88:91]
	v_mfma_f32_16x16x32_bf16 v[84:87], v[238:241], v[202:205], v[84:87]
	v_mfma_f32_16x16x32_bf16 v[80:83], v[246:249], v[202:205], v[80:83]
	v_mfma_f32_16x16x32_bf16 v[76:79], v[238:241], v[222:225], v[76:79]
	v_mfma_f32_16x16x32_bf16 v[72:75], v[246:249], v[222:225], v[72:75]
	v_mfma_f32_16x16x32_bf16 v[68:71], v[238:241], v[230:233], v[68:71]
	v_mfma_f32_16x16x32_bf16 v[64:67], v[246:249], v[230:233], v[64:67]
	v_readfirstlane_b32 s18, v157
	v_add_u32_e32 v134, 0x2000, v157
	v_lshl_add_u64 v[214:215], v[136:137], 0, s[8:9]
	s_mov_b32 m0, s18
	v_readfirstlane_b32 s18, v134
	s_barrier
	ds_read_b128 v[190:193], v162 offset:16384
	ds_read_b128 v[194:197], v162 offset:17408
	ds_read_b128 v[198:201], v161 offset:16384
	ds_read_b128 v[202:205], v161 offset:17408
	ds_read_b128 v[218:221], v160 offset:16384
	ds_read_b128 v[222:225], v160 offset:17408
	ds_read_b128 v[226:229], v159 offset:16384
	ds_read_b128 v[230:233], v159 offset:17408
	global_load_lds_dwordx4 v[214:215], off
	v_lshl_add_u64 v[214:215], v[138:139], 0, s[8:9]
	s_mov_b32 m0, s18
	s_nop 0
	global_load_lds_dwordx4 v[214:215], off
	s_barrier
	s_waitcnt lgkmcnt(0)
	s_waitcnt lgkmcnt(0)
	v_mfma_f32_16x16x32_bf16 v[60:63], v[174:177], v[190:193], v[60:63]
	v_mfma_f32_16x16x32_bf16 v[56:59], v[182:185], v[190:193], v[56:59]
	v_mfma_f32_16x16x32_bf16 v[52:55], v[174:177], v[198:201], v[52:55]
	v_mfma_f32_16x16x32_bf16 v[48:51], v[182:185], v[198:201], v[48:51]
	v_mfma_f32_16x16x32_bf16 v[44:47], v[174:177], v[218:221], v[44:47]
	v_mfma_f32_16x16x32_bf16 v[40:43], v[182:185], v[218:221], v[40:43]
	v_mfma_f32_16x16x32_bf16 v[36:39], v[174:177], v[226:229], v[36:39]
	v_mfma_f32_16x16x32_bf16 v[32:35], v[182:185], v[226:229], v[32:35]
	v_mfma_f32_16x16x32_bf16 v[60:63], v[178:181], v[194:197], v[60:63]
	v_mfma_f32_16x16x32_bf16 v[56:59], v[186:189], v[194:197], v[56:59]
	v_mfma_f32_16x16x32_bf16 v[52:55], v[178:181], v[202:205], v[52:55]
	v_mfma_f32_16x16x32_bf16 v[48:51], v[186:189], v[202:205], v[48:51]
	v_mfma_f32_16x16x32_bf16 v[44:47], v[178:181], v[222:225], v[44:47]
	v_mfma_f32_16x16x32_bf16 v[40:43], v[186:189], v[222:225], v[40:43]
	v_mfma_f32_16x16x32_bf16 v[36:39], v[178:181], v[230:233], v[36:39]
	v_mfma_f32_16x16x32_bf16 v[32:35], v[186:189], v[230:233], v[32:35]
	v_readfirstlane_b32 s18, v158
	v_add_u32_e32 v134, 0x2000, v158
	s_mov_b32 m0, s18
	v_readfirstlane_b32 s18, v134
	s_barrier
; #define STAGE(P, BASE, br, kt) STAGET(tid_, P, BASE, br, kt)
; #define LDA(dst, b, h) UFOR(m, 4) UFOR(k, 2) \
;     dst[m][k] = *reinterpret_cast<const bf16x8*>((char*)SA(b, h) + lds_byte(wr * 64 + m * 16 + fr, k * 32 + fq * 8))
; #define LDB(dst, b, h) UFOR(n, 2) UFOR(k, 2) \
;     dst[n][k] = *reinterpret_cast<const bf16x8*>((char*)SB(b, h) + lds_byte(wc * 32 + n * 16 + fr, k * 32 + fq * 8))
; #define MMA(ai, bj, At, Bq) do { __builtin_amdgcn_s_setprio(1); \
;     UFOR(m, 4) UFOR(n, 2) UFOR(k, 2) \
;       acc[ai][bj][m][n] = __builtin_amdgcn_mfma_f32_16x16x32_bf16(Bq[n][k], At[m][k], acc[ai][bj][m][n], 0, 0, 0); \
;     __builtin_amdgcn_s_setprio(0); } while (0)
; #define WAIT_V(n) asm volatile("s_waitcnt vmcnt(" #n ")" ::: "memory")
; #define WAIT_L(n) asm volatile("s_waitcnt lgkmcnt(" #n ")" ::: "memory")
; #define BAR __builtin_amdgcn_s_barrier()
; #define SCHED __builtin_amdgcn_sched_barrier(0)
; template <int EPI, int K, int KL> ...
;     ...
;     STAGE(SB(0, 1), Bt, bcol + HALF, t + 2);
;     WAIT_V(6); BAR; MMA(1, 1, At, B1); BAR;
;     LDB(B0, 1, 0); SCHED; LDA(At, 1, 0); STAGE(SA(0, 1), A, brow + HALF, t + 2);
;     WAIT_L(8); BAR; WAIT_L(0); MMA(0, 0, At, B0); BAR; SCHED;
;     LDB(B1, 1, 1); STAGE(SB(1, 0), Bt, bcol, t + 3);
;     BAR; WAIT_L(0); MMA(0, 1, At, B1); BAR;
;     LDA(At, 1, 1); STAGE(SA(1, 0), A, brow, t + 3);
;     BAR; WAIT_L(0); MMA(1, 0, At, B0); BAR; SCHED;
;     STAGE(SB(1, 1), Bt, bcol + HALF, t + 3);
;     WAIT_V(6); BAR; MMA(1, 1, At, B1); BAR;
	v_lshl_add_u64 v[174:175], v[208:209], 0, s[54:55]
	global_load_lds_dwordx4 v[174:175], off
	v_lshl_add_u64 v[174:175], v[210:211], 0, s[54:55]
	s_mov_b32 m0, s18
	s_nop 0
	global_load_lds_dwordx4 v[174:175], off
	s_waitcnt vmcnt(6)
	s_barrier
	v_mfma_f32_16x16x32_bf16 v[28:31], v[234:237], v[190:193], v[28:31]
	v_mfma_f32_16x16x32_bf16 v[24:27], v[242:245], v[190:193], v[24:27]
	v_mfma_f32_16x16x32_bf16 v[20:23], v[234:237], v[198:201], v[20:23]
	v_mfma_f32_16x16x32_bf16 v[16:19], v[242:245], v[198:201], v[16:19]
	v_mfma_f32_16x16x32_bf16 v[12:15], v[234:237], v[218:221], v[12:15]
	v_mfma_f32_16x16x32_bf16 v[8:11], v[242:245], v[218:221], v[8:11]
	v_mfma_f32_16x16x32_bf16 v[4:7], v[234:237], v[226:229], v[4:7]
	v_mfma_f32_16x16x32_bf16 v[0:3], v[242:245], v[226:229], v[0:3]
	v_mfma_f32_16x16x32_bf16 v[28:31], v[238:241], v[194:197], v[28:31]
	v_mfma_f32_16x16x32_bf16 v[24:27], v[246:249], v[194:197], v[24:27]
	v_mfma_f32_16x16x32_bf16 v[20:23], v[238:241], v[202:205], v[20:23]
	v_mfma_f32_16x16x32_bf16 v[16:19], v[246:249], v[202:205], v[16:19]
	v_mfma_f32_16x16x32_bf16 v[12:15], v[238:241], v[222:225], v[12:15]
	v_mfma_f32_16x16x32_bf16 v[8:11], v[246:249], v[222:225], v[8:11]
	v_mfma_f32_16x16x32_bf16 v[4:7], v[238:241], v[230:233], v[4:7]
	v_mfma_f32_16x16x32_bf16 v[0:3], v[246:249], v[230:233], v[0:3]
	s_barrier
	ds_read_b128 v[174:177], v164
	ds_read_b128 v[178:181], v164 offset:1024
	ds_read_b128 v[182:185], v164 offset:2048
	ds_read_b128 v[186:189], v164 offset:3072
	ds_read_b128 v[190:193], v162 offset:32768
	ds_read_b128 v[194:197], v162 offset:33792
	ds_read_b128 v[198:201], v161 offset:32768
	ds_read_b128 v[202:205], v161 offset:33792
	ds_read_b128 v[218:221], v160 offset:32768
	ds_read_b128 v[222:225], v160 offset:33792
	ds_read_b128 v[226:229], v159 offset:32768
	ds_read_b128 v[230:233], v159 offset:33792
	v_add_u32_e32 v134, 0x4000, v157
	v_lshl_add_u64 v[214:215], v[136:137], 0, s[12:13]
	v_readfirstlane_b32 s18, v134
	v_add_u32_e32 v134, 0x6000, v157
	s_mov_b32 m0, s18
	v_readfirstlane_b32 s18, v134
	global_load_lds_dwordx4 v[214:215], off
	v_lshl_add_u64 v[214:215], v[138:139], 0, s[12:13]
	s_mov_b32 m0, s18
	s_nop 0
	global_load_lds_dwordx4 v[214:215], off
	s_waitcnt lgkmcnt(8)
	s_barrier
	s_waitcnt lgkmcnt(0)
	s_waitcnt lgkmcnt(0)
	v_mfma_f32_16x16x32_bf16 v[124:127], v[174:177], v[190:193], v[124:127]
	v_mfma_f32_16x16x32_bf16 v[120:123], v[182:185], v[190:193], v[120:123]
	v_mfma_f32_16x16x32_bf16 v[116:119], v[174:177], v[198:201], v[116:119]
	v_mfma_f32_16x16x32_bf16 v[112:115], v[182:185], v[198:201], v[112:115]
	v_mfma_f32_16x16x32_bf16 v[108:111], v[174:177], v[218:221], v[108:111]
	v_mfma_f32_16x16x32_bf16 v[104:107], v[182:185], v[218:221], v[104:107]
	v_mfma_f32_16x16x32_bf16 v[100:103], v[174:177], v[226:229], v[100:103]
	v_mfma_f32_16x16x32_bf16 v[96:99], v[182:185], v[226:229], v[96:99]
	v_mfma_f32_16x16x32_bf16 v[124:127], v[178:181], v[194:197], v[124:127]
	v_mfma_f32_16x16x32_bf16 v[120:123], v[186:189], v[194:197], v[120:123]
	v_mfma_f32_16x16x32_bf16 v[116:119], v[178:181], v[202:205], v[116:119]
	v_mfma_f32_16x16x32_bf16 v[112:115], v[186:189], v[202:205], v[112:115]
	v_mfma_f32_16x16x32_bf16 v[108:111], v[178:181], v[222:225], v[108:111]
	v_mfma_f32_16x16x32_bf16 v[104:107], v[186:189], v[222:225], v[104:107]
	v_mfma_f32_16x16x32_bf16 v[100:103], v[178:181], v[230:233], v[100:103]
	v_mfma_f32_16x16x32_bf16 v[96:99], v[186:189], v[230:233], v[96:99]
	s_barrier
	ds_read_b128 v[234:237], v163
	ds_read_b128 v[238:241], v163 offset:1024
	ds_read_b128 v[242:245], v163 offset:2048
	ds_read_b128 v[246:249], v163 offset:3072
	v_readfirstlane_b32 s18, v165
	v_add_u32_e32 v134, 0x2000, v165
	v_lshl_add_u64 v[214:215], v[208:209], 0, s[56:57]
	s_mov_b32 m0, s18
	v_readfirstlane_b32 s18, v134
	global_load_lds_dwordx4 v[214:215], off
	v_lshl_add_u64 v[214:215], v[210:211], 0, s[56:57]
	s_mov_b32 m0, s18
	s_nop 0
	global_load_lds_dwordx4 v[214:215], off
	s_barrier
	s_waitcnt lgkmcnt(0)
	s_waitcnt lgkmcnt(0)
	v_mfma_f32_16x16x32_bf16 v[92:95], v[234:237], v[190:193], v[92:95]
	v_mfma_f32_16x16x32_bf16 v[88:91], v[242:245], v[190:193], v[88:91]
	v_mfma_f32_16x16x32_bf16 v[84:87], v[234:237], v[198:201], v[84:87]
	v_mfma_f32_16x16x32_bf16 v[80:83], v[242:245], v[198:201], v[80:83]
	v_mfma_f32_16x16x32_bf16 v[76:79], v[234:237], v[218:221], v[76:79]
	v_mfma_f32_16x16x32_bf16 v[72:75], v[242:245], v[218:221], v[72:75]
	v_mfma_f32_16x16x32_bf16 v[68:71], v[234:237], v[226:229], v[68:71]
	v_mfma_f32_16x16x32_bf16 v[64:67], v[242:245], v[226:229], v[64:67]
	v_mfma_f32_16x16x32_bf16 v[92:95], v[238:241], v[194:197], v[92:95]
	v_mfma_f32_16x16x32_bf16 v[88:91], v[246:249], v[194:197], v[88:91]
	v_mfma_f32_16x16x32_bf16 v[84:87], v[238:241], v[202:205], v[84:87]
	v_mfma_f32_16x16x32_bf16 v[80:83], v[246:249], v[202:205], v[80:83]
	v_mfma_f32_16x16x32_bf16 v[76:79], v[238:241], v[222:225], v[76:79]
	v_mfma_f32_16x16x32_bf16 v[72:75], v[246:249], v[222:225], v[72:75]
	v_mfma_f32_16x16x32_bf16 v[68:71], v[238:241], v[230:233], v[68:71]
	v_mfma_f32_16x16x32_bf16 v[64:67], v[246:249], v[230:233], v[64:67]
	v_readfirstlane_b32 s18, v166
	v_lshl_add_u64 v[136:137], v[136:137], 0, s[16:17]
	s_mov_b32 m0, s18
	v_readfirstlane_b32 s18, v167
	s_barrier
	ds_read_b128 v[190:193], v162 offset:49152
	ds_read_b128 v[194:197], v162 offset:50176
	ds_read_b128 v[198:201], v161 offset:49152
	ds_read_b128 v[202:205], v161 offset:50176
	ds_read_b128 v[218:221], v160 offset:49152
	ds_read_b128 v[222:225], v160 offset:50176
	ds_read_b128 v[226:229], v159 offset:49152
	ds_read_b128 v[230:233], v159 offset:50176
	global_load_lds_dwordx4 v[136:137], off
	v_lshl_add_u64 v[136:137], v[138:139], 0, s[16:17]
	s_mov_b32 m0, s18
	s_nop 0
	global_load_lds_dwordx4 v[136:137], off
	s_barrier
; #define STAGE(P, BASE, br, kt) STAGET(tid_, P, BASE, br, kt)
; #define LDA(dst, b, h) UFOR(m, 4) UFOR(k, 2) \
;     dst[m][k] = *reinterpret_cast<const bf16x8*>((char*)SA(b, h) + lds_byte(wr * 64 + m * 16 + fr, k * 32 + fq * 8))
; #define LDB(dst, b, h) UFOR(n, 2) UFOR(k, 2) \
;     dst[n][k] = *reinterpret_cast<const bf16x8*>((char*)SB(b, h) + lds_byte(wc * 32 + n * 16 + fr, k * 32 + fq * 8))
; #define MMA(ai, bj, At, Bq) do { __builtin_amdgcn_s_setprio(1); \
;     UFOR(m, 4) UFOR(n, 2) UFOR(k, 2) \
;       acc[ai][bj][m][n] = __builtin_amdgcn_mfma_f32_16x16x32_bf16(Bq[n][k], At[m][k], acc[ai][bj][m][n], 0, 0, 0); \
;     __builtin_amdgcn_s_setprio(0); } while (0)
; #define WAIT_V(n) asm volatile("s_waitcnt vmcnt(" #n ")" ::: "memory")
; #define WAIT_L(n) asm volatile("s_waitcnt lgkmcnt(" #n ")" ::: "memory")
; #define BAR __builtin_amdgcn_s_barrier()
; template <int EPI, int K, int KL> ...
;     ...
;     STAGE(SB(1, 1), Bt, bcol + HALF, t + 3);
;     WAIT_V(6); BAR; MMA(1, 1, At, B1); BAR;
;   }
;   { LDB(B0, 0, 0); LDA(At, 0, 0); STAGE(SA(1, 1), A, brow + HALF, nt - 1);
;     BAR; WAIT_L(0); MMA(0, 0, At, B0); BAR;
;     LDB(B1, 0, 1); BAR; WAIT_L(0); MMA(0, 1, At, B1); BAR;
	s_waitcnt lgkmcnt(0)
	s_waitcnt lgkmcnt(0)
	v_mfma_f32_16x16x32_bf16 v[60:63], v[174:177], v[190:193], v[60:63]
	v_mfma_f32_16x16x32_bf16 v[56:59], v[182:185], v[190:193], v[56:59]
	v_mfma_f32_16x16x32_bf16 v[52:55], v[174:177], v[198:201], v[52:55]
	v_mfma_f32_16x16x32_bf16 v[48:51], v[182:185], v[198:201], v[48:51]
	v_mfma_f32_16x16x32_bf16 v[44:47], v[174:177], v[218:221], v[44:47]
	v_mfma_f32_16x16x32_bf16 v[40:43], v[182:185], v[218:221], v[40:43]
	v_mfma_f32_16x16x32_bf16 v[36:39], v[174:177], v[226:229], v[36:39]
	v_mfma_f32_16x16x32_bf16 v[32:35], v[182:185], v[226:229], v[32:35]
	v_mfma_f32_16x16x32_bf16 v[60:63], v[178:181], v[194:197], v[60:63]
	v_mfma_f32_16x16x32_bf16 v[56:59], v[186:189], v[194:197], v[56:59]
	v_mfma_f32_16x16x32_bf16 v[52:55], v[178:181], v[202:205], v[52:55]
	v_mfma_f32_16x16x32_bf16 v[48:51], v[186:189], v[202:205], v[48:51]
	v_mfma_f32_16x16x32_bf16 v[44:47], v[178:181], v[222:225], v[44:47]
	v_mfma_f32_16x16x32_bf16 v[40:43], v[186:189], v[222:225], v[40:43]
	v_mfma_f32_16x16x32_bf16 v[36:39], v[178:181], v[230:233], v[36:39]
	v_mfma_f32_16x16x32_bf16 v[32:35], v[186:189], v[230:233], v[32:35]
	v_readfirstlane_b32 s18, v169
	v_add_u32_e32 v134, 0x2000, v169
	s_mov_b32 m0, s18
	v_readfirstlane_b32 s18, v134
	s_barrier
	v_lshl_add_u64 v[136:137], v[208:209], 0, s[58:59]
	global_load_lds_dwordx4 v[136:137], off
	v_lshl_add_u64 v[136:137], v[210:211], 0, s[58:59]
	s_mov_b32 m0, s18
	s_nop 0
	global_load_lds_dwordx4 v[136:137], off
	s_waitcnt vmcnt(6)
	s_barrier
	v_mfma_f32_16x16x32_bf16 v[28:31], v[234:237], v[190:193], v[28:31]
	v_mfma_f32_16x16x32_bf16 v[24:27], v[242:245], v[190:193], v[24:27]
	v_mfma_f32_16x16x32_bf16 v[20:23], v[234:237], v[198:201], v[20:23]
	v_mfma_f32_16x16x32_bf16 v[16:19], v[242:245], v[198:201], v[16:19]
	v_mfma_f32_16x16x32_bf16 v[12:15], v[234:237], v[218:221], v[12:15]
	v_mfma_f32_16x16x32_bf16 v[8:11], v[242:245], v[218:221], v[8:11]
	v_mfma_f32_16x16x32_bf16 v[4:7], v[234:237], v[226:229], v[4:7]
	v_mfma_f32_16x16x32_bf16 v[0:3], v[242:245], v[226:229], v[0:3]
	v_mfma_f32_16x16x32_bf16 v[28:31], v[238:241], v[194:197], v[28:31]
	v_mfma_f32_16x16x32_bf16 v[24:27], v[246:249], v[194:197], v[24:27]
	v_mfma_f32_16x16x32_bf16 v[20:23], v[238:241], v[202:205], v[20:23]
	v_mfma_f32_16x16x32_bf16 v[16:19], v[246:249], v[202:205], v[16:19]
	v_mfma_f32_16x16x32_bf16 v[12:15], v[238:241], v[222:225], v[12:15]
	v_mfma_f32_16x16x32_bf16 v[8:11], v[246:249], v[222:225], v[8:11]
	v_mfma_f32_16x16x32_bf16 v[4:7], v[238:241], v[230:233], v[4:7]
	v_mfma_f32_16x16x32_bf16 v[0:3], v[246:249], v[230:233], v[0:3]
	s_add_i32 s15, s15, 2
	v_lshl_add_u64 v[146:147], v[146:147], 0, s[20:21]
	v_lshl_add_u64 v[148:149], v[148:149], 0, s[20:21]
	v_lshl_add_u64 v[150:151], v[150:151], 0, s[20:21]
	s_cmp_lt_u32 s15, 28
	v_lshl_add_u64 v[152:153], v[152:153], 0, s[20:21]
	s_cbranch_scc1 .Lkrot_236
	s_barrier
	s_add_u32 s18, s50, 0x80f80
	s_addc_u32 s19, s51, 0
	v_lshl_add_u64 v[136:137], s[18:19], 0, v[140:141]
	v_readfirstlane_b32 s15, v171
	v_lshl_add_u64 v[130:131], v[130:131], 1, v[136:137]
	s_mov_b32 m0, s15
	ds_read_b128 v[146:149], v170
	ds_read_b128 v[150:153], v170 offset:1024
	ds_read_b128 v[174:177], v170 offset:2048
	ds_read_b128 v[178:181], v170 offset:3072
	ds_read_b128 v[182:185], v162
	ds_read_b128 v[186:189], v162 offset:1024
	ds_read_b128 v[190:193], v161
	ds_read_b128 v[194:197], v161 offset:1024
	ds_read_b128 v[198:201], v160
	ds_read_b128 v[202:205], v160 offset:1024
	ds_read_b128 v[218:221], v159
	ds_read_b128 v[222:225], v159 offset:1024
	global_load_lds_dwordx4 v[130:131], off
	v_lshl_add_u64 v[130:131], s[18:19], 0, v[144:145]
	v_readfirstlane_b32 s15, v172
	v_lshl_add_u64 v[130:131], v[142:143], 1, v[130:131]
	s_mov_b32 m0, s15
	s_nop 0
	global_load_lds_dwordx4 v[130:131], off
	s_barrier
	s_waitcnt lgkmcnt(0)
	s_waitcnt lgkmcnt(0)
	v_mfma_f32_16x16x32_bf16 v[124:127], v[146:149], v[182:185], v[124:127]
	v_mfma_f32_16x16x32_bf16 v[120:123], v[174:177], v[182:185], v[120:123]
	v_mfma_f32_16x16x32_bf16 v[116:119], v[146:149], v[190:193], v[116:119]
	v_mfma_f32_16x16x32_bf16 v[112:115], v[174:177], v[190:193], v[112:115]
	v_mfma_f32_16x16x32_bf16 v[108:111], v[146:149], v[198:201], v[108:111]
	v_mfma_f32_16x16x32_bf16 v[104:107], v[174:177], v[198:201], v[104:107]
	v_mfma_f32_16x16x32_bf16 v[100:103], v[146:149], v[218:221], v[100:103]
	v_mfma_f32_16x16x32_bf16 v[96:99], v[174:177], v[218:221], v[96:99]
	v_mfma_f32_16x16x32_bf16 v[124:127], v[150:153], v[186:189], v[124:127]
	v_mfma_f32_16x16x32_bf16 v[120:123], v[178:181], v[186:189], v[120:123]
	v_mfma_f32_16x16x32_bf16 v[116:119], v[150:153], v[194:197], v[116:119]
	v_mfma_f32_16x16x32_bf16 v[112:115], v[178:181], v[194:197], v[112:115]
	v_mfma_f32_16x16x32_bf16 v[108:111], v[150:153], v[202:205], v[108:111]
	v_mfma_f32_16x16x32_bf16 v[104:107], v[178:181], v[202:205], v[104:107]
	v_mfma_f32_16x16x32_bf16 v[100:103], v[150:153], v[222:225], v[100:103]
	v_mfma_f32_16x16x32_bf16 v[96:99], v[178:181], v[222:225], v[96:99]
	s_barrier
	ds_read_b128 v[140:143], v168
	ds_read_b128 v[170:173], v168 offset:1024
	ds_read_b128 v[226:229], v168 offset:2048
	ds_read_b128 v[166:169], v168 offset:3072
	s_barrier
; #define LDA(dst, b, h) UFOR(m, 4) UFOR(k, 2) \
;     dst[m][k] = *reinterpret_cast<const bf16x8*>((char*)SA(b, h) + lds_byte(wr * 64 + m * 16 + fr, k * 32 + fq * 8))
; #define LDB(dst, b, h) UFOR(n, 2) UFOR(k, 2) \
;     dst[n][k] = *reinterpret_cast<const bf16x8*>((char*)SB(b, h) + lds_byte(wc * 32 + n * 16 + fr, k * 32 + fq * 8))
; #define MMA(ai, bj, At, Bq) do { __builtin_amdgcn_s_setprio(1); \
;     UFOR(m, 4) UFOR(n, 2) UFOR(k, 2) \
;       acc[ai][bj][m][n] = __builtin_amdgcn_mfma_f32_16x16x32_bf16(Bq[n][k], At[m][k], acc[ai][bj][m][n], 0, 0, 0); \
;     __builtin_amdgcn_s_setprio(0); } while (0)
; #define WAIT_V(n) asm volatile("s_waitcnt vmcnt(" #n ")" ::: "memory")
; #define WAIT_L(n) asm volatile("s_waitcnt lgkmcnt(" #n ")" ::: "memory")
; #define BAR __builtin_amdgcn_s_barrier()
; template <int EPI, int K, int KL> ...
;     ...
;     LDB(B1, 0, 1); BAR; WAIT_L(0); MMA(0, 1, At, B1); BAR;
;     LDA(At, 0, 1); WAIT_V(4); BAR; WAIT_L(0); MMA(1, 0, At, B0); MMA(1, 1, At, B1); BAR; }
;   { LDB(B0, 1, 0); LDA(At, 1, 0); WAIT_V(2); BAR; WAIT_L(0); MMA(0, 0, At, B0); BAR;
;     LDB(B1, 1, 1); WAIT_V(0); BAR; WAIT_L(0); MMA(0, 1, At, B1); BAR;
	s_waitcnt lgkmcnt(0)
	s_waitcnt lgkmcnt(0)
	v_mfma_f32_16x16x32_bf16 v[92:95], v[140:143], v[182:185], v[92:95]
	v_mfma_f32_16x16x32_bf16 v[88:91], v[226:229], v[182:185], v[88:91]
	v_mfma_f32_16x16x32_bf16 v[84:87], v[140:143], v[190:193], v[84:87]
	v_mfma_f32_16x16x32_bf16 v[80:83], v[226:229], v[190:193], v[80:83]
	v_mfma_f32_16x16x32_bf16 v[76:79], v[140:143], v[198:201], v[76:79]
	v_mfma_f32_16x16x32_bf16 v[72:75], v[226:229], v[198:201], v[72:75]
	v_mfma_f32_16x16x32_bf16 v[68:71], v[140:143], v[218:221], v[68:71]
	v_mfma_f32_16x16x32_bf16 v[64:67], v[226:229], v[218:221], v[64:67]
	v_mfma_f32_16x16x32_bf16 v[92:95], v[170:173], v[186:189], v[92:95]
	v_mfma_f32_16x16x32_bf16 v[88:91], v[166:169], v[186:189], v[88:91]
	v_mfma_f32_16x16x32_bf16 v[84:87], v[170:173], v[194:197], v[84:87]
	v_mfma_f32_16x16x32_bf16 v[80:83], v[166:169], v[194:197], v[80:83]
	v_mfma_f32_16x16x32_bf16 v[76:79], v[170:173], v[202:205], v[76:79]
	v_mfma_f32_16x16x32_bf16 v[72:75], v[166:169], v[202:205], v[72:75]
	v_mfma_f32_16x16x32_bf16 v[68:71], v[170:173], v[222:225], v[68:71]
	v_mfma_f32_16x16x32_bf16 v[64:67], v[166:169], v[222:225], v[64:67]
	s_barrier
	ds_read_b128 v[182:185], v162 offset:16384
	ds_read_b128 v[186:189], v162 offset:17408
	ds_read_b128 v[190:193], v161 offset:16384
	ds_read_b128 v[194:197], v161 offset:17408
	ds_read_b128 v[198:201], v160 offset:16384
	ds_read_b128 v[202:205], v160 offset:17408
	ds_read_b128 v[218:221], v159 offset:16384
	ds_read_b128 v[222:225], v159 offset:17408
	s_waitcnt vmcnt(4)
	s_barrier
	s_waitcnt lgkmcnt(0)
	s_waitcnt lgkmcnt(0)
	v_mfma_f32_16x16x32_bf16 v[60:63], v[146:149], v[182:185], v[60:63]
	v_mfma_f32_16x16x32_bf16 v[56:59], v[174:177], v[182:185], v[56:59]
	v_mfma_f32_16x16x32_bf16 v[52:55], v[146:149], v[190:193], v[52:55]
	v_mfma_f32_16x16x32_bf16 v[48:51], v[174:177], v[190:193], v[48:51]
	v_mfma_f32_16x16x32_bf16 v[44:47], v[146:149], v[198:201], v[44:47]
	v_mfma_f32_16x16x32_bf16 v[40:43], v[174:177], v[198:201], v[40:43]
	v_mfma_f32_16x16x32_bf16 v[36:39], v[146:149], v[218:221], v[36:39]
	v_mfma_f32_16x16x32_bf16 v[32:35], v[174:177], v[218:221], v[32:35]
	v_mfma_f32_16x16x32_bf16 v[60:63], v[150:153], v[186:189], v[60:63]
	v_mfma_f32_16x16x32_bf16 v[56:59], v[178:181], v[186:189], v[56:59]
	v_mfma_f32_16x16x32_bf16 v[52:55], v[150:153], v[194:197], v[52:55]
	v_mfma_f32_16x16x32_bf16 v[48:51], v[178:181], v[194:197], v[48:51]
	v_mfma_f32_16x16x32_bf16 v[44:47], v[150:153], v[202:205], v[44:47]
	v_mfma_f32_16x16x32_bf16 v[40:43], v[178:181], v[202:205], v[40:43]
	v_mfma_f32_16x16x32_bf16 v[36:39], v[150:153], v[222:225], v[36:39]
	v_mfma_f32_16x16x32_bf16 v[32:35], v[178:181], v[222:225], v[32:35]
	v_mfma_f32_16x16x32_bf16 v[28:31], v[140:143], v[182:185], v[28:31]
	v_mfma_f32_16x16x32_bf16 v[24:27], v[226:229], v[182:185], v[24:27]
	v_mfma_f32_16x16x32_bf16 v[20:23], v[140:143], v[190:193], v[20:23]
	v_mfma_f32_16x16x32_bf16 v[16:19], v[226:229], v[190:193], v[16:19]
	v_mfma_f32_16x16x32_bf16 v[12:15], v[140:143], v[198:201], v[12:15]
	v_mfma_f32_16x16x32_bf16 v[8:11], v[226:229], v[198:201], v[8:11]
	v_mfma_f32_16x16x32_bf16 v[4:7], v[140:143], v[218:221], v[4:7]
	v_mfma_f32_16x16x32_bf16 v[0:3], v[226:229], v[218:221], v[0:3]
	v_mfma_f32_16x16x32_bf16 v[28:31], v[170:173], v[186:189], v[28:31]
	v_mfma_f32_16x16x32_bf16 v[24:27], v[166:169], v[186:189], v[24:27]
	v_mfma_f32_16x16x32_bf16 v[20:23], v[170:173], v[194:197], v[20:23]
	v_mfma_f32_16x16x32_bf16 v[16:19], v[166:169], v[194:197], v[16:19]
	v_mfma_f32_16x16x32_bf16 v[12:15], v[170:173], v[202:205], v[12:15]
	v_mfma_f32_16x16x32_bf16 v[8:11], v[166:169], v[202:205], v[8:11]
	v_mfma_f32_16x16x32_bf16 v[4:7], v[170:173], v[222:225], v[4:7]
	v_mfma_f32_16x16x32_bf16 v[0:3], v[166:169], v[222:225], v[0:3]
	s_barrier
	ds_read_b128 v[140:143], v164
	ds_read_b128 v[144:147], v164 offset:1024
	ds_read_b128 v[148:151], v164 offset:2048
	ds_read_b128 v[164:167], v164 offset:3072
	ds_read_b128 v[168:171], v162 offset:32768
	ds_read_b128 v[172:175], v162 offset:33792
	ds_read_b128 v[176:179], v161 offset:32768
	ds_read_b128 v[180:183], v161 offset:33792
	ds_read_b128 v[184:187], v160 offset:32768
	ds_read_b128 v[188:191], v160 offset:33792
	ds_read_b128 v[192:195], v159 offset:32768
	ds_read_b128 v[196:199], v159 offset:33792
	s_waitcnt vmcnt(2)
	s_barrier
; #define LDA(dst, b, h) UFOR(m, 4) UFOR(k, 2) \
;     dst[m][k] = *reinterpret_cast<const bf16x8*>((char*)SA(b, h) + lds_byte(wr * 64 + m * 16 + fr, k * 32 + fq * 8))
; #define LDB(dst, b, h) UFOR(n, 2) UFOR(k, 2) \
;     dst[n][k] = *reinterpret_cast<const bf16x8*>((char*)SB(b, h) + lds_byte(wc * 32 + n * 16 + fr, k * 32 + fq * 8))
; #define MMA(ai, bj, At, Bq) do { __builtin_amdgcn_s_setprio(1); \
;     UFOR(m, 4) UFOR(n, 2) UFOR(k, 2) \
;       acc[ai][bj][m][n] = __builtin_amdgcn_mfma_f32_16x16x32_bf16(Bq[n][k], At[m][k], acc[ai][bj][m][n], 0, 0, 0); \
;     __builtin_amdgcn_s_setprio(0); } while (0)
; #define WAIT_V(n) asm volatile("s_waitcnt vmcnt(" #n ")" ::: "memory")
; #define WAIT_L(n) asm volatile("s_waitcnt lgkmcnt(" #n ")" ::: "memory")
; #define BAR __builtin_amdgcn_s_barrier()
; template <int EPI, int K, int KL> ...
;     ...
;   { LDB(B0, 1, 0); LDA(At, 1, 0); WAIT_V(2); BAR; WAIT_L(0); MMA(0, 0, At, B0); BAR;
;     LDB(B1, 1, 1); WAIT_V(0); BAR; WAIT_L(0); MMA(0, 1, At, B1); BAR;
;     LDA(At, 1, 1); BAR; WAIT_L(0); MMA(1, 0, At, B0); MMA(1, 1, At, B1); BAR; }
;   if (wr == 0) BAR;
	s_waitcnt lgkmcnt(0)
	s_waitcnt lgkmcnt(0)
	v_mfma_f32_16x16x32_bf16 v[124:127], v[140:143], v[168:171], v[124:127]
	v_mfma_f32_16x16x32_bf16 v[120:123], v[148:151], v[168:171], v[120:123]
	v_mfma_f32_16x16x32_bf16 v[116:119], v[140:143], v[176:179], v[116:119]
	v_mfma_f32_16x16x32_bf16 v[112:115], v[148:151], v[176:179], v[112:115]
	v_mfma_f32_16x16x32_bf16 v[108:111], v[140:143], v[184:187], v[108:111]
	v_mfma_f32_16x16x32_bf16 v[104:107], v[148:151], v[184:187], v[104:107]
	v_mfma_f32_16x16x32_bf16 v[100:103], v[140:143], v[192:195], v[100:103]
	v_mfma_f32_16x16x32_bf16 v[96:99], v[148:151], v[192:195], v[96:99]
	v_mfma_f32_16x16x32_bf16 v[124:127], v[144:147], v[172:175], v[124:127]
	v_mfma_f32_16x16x32_bf16 v[120:123], v[164:167], v[172:175], v[120:123]
	v_mfma_f32_16x16x32_bf16 v[116:119], v[144:147], v[180:183], v[116:119]
	v_mfma_f32_16x16x32_bf16 v[112:115], v[164:167], v[180:183], v[112:115]
	v_mfma_f32_16x16x32_bf16 v[108:111], v[144:147], v[188:191], v[108:111]
	v_mfma_f32_16x16x32_bf16 v[104:107], v[164:167], v[188:191], v[104:107]
	v_mfma_f32_16x16x32_bf16 v[100:103], v[144:147], v[196:199], v[100:103]
	v_mfma_f32_16x16x32_bf16 v[96:99], v[164:167], v[196:199], v[96:99]
	s_barrier
	ds_read_b128 v[200:203], v163
	ds_read_b128 v[218:221], v163 offset:1024
	ds_read_b128 v[222:225], v163 offset:2048
	ds_read_b128 v[226:229], v163 offset:3072
	s_waitcnt vmcnt(0)
	s_barrier
	s_waitcnt lgkmcnt(0)
	s_waitcnt lgkmcnt(0)
	v_mfma_f32_16x16x32_bf16 v[92:95], v[200:203], v[168:171], v[92:95]
	v_mfma_f32_16x16x32_bf16 v[88:91], v[222:225], v[168:171], v[88:91]
	v_mfma_f32_16x16x32_bf16 v[84:87], v[200:203], v[176:179], v[84:87]
	v_mfma_f32_16x16x32_bf16 v[80:83], v[222:225], v[176:179], v[80:83]
	v_mfma_f32_16x16x32_bf16 v[76:79], v[200:203], v[184:187], v[76:79]
	v_mfma_f32_16x16x32_bf16 v[72:75], v[222:225], v[184:187], v[72:75]
	v_mfma_f32_16x16x32_bf16 v[68:71], v[200:203], v[192:195], v[68:71]
	v_mfma_f32_16x16x32_bf16 v[64:67], v[222:225], v[192:195], v[64:67]
	v_mfma_f32_16x16x32_bf16 v[92:95], v[218:221], v[172:175], v[92:95]
	v_mfma_f32_16x16x32_bf16 v[88:91], v[226:229], v[172:175], v[88:91]
	v_mfma_f32_16x16x32_bf16 v[84:87], v[218:221], v[180:183], v[84:87]
	v_mfma_f32_16x16x32_bf16 v[80:83], v[226:229], v[180:183], v[80:83]
	v_mfma_f32_16x16x32_bf16 v[76:79], v[218:221], v[188:191], v[76:79]
	v_mfma_f32_16x16x32_bf16 v[72:75], v[226:229], v[188:191], v[72:75]
	v_mfma_f32_16x16x32_bf16 v[68:71], v[218:221], v[196:199], v[68:71]
	v_mfma_f32_16x16x32_bf16 v[64:67], v[226:229], v[196:199], v[64:67]
	s_barrier
	ds_read_b128 v[168:171], v162 offset:49152
	ds_read_b128 v[172:175], v162 offset:50176
	ds_read_b128 v[176:179], v161 offset:49152
	ds_read_b128 v[180:183], v161 offset:50176
	ds_read_b128 v[184:187], v160 offset:49152
	ds_read_b128 v[160:163], v160 offset:50176
	ds_read_b128 v[188:191], v159 offset:49152
	ds_read_b128 v[156:159], v159 offset:50176
	s_barrier
	s_waitcnt lgkmcnt(0)
	s_waitcnt lgkmcnt(0)
	v_mfma_f32_16x16x32_bf16 v[60:63], v[140:143], v[168:171], v[60:63]
	v_mfma_f32_16x16x32_bf16 v[56:59], v[148:151], v[168:171], v[56:59]
	v_mfma_f32_16x16x32_bf16 v[52:55], v[140:143], v[176:179], v[52:55]
	v_mfma_f32_16x16x32_bf16 v[48:51], v[148:151], v[176:179], v[48:51]
	v_mfma_f32_16x16x32_bf16 v[44:47], v[140:143], v[184:187], v[44:47]
	v_mfma_f32_16x16x32_bf16 v[40:43], v[148:151], v[184:187], v[40:43]
	v_mfma_f32_16x16x32_bf16 v[36:39], v[140:143], v[188:191], v[36:39]
	v_mfma_f32_16x16x32_bf16 v[32:35], v[148:151], v[188:191], v[32:35]
	v_mfma_f32_16x16x32_bf16 v[60:63], v[144:147], v[172:175], v[60:63]
	v_mfma_f32_16x16x32_bf16 v[56:59], v[164:167], v[172:175], v[56:59]
	v_mfma_f32_16x16x32_bf16 v[52:55], v[144:147], v[180:183], v[52:55]
	v_mfma_f32_16x16x32_bf16 v[48:51], v[164:167], v[180:183], v[48:51]
	v_mfma_f32_16x16x32_bf16 v[44:47], v[144:147], v[160:163], v[44:47]
	v_mfma_f32_16x16x32_bf16 v[40:43], v[164:167], v[160:163], v[40:43]
	v_mfma_f32_16x16x32_bf16 v[36:39], v[144:147], v[156:159], v[36:39]
	v_mfma_f32_16x16x32_bf16 v[32:35], v[164:167], v[156:159], v[32:35]
	v_mfma_f32_16x16x32_bf16 v[28:31], v[200:203], v[168:171], v[28:31]
	v_mfma_f32_16x16x32_bf16 v[24:27], v[222:225], v[168:171], v[24:27]
	v_mfma_f32_16x16x32_bf16 v[20:23], v[200:203], v[176:179], v[20:23]
	v_mfma_f32_16x16x32_bf16 v[16:19], v[222:225], v[176:179], v[16:19]
	v_mfma_f32_16x16x32_bf16 v[12:15], v[200:203], v[184:187], v[12:15]
	v_mfma_f32_16x16x32_bf16 v[8:11], v[222:225], v[184:187], v[8:11]
	v_mfma_f32_16x16x32_bf16 v[4:7], v[200:203], v[188:191], v[4:7]
	v_mfma_f32_16x16x32_bf16 v[0:3], v[222:225], v[188:191], v[0:3]
	v_mfma_f32_16x16x32_bf16 v[28:31], v[218:221], v[172:175], v[28:31]
	v_mfma_f32_16x16x32_bf16 v[24:27], v[226:229], v[172:175], v[24:27]
	v_mfma_f32_16x16x32_bf16 v[20:23], v[218:221], v[180:183], v[20:23]
	v_mfma_f32_16x16x32_bf16 v[16:19], v[226:229], v[180:183], v[16:19]
	v_mfma_f32_16x16x32_bf16 v[12:15], v[218:221], v[160:163], v[12:15]
	v_mfma_f32_16x16x32_bf16 v[8:11], v[226:229], v[160:163], v[8:11]
	v_mfma_f32_16x16x32_bf16 v[4:7], v[218:221], v[156:159], v[4:7]
	v_mfma_f32_16x16x32_bf16 v[0:3], v[226:229], v[156:159], v[0:3]
	s_movk_i32 s15, 0x100
	v_cmp_gt_u32_e32 vcc, s15, v129
	s_barrier
	s_and_saveexec_b64 s[50:51], vcc
	s_cbranch_execz .LBB0_239
	s_barrier

; #define STAGE(P, BASE, br, kt) STAGET(tid_, P, BASE, br, kt)
; #define LDA(dst, b, h) UFOR(m, 4) UFOR(k, 2) \
;     dst[m][k] = *reinterpret_cast<const bf16x8*>((char*)SA(b, h) + lds_byte(wr * 64 + m * 16 + fr, k * 32 + fq * 8))
; #define LDB(dst, b, h) UFOR(n, 2) UFOR(k, 2) \
;     dst[n][k] = *reinterpret_cast<const bf16x8*>((char*)SB(b, h) + lds_byte(wc * 32 + n * 16 + fr, k * 32 + fq * 8))
; #define MMA(ai, bj, At, Bq) do { __builtin_amdgcn_s_setprio(1); \
;     UFOR(m, 4) UFOR(n, 2) UFOR(k, 2) \
;       acc[ai][bj][m][n] = __builtin_amdgcn_mfma_f32_16x16x32_bf16(Bq[n][k], At[m][k], acc[ai][bj][m][n], 0, 0, 0); \
;     __builtin_amdgcn_s_setprio(0); } while (0)
; #define WAIT_V(n) asm volatile("s_waitcnt vmcnt(" #n ")" ::: "memory")
; #define WAIT_L(n) asm volatile("s_waitcnt lgkmcnt(" #n ")" ::: "memory")
; #define BAR __builtin_amdgcn_s_barrier()
; #define SCHED __builtin_amdgcn_sched_barrier(0)
; template <int EPI, int K, int KL> ...
;     ...
;     LDB(B0, 0, 0); SCHED; LDA(At, 0, 0); STAGE(SA(1, 1), A, brow + HALF, t + 1);
;     WAIT_L(8); BAR; WAIT_L(0); MMA(0, 0, At, B0); BAR; SCHED;
;     LDB(B1, 0, 1); STAGE(SB(0, 0), Bt, bcol, t + 2);
;     BAR; WAIT_L(0); MMA(0, 1, At, B1); BAR;
;     LDA(At, 0, 1); STAGE(SA(0, 0), A, brow, t + 2);
;     BAR; WAIT_L(0); MMA(1, 0, At, B0); BAR; SCHED;
;     STAGE(SB(0, 1), Bt, bcol + HALF, t + 2);
;     WAIT_V(6); BAR; MMA(1, 1, At, B1); BAR;
.LBB0_940:
	ds_read_b128 v[174:177], v170
	ds_read_b128 v[178:181], v170 offset:1024
	ds_read_b128 v[182:185], v170 offset:2048
	ds_read_b128 v[186:189], v170 offset:3072
	ds_read_b128 v[190:193], v162
	ds_read_b128 v[194:197], v162 offset:1024
	ds_read_b128 v[198:201], v161
	ds_read_b128 v[202:205], v161 offset:1024
	ds_read_b128 v[218:221], v160
	ds_read_b128 v[222:225], v160 offset:1024
	ds_read_b128 v[226:229], v159
	ds_read_b128 v[230:233], v159 offset:1024
	v_add_u32_e32 v171, 0xc000, v157
	v_lshl_add_u64 v[136:137], s[92:93], 0, v[148:149]
	v_readfirstlane_b32 s60, v171
	v_lshl_add_u64 v[138:139], v[136:137], 0, s[88:89]
	s_mov_b32 m0, s60
	v_add_u32_e32 v172, 0xe000, v157
	global_load_lds_dwordx4 v[138:139], off
	v_lshl_add_u64 v[138:139], s[92:93], 0, v[150:151]
	v_readfirstlane_b32 s60, v172
	v_lshl_add_u64 v[208:209], v[138:139], 0, s[88:89]
	s_mov_b32 m0, s60
	s_nop 0
	global_load_lds_dwordx4 v[208:209], off
	s_waitcnt lgkmcnt(8)
	s_barrier
	s_waitcnt lgkmcnt(0)
	s_waitcnt lgkmcnt(0)
	v_mfma_f32_16x16x32_bf16 v[124:127], v[174:177], v[190:193], v[124:127]
	v_mfma_f32_16x16x32_bf16 v[120:123], v[182:185], v[190:193], v[120:123]
	v_mfma_f32_16x16x32_bf16 v[116:119], v[174:177], v[198:201], v[116:119]
	v_mfma_f32_16x16x32_bf16 v[112:115], v[182:185], v[198:201], v[112:115]
	v_mfma_f32_16x16x32_bf16 v[108:111], v[174:177], v[218:221], v[108:111]
	v_mfma_f32_16x16x32_bf16 v[104:107], v[182:185], v[218:221], v[104:107]
	v_mfma_f32_16x16x32_bf16 v[100:103], v[174:177], v[226:229], v[100:103]
	v_mfma_f32_16x16x32_bf16 v[96:99], v[182:185], v[226:229], v[96:99]
	v_mfma_f32_16x16x32_bf16 v[124:127], v[178:181], v[194:197], v[124:127]
	v_mfma_f32_16x16x32_bf16 v[120:123], v[186:189], v[194:197], v[120:123]
	v_mfma_f32_16x16x32_bf16 v[116:119], v[178:181], v[202:205], v[116:119]
	v_mfma_f32_16x16x32_bf16 v[112:115], v[186:189], v[202:205], v[112:115]
	v_mfma_f32_16x16x32_bf16 v[108:111], v[178:181], v[222:225], v[108:111]
	v_mfma_f32_16x16x32_bf16 v[104:107], v[186:189], v[222:225], v[104:107]
	v_mfma_f32_16x16x32_bf16 v[100:103], v[178:181], v[230:233], v[100:103]
	v_mfma_f32_16x16x32_bf16 v[96:99], v[186:189], v[230:233], v[96:99]
	s_barrier
	ds_read_b128 v[234:237], v168
	ds_read_b128 v[238:241], v168 offset:1024
	ds_read_b128 v[242:245], v168 offset:2048
	ds_read_b128 v[246:249], v168 offset:3072
	v_lshl_add_u64 v[208:209], s[92:93], 0, v[144:145]
	v_readfirstlane_b32 s60, v156
	v_lshl_add_u64 v[210:211], v[208:209], 0, s[62:63]
	s_mov_b32 m0, s60
	v_add_u32_e32 v134, 0x2000, v156
	global_load_lds_dwordx4 v[210:211], off
	v_lshl_add_u64 v[210:211], s[92:93], 0, v[146:147]
	v_readfirstlane_b32 s60, v134
	v_lshl_add_u64 v[214:215], v[210:211], 0, s[62:63]
	s_mov_b32 m0, s60
	s_nop 0
	global_load_lds_dwordx4 v[214:215], off
	s_barrier
	s_waitcnt lgkmcnt(0)
	s_waitcnt lgkmcnt(0)
	v_mfma_f32_16x16x32_bf16 v[92:95], v[234:237], v[190:193], v[92:95]
	v_mfma_f32_16x16x32_bf16 v[88:91], v[242:245], v[190:193], v[88:91]
	v_mfma_f32_16x16x32_bf16 v[84:87], v[234:237], v[198:201], v[84:87]
	v_mfma_f32_16x16x32_bf16 v[80:83], v[242:245], v[198:201], v[80:83]
	v_mfma_f32_16x16x32_bf16 v[76:79], v[234:237], v[218:221], v[76:79]
	v_mfma_f32_16x16x32_bf16 v[72:75], v[242:245], v[218:221], v[72:75]
	v_mfma_f32_16x16x32_bf16 v[68:71], v[234:237], v[226:229], v[68:71]
	v_mfma_f32_16x16x32_bf16 v[64:67], v[242:245], v[226:229], v[64:67]
	v_mfma_f32_16x16x32_bf16 v[92:95], v[238:241], v[194:197], v[92:95]
	v_mfma_f32_16x16x32_bf16 v[88:91], v[246:249], v[194:197], v[88:91]
	v_mfma_f32_16x16x32_bf16 v[84:87], v[238:241], v[202:205], v[84:87]
	v_mfma_f32_16x16x32_bf16 v[80:83], v[246:249], v[202:205], v[80:83]
	v_mfma_f32_16x16x32_bf16 v[76:79], v[238:241], v[222:225], v[76:79]
	v_mfma_f32_16x16x32_bf16 v[72:75], v[246:249], v[222:225], v[72:75]
	v_mfma_f32_16x16x32_bf16 v[68:71], v[238:241], v[230:233], v[68:71]
	v_mfma_f32_16x16x32_bf16 v[64:67], v[246:249], v[230:233], v[64:67]
	v_readfirstlane_b32 s60, v157
	v_add_u32_e32 v134, 0x2000, v157
	v_lshl_add_u64 v[214:215], v[136:137], 0, s[8:9]
	s_mov_b32 m0, s60
	v_readfirstlane_b32 s60, v134
	s_barrier
	ds_read_b128 v[190:193], v162 offset:16384
	ds_read_b128 v[194:197], v162 offset:17408
	ds_read_b128 v[198:201], v161 offset:16384
	ds_read_b128 v[202:205], v161 offset:17408
	ds_read_b128 v[218:221], v160 offset:16384
	ds_read_b128 v[222:225], v160 offset:17408
	ds_read_b128 v[226:229], v159 offset:16384
	ds_read_b128 v[230:233], v159 offset:17408
	global_load_lds_dwordx4 v[214:215], off
	v_lshl_add_u64 v[214:215], v[138:139], 0, s[8:9]
	s_mov_b32 m0, s60
	s_nop 0
	global_load_lds_dwordx4 v[214:215], off
	s_barrier
	s_waitcnt lgkmcnt(0)
	s_waitcnt lgkmcnt(0)
	v_mfma_f32_16x16x32_bf16 v[60:63], v[174:177], v[190:193], v[60:63]
	v_mfma_f32_16x16x32_bf16 v[56:59], v[182:185], v[190:193], v[56:59]
	v_mfma_f32_16x16x32_bf16 v[52:55], v[174:177], v[198:201], v[52:55]
	v_mfma_f32_16x16x32_bf16 v[48:51], v[182:185], v[198:201], v[48:51]
	v_mfma_f32_16x16x32_bf16 v[44:47], v[174:177], v[218:221], v[44:47]
	v_mfma_f32_16x16x32_bf16 v[40:43], v[182:185], v[218:221], v[40:43]
	v_mfma_f32_16x16x32_bf16 v[36:39], v[174:177], v[226:229], v[36:39]
	v_mfma_f32_16x16x32_bf16 v[32:35], v[182:185], v[226:229], v[32:35]
	v_mfma_f32_16x16x32_bf16 v[60:63], v[178:181], v[194:197], v[60:63]
	v_mfma_f32_16x16x32_bf16 v[56:59], v[186:189], v[194:197], v[56:59]
	v_mfma_f32_16x16x32_bf16 v[52:55], v[178:181], v[202:205], v[52:55]
	v_mfma_f32_16x16x32_bf16 v[48:51], v[186:189], v[202:205], v[48:51]
	v_mfma_f32_16x16x32_bf16 v[44:47], v[178:181], v[222:225], v[44:47]
	v_mfma_f32_16x16x32_bf16 v[40:43], v[186:189], v[222:225], v[40:43]
	v_mfma_f32_16x16x32_bf16 v[36:39], v[178:181], v[230:233], v[36:39]
	v_mfma_f32_16x16x32_bf16 v[32:35], v[186:189], v[230:233], v[32:35]
	v_readfirstlane_b32 s60, v158
	v_add_u32_e32 v134, 0x2000, v158
	s_mov_b32 m0, s60
	v_readfirstlane_b32 s60, v134
	s_barrier
; #define STAGE(P, BASE, br, kt) STAGET(tid_, P, BASE, br, kt)
; #define LDA(dst, b, h) UFOR(m, 4) UFOR(k, 2) \
;     dst[m][k] = *reinterpret_cast<const bf16x8*>((char*)SA(b, h) + lds_byte(wr * 64 + m * 16 + fr, k * 32 + fq * 8))
; #define LDB(dst, b, h) UFOR(n, 2) UFOR(k, 2) \
;     dst[n][k] = *reinterpret_cast<const bf16x8*>((char*)SB(b, h) + lds_byte(wc * 32 + n * 16 + fr, k * 32 + fq * 8))
; #define MMA(ai, bj, At, Bq) do { __builtin_amdgcn_s_setprio(1); \
;     UFOR(m, 4) UFOR(n, 2) UFOR(k, 2) \
;       acc[ai][bj][m][n] = __builtin_amdgcn_mfma_f32_16x16x32_bf16(Bq[n][k], At[m][k], acc[ai][bj][m][n], 0, 0, 0); \
;     __builtin_amdgcn_s_setprio(0); } while (0)
; #define WAIT_V(n) asm volatile("s_waitcnt vmcnt(" #n ")" ::: "memory")
; #define WAIT_L(n) asm volatile("s_waitcnt lgkmcnt(" #n ")" ::: "memory")
; #define BAR __builtin_amdgcn_s_barrier()
; #define SCHED __builtin_amdgcn_sched_barrier(0)
; template <int EPI, int K, int KL> ...
;     ...
;     STAGE(SB(0, 1), Bt, bcol + HALF, t + 2);
;     WAIT_V(6); BAR; MMA(1, 1, At, B1); BAR;
;     LDB(B0, 1, 0); SCHED; LDA(At, 1, 0); STAGE(SA(0, 1), A, brow + HALF, t + 2);
;     WAIT_L(8); BAR; WAIT_L(0); MMA(0, 0, At, B0); BAR; SCHED;
;     LDB(B1, 1, 1); STAGE(SB(1, 0), Bt, bcol, t + 3);
;     BAR; WAIT_L(0); MMA(0, 1, At, B1); BAR;
;     LDA(At, 1, 1); STAGE(SA(1, 0), A, brow, t + 3);
;     BAR; WAIT_L(0); MMA(1, 0, At, B0); BAR; SCHED;
;     STAGE(SB(1, 1), Bt, bcol + HALF, t + 3);
;     WAIT_V(6); BAR; MMA(1, 1, At, B1); BAR;
	v_lshl_add_u64 v[174:175], v[208:209], 0, s[66:67]
	global_load_lds_dwordx4 v[174:175], off
	v_lshl_add_u64 v[174:175], v[210:211], 0, s[66:67]
	s_mov_b32 m0, s60
	s_nop 0
	global_load_lds_dwordx4 v[174:175], off
	s_waitcnt vmcnt(6)
	s_barrier
	v_mfma_f32_16x16x32_bf16 v[28:31], v[234:237], v[190:193], v[28:31]
	v_mfma_f32_16x16x32_bf16 v[24:27], v[242:245], v[190:193], v[24:27]
	v_mfma_f32_16x16x32_bf16 v[20:23], v[234:237], v[198:201], v[20:23]
	v_mfma_f32_16x16x32_bf16 v[16:19], v[242:245], v[198:201], v[16:19]
	v_mfma_f32_16x16x32_bf16 v[12:15], v[234:237], v[218:221], v[12:15]
	v_mfma_f32_16x16x32_bf16 v[8:11], v[242:245], v[218:221], v[8:11]
	v_mfma_f32_16x16x32_bf16 v[4:7], v[234:237], v[226:229], v[4:7]
	v_mfma_f32_16x16x32_bf16 v[0:3], v[242:245], v[226:229], v[0:3]
	v_mfma_f32_16x16x32_bf16 v[28:31], v[238:241], v[194:197], v[28:31]
	v_mfma_f32_16x16x32_bf16 v[24:27], v[246:249], v[194:197], v[24:27]
	v_mfma_f32_16x16x32_bf16 v[20:23], v[238:241], v[202:205], v[20:23]
	v_mfma_f32_16x16x32_bf16 v[16:19], v[246:249], v[202:205], v[16:19]
	v_mfma_f32_16x16x32_bf16 v[12:15], v[238:241], v[222:225], v[12:15]
	v_mfma_f32_16x16x32_bf16 v[8:11], v[246:249], v[222:225], v[8:11]
	v_mfma_f32_16x16x32_bf16 v[4:7], v[238:241], v[230:233], v[4:7]
	v_mfma_f32_16x16x32_bf16 v[0:3], v[246:249], v[230:233], v[0:3]
	s_barrier
	ds_read_b128 v[174:177], v165
	ds_read_b128 v[178:181], v165 offset:1024
	ds_read_b128 v[182:185], v165 offset:2048
	ds_read_b128 v[186:189], v165 offset:3072
	ds_read_b128 v[190:193], v162 offset:32768
	ds_read_b128 v[194:197], v162 offset:33792
	ds_read_b128 v[198:201], v161 offset:32768
	ds_read_b128 v[202:205], v161 offset:33792
	ds_read_b128 v[218:221], v160 offset:32768
	ds_read_b128 v[222:225], v160 offset:33792
	ds_read_b128 v[226:229], v159 offset:32768
	ds_read_b128 v[230:233], v159 offset:33792
	v_add_u32_e32 v134, 0x4000, v157
	v_lshl_add_u64 v[214:215], v[136:137], 0, s[12:13]
	v_readfirstlane_b32 s60, v134
	v_add_u32_e32 v134, 0x6000, v157
	s_mov_b32 m0, s60
	v_readfirstlane_b32 s60, v134
	global_load_lds_dwordx4 v[214:215], off
	v_lshl_add_u64 v[214:215], v[138:139], 0, s[12:13]
	s_mov_b32 m0, s60
	s_nop 0
	global_load_lds_dwordx4 v[214:215], off
	s_waitcnt lgkmcnt(8)
	s_barrier
	s_waitcnt lgkmcnt(0)
	s_waitcnt lgkmcnt(0)
	v_mfma_f32_16x16x32_bf16 v[124:127], v[174:177], v[190:193], v[124:127]
	v_mfma_f32_16x16x32_bf16 v[120:123], v[182:185], v[190:193], v[120:123]
	v_mfma_f32_16x16x32_bf16 v[116:119], v[174:177], v[198:201], v[116:119]
	v_mfma_f32_16x16x32_bf16 v[112:115], v[182:185], v[198:201], v[112:115]
	v_mfma_f32_16x16x32_bf16 v[108:111], v[174:177], v[218:221], v[108:111]
	v_mfma_f32_16x16x32_bf16 v[104:107], v[182:185], v[218:221], v[104:107]
	v_mfma_f32_16x16x32_bf16 v[100:103], v[174:177], v[226:229], v[100:103]
	v_mfma_f32_16x16x32_bf16 v[96:99], v[182:185], v[226:229], v[96:99]
	v_mfma_f32_16x16x32_bf16 v[124:127], v[178:181], v[194:197], v[124:127]
	v_mfma_f32_16x16x32_bf16 v[120:123], v[186:189], v[194:197], v[120:123]
	v_mfma_f32_16x16x32_bf16 v[116:119], v[178:181], v[202:205], v[116:119]
	v_mfma_f32_16x16x32_bf16 v[112:115], v[186:189], v[202:205], v[112:115]
	v_mfma_f32_16x16x32_bf16 v[108:111], v[178:181], v[222:225], v[108:111]
	v_mfma_f32_16x16x32_bf16 v[104:107], v[186:189], v[222:225], v[104:107]
	v_mfma_f32_16x16x32_bf16 v[100:103], v[178:181], v[230:233], v[100:103]
	v_mfma_f32_16x16x32_bf16 v[96:99], v[186:189], v[230:233], v[96:99]
	s_barrier
	ds_read_b128 v[234:237], v163
	ds_read_b128 v[238:241], v163 offset:1024
	ds_read_b128 v[242:245], v163 offset:2048
	ds_read_b128 v[246:249], v163 offset:3072
	v_readfirstlane_b32 s60, v164
	v_add_u32_e32 v134, 0x2000, v164
	v_lshl_add_u64 v[214:215], v[208:209], 0, s[70:71]
	s_mov_b32 m0, s60
	v_readfirstlane_b32 s60, v134
	global_load_lds_dwordx4 v[214:215], off
	v_lshl_add_u64 v[214:215], v[210:211], 0, s[70:71]
	s_mov_b32 m0, s60
	s_nop 0
	global_load_lds_dwordx4 v[214:215], off
	s_barrier
	s_waitcnt lgkmcnt(0)
	s_waitcnt lgkmcnt(0)
	v_mfma_f32_16x16x32_bf16 v[92:95], v[234:237], v[190:193], v[92:95]
	v_mfma_f32_16x16x32_bf16 v[88:91], v[242:245], v[190:193], v[88:91]
	v_mfma_f32_16x16x32_bf16 v[84:87], v[234:237], v[198:201], v[84:87]
	v_mfma_f32_16x16x32_bf16 v[80:83], v[242:245], v[198:201], v[80:83]
	v_mfma_f32_16x16x32_bf16 v[76:79], v[234:237], v[218:221], v[76:79]
	v_mfma_f32_16x16x32_bf16 v[72:75], v[242:245], v[218:221], v[72:75]
	v_mfma_f32_16x16x32_bf16 v[68:71], v[234:237], v[226:229], v[68:71]
	v_mfma_f32_16x16x32_bf16 v[64:67], v[242:245], v[226:229], v[64:67]
	v_mfma_f32_16x16x32_bf16 v[92:95], v[238:241], v[194:197], v[92:95]
	v_mfma_f32_16x16x32_bf16 v[88:91], v[246:249], v[194:197], v[88:91]
	v_mfma_f32_16x16x32_bf16 v[84:87], v[238:241], v[202:205], v[84:87]
	v_mfma_f32_16x16x32_bf16 v[80:83], v[246:249], v[202:205], v[80:83]
	v_mfma_f32_16x16x32_bf16 v[76:79], v[238:241], v[222:225], v[76:79]
	v_mfma_f32_16x16x32_bf16 v[72:75], v[246:249], v[222:225], v[72:75]
	v_mfma_f32_16x16x32_bf16 v[68:71], v[238:241], v[230:233], v[68:71]
	v_mfma_f32_16x16x32_bf16 v[64:67], v[246:249], v[230:233], v[64:67]
	v_readfirstlane_b32 s60, v166
	v_lshl_add_u64 v[136:137], v[136:137], 0, s[16:17]
	s_mov_b32 m0, s60
	v_readfirstlane_b32 s60, v167
	s_barrier
	ds_read_b128 v[190:193], v162 offset:49152
	ds_read_b128 v[194:197], v162 offset:50176
	ds_read_b128 v[198:201], v161 offset:49152
	ds_read_b128 v[202:205], v161 offset:50176
	ds_read_b128 v[218:221], v160 offset:49152
	ds_read_b128 v[222:225], v160 offset:50176
	ds_read_b128 v[226:229], v159 offset:49152
	ds_read_b128 v[230:233], v159 offset:50176
	global_load_lds_dwordx4 v[136:137], off
	v_lshl_add_u64 v[136:137], v[138:139], 0, s[16:17]
	s_mov_b32 m0, s60
	s_nop 0
	global_load_lds_dwordx4 v[136:137], off
	s_barrier
; #define STAGE(P, BASE, br, kt) STAGET(tid_, P, BASE, br, kt)
; #define LDA(dst, b, h) UFOR(m, 4) UFOR(k, 2) \
;     dst[m][k] = *reinterpret_cast<const bf16x8*>((char*)SA(b, h) + lds_byte(wr * 64 + m * 16 + fr, k * 32 + fq * 8))
; #define LDB(dst, b, h) UFOR(n, 2) UFOR(k, 2) \
;     dst[n][k] = *reinterpret_cast<const bf16x8*>((char*)SB(b, h) + lds_byte(wc * 32 + n * 16 + fr, k * 32 + fq * 8))
; #define MMA(ai, bj, At, Bq) do { __builtin_amdgcn_s_setprio(1); \
;     UFOR(m, 4) UFOR(n, 2) UFOR(k, 2) \
;       acc[ai][bj][m][n] = __builtin_amdgcn_mfma_f32_16x16x32_bf16(Bq[n][k], At[m][k], acc[ai][bj][m][n], 0, 0, 0); \
;     __builtin_amdgcn_s_setprio(0); } while (0)
; #define WAIT_V(n) asm volatile("s_waitcnt vmcnt(" #n ")" ::: "memory")
; #define WAIT_L(n) asm volatile("s_waitcnt lgkmcnt(" #n ")" ::: "memory")
; #define BAR __builtin_amdgcn_s_barrier()
; template <int EPI, int K, int KL> ...
;     ...
;     STAGE(SB(1, 1), Bt, bcol + HALF, t + 3);
;     WAIT_V(6); BAR; MMA(1, 1, At, B1); BAR;
;   }
;   { LDB(B0, 0, 0); LDA(At, 0, 0); STAGE(SA(1, 1), A, brow + HALF, nt - 1);
;     BAR; WAIT_L(0); MMA(0, 0, At, B0); BAR;
;     LDB(B1, 0, 1); BAR; WAIT_L(0); MMA(0, 1, At, B1); BAR;
	s_waitcnt lgkmcnt(0)
	s_waitcnt lgkmcnt(0)
	v_mfma_f32_16x16x32_bf16 v[60:63], v[174:177], v[190:193], v[60:63]
	v_mfma_f32_16x16x32_bf16 v[56:59], v[182:185], v[190:193], v[56:59]
	v_mfma_f32_16x16x32_bf16 v[52:55], v[174:177], v[198:201], v[52:55]
	v_mfma_f32_16x16x32_bf16 v[48:51], v[182:185], v[198:201], v[48:51]
	v_mfma_f32_16x16x32_bf16 v[44:47], v[174:177], v[218:221], v[44:47]
	v_mfma_f32_16x16x32_bf16 v[40:43], v[182:185], v[218:221], v[40:43]
	v_mfma_f32_16x16x32_bf16 v[36:39], v[174:177], v[226:229], v[36:39]
	v_mfma_f32_16x16x32_bf16 v[32:35], v[182:185], v[226:229], v[32:35]
	v_mfma_f32_16x16x32_bf16 v[60:63], v[178:181], v[194:197], v[60:63]
	v_mfma_f32_16x16x32_bf16 v[56:59], v[186:189], v[194:197], v[56:59]
	v_mfma_f32_16x16x32_bf16 v[52:55], v[178:181], v[202:205], v[52:55]
	v_mfma_f32_16x16x32_bf16 v[48:51], v[186:189], v[202:205], v[48:51]
	v_mfma_f32_16x16x32_bf16 v[44:47], v[178:181], v[222:225], v[44:47]
	v_mfma_f32_16x16x32_bf16 v[40:43], v[186:189], v[222:225], v[40:43]
	v_mfma_f32_16x16x32_bf16 v[36:39], v[178:181], v[230:233], v[36:39]
	v_mfma_f32_16x16x32_bf16 v[32:35], v[186:189], v[230:233], v[32:35]
	v_readfirstlane_b32 s60, v169
	v_add_u32_e32 v134, 0x2000, v169
	s_mov_b32 m0, s60
	v_readfirstlane_b32 s60, v134
	s_barrier
	v_lshl_add_u64 v[136:137], v[208:209], 0, s[74:75]
	global_load_lds_dwordx4 v[136:137], off
	v_lshl_add_u64 v[136:137], v[210:211], 0, s[74:75]
	s_mov_b32 m0, s60
	s_nop 0
	global_load_lds_dwordx4 v[136:137], off
	s_waitcnt vmcnt(6)
	s_barrier
	v_mfma_f32_16x16x32_bf16 v[28:31], v[234:237], v[190:193], v[28:31]
	v_mfma_f32_16x16x32_bf16 v[24:27], v[242:245], v[190:193], v[24:27]
	v_mfma_f32_16x16x32_bf16 v[20:23], v[234:237], v[198:201], v[20:23]
	v_mfma_f32_16x16x32_bf16 v[16:19], v[242:245], v[198:201], v[16:19]
	v_mfma_f32_16x16x32_bf16 v[12:15], v[234:237], v[218:221], v[12:15]
	v_mfma_f32_16x16x32_bf16 v[8:11], v[242:245], v[218:221], v[8:11]
	v_mfma_f32_16x16x32_bf16 v[4:7], v[234:237], v[226:229], v[4:7]
	v_mfma_f32_16x16x32_bf16 v[0:3], v[242:245], v[226:229], v[0:3]
	v_mfma_f32_16x16x32_bf16 v[28:31], v[238:241], v[194:197], v[28:31]
	v_mfma_f32_16x16x32_bf16 v[24:27], v[246:249], v[194:197], v[24:27]
	v_mfma_f32_16x16x32_bf16 v[20:23], v[238:241], v[202:205], v[20:23]
	v_mfma_f32_16x16x32_bf16 v[16:19], v[246:249], v[202:205], v[16:19]
	v_mfma_f32_16x16x32_bf16 v[12:15], v[238:241], v[222:225], v[12:15]
	v_mfma_f32_16x16x32_bf16 v[8:11], v[246:249], v[222:225], v[8:11]
	v_mfma_f32_16x16x32_bf16 v[4:7], v[238:241], v[230:233], v[4:7]
	v_mfma_f32_16x16x32_bf16 v[0:3], v[246:249], v[230:233], v[0:3]
	s_add_i32 s55, s55, 2
	v_lshl_add_u64 v[144:145], v[144:145], 0, s[20:21]
	v_lshl_add_u64 v[146:147], v[146:147], 0, s[20:21]
	v_lshl_add_u64 v[148:149], v[148:149], 0, s[20:21]
	s_cmp_lt_u32 s55, 28
	v_lshl_add_u64 v[150:151], v[150:151], 0, s[20:21]
	s_cbranch_scc1 .Lkrot_940
	s_barrier
	s_add_u32 s58, s58, 0x80f80
	s_addc_u32 s59, s59, 0
	v_lshl_add_u64 v[130:131], s[58:59], 0, v[130:131]
	v_readfirstlane_b32 s55, v171
	v_lshl_add_u64 v[128:129], v[128:129], 1, v[130:131]
	s_mov_b32 m0, s55
	ds_read_b128 v[144:147], v170
	ds_read_b128 v[148:151], v170 offset:1024
	ds_read_b128 v[174:177], v170 offset:2048
	ds_read_b128 v[178:181], v170 offset:3072
	ds_read_b128 v[182:185], v162
	ds_read_b128 v[186:189], v162 offset:1024
	ds_read_b128 v[190:193], v161
	ds_read_b128 v[194:197], v161 offset:1024
	ds_read_b128 v[198:201], v160
	ds_read_b128 v[202:205], v160 offset:1024
	ds_read_b128 v[218:221], v159
	ds_read_b128 v[222:225], v159 offset:1024
	global_load_lds_dwordx4 v[128:129], off
	v_lshl_add_u64 v[128:129], s[58:59], 0, v[142:143]
	v_readfirstlane_b32 s55, v172
	v_lshl_add_u64 v[128:129], v[140:141], 1, v[128:129]
	s_mov_b32 m0, s55
	s_nop 0
	global_load_lds_dwordx4 v[128:129], off
	s_barrier
	s_waitcnt lgkmcnt(0)
	s_waitcnt lgkmcnt(0)
	v_mfma_f32_16x16x32_bf16 v[124:127], v[144:147], v[182:185], v[124:127]
	v_mfma_f32_16x16x32_bf16 v[120:123], v[174:177], v[182:185], v[120:123]
	v_mfma_f32_16x16x32_bf16 v[116:119], v[144:147], v[190:193], v[116:119]
	v_mfma_f32_16x16x32_bf16 v[112:115], v[174:177], v[190:193], v[112:115]
	v_mfma_f32_16x16x32_bf16 v[108:111], v[144:147], v[198:201], v[108:111]
	v_mfma_f32_16x16x32_bf16 v[104:107], v[174:177], v[198:201], v[104:107]
	v_mfma_f32_16x16x32_bf16 v[100:103], v[144:147], v[218:221], v[100:103]
	v_mfma_f32_16x16x32_bf16 v[96:99], v[174:177], v[218:221], v[96:99]
	v_mfma_f32_16x16x32_bf16 v[124:127], v[148:151], v[186:189], v[124:127]
	v_mfma_f32_16x16x32_bf16 v[120:123], v[178:181], v[186:189], v[120:123]
	v_mfma_f32_16x16x32_bf16 v[116:119], v[148:151], v[194:197], v[116:119]
	v_mfma_f32_16x16x32_bf16 v[112:115], v[178:181], v[194:197], v[112:115]
	v_mfma_f32_16x16x32_bf16 v[108:111], v[148:151], v[202:205], v[108:111]
	v_mfma_f32_16x16x32_bf16 v[104:107], v[178:181], v[202:205], v[104:107]
	v_mfma_f32_16x16x32_bf16 v[100:103], v[148:151], v[222:225], v[100:103]
	v_mfma_f32_16x16x32_bf16 v[96:99], v[178:181], v[222:225], v[96:99]
	s_barrier
	ds_read_b128 v[128:131], v168
	ds_read_b128 v[140:143], v168 offset:1024
	ds_read_b128 v[170:173], v168 offset:2048
	ds_read_b128 v[166:169], v168 offset:3072
	s_barrier
; #define LDA(dst, b, h) UFOR(m, 4) UFOR(k, 2) \
;     dst[m][k] = *reinterpret_cast<const bf16x8*>((char*)SA(b, h) + lds_byte(wr * 64 + m * 16 + fr, k * 32 + fq * 8))
; #define LDB(dst, b, h) UFOR(n, 2) UFOR(k, 2) \
;     dst[n][k] = *reinterpret_cast<const bf16x8*>((char*)SB(b, h) + lds_byte(wc * 32 + n * 16 + fr, k * 32 + fq * 8))
; #define MMA(ai, bj, At, Bq) do { __builtin_amdgcn_s_setprio(1); \
;     UFOR(m, 4) UFOR(n, 2) UFOR(k, 2) \
;       acc[ai][bj][m][n] = __builtin_amdgcn_mfma_f32_16x16x32_bf16(Bq[n][k], At[m][k], acc[ai][bj][m][n], 0, 0, 0); \
;     __builtin_amdgcn_s_setprio(0); } while (0)
; #define WAIT_V(n) asm volatile("s_waitcnt vmcnt(" #n ")" ::: "memory")
; #define WAIT_L(n) asm volatile("s_waitcnt lgkmcnt(" #n ")" ::: "memory")
; #define BAR __builtin_amdgcn_s_barrier()
; template <int EPI, int K, int KL> ...
;     ...
;     LDB(B1, 0, 1); BAR; WAIT_L(0); MMA(0, 1, At, B1); BAR;
;     LDA(At, 0, 1); WAIT_V(4); BAR; WAIT_L(0); MMA(1, 0, At, B0); MMA(1, 1, At, B1); BAR; }
;   { LDB(B0, 1, 0); LDA(At, 1, 0); WAIT_V(2); BAR; WAIT_L(0); MMA(0, 0, At, B0); BAR;
;     LDB(B1, 1, 1); WAIT_V(0); BAR; WAIT_L(0); MMA(0, 1, At, B1); BAR;
	s_waitcnt lgkmcnt(0)
	s_waitcnt lgkmcnt(0)
	v_mfma_f32_16x16x32_bf16 v[80:83], v[170:173], v[190:193], v[80:83]
	v_mfma_f32_16x16x32_bf16 v[72:75], v[170:173], v[198:201], v[72:75]
	v_mfma_f32_16x16x32_bf16 v[68:71], v[128:131], v[218:221], v[68:71]
	v_mfma_f32_16x16x32_bf16 v[64:67], v[170:173], v[218:221], v[64:67]
	v_mfma_f32_16x16x32_bf16 v[92:95], v[128:131], v[182:185], v[92:95]
	v_mfma_f32_16x16x32_bf16 v[88:91], v[170:173], v[182:185], v[88:91]
	v_mfma_f32_16x16x32_bf16 v[84:87], v[128:131], v[190:193], v[84:87]
	v_mfma_f32_16x16x32_bf16 v[80:83], v[166:169], v[194:197], v[80:83]
	v_mfma_f32_16x16x32_bf16 v[76:79], v[128:131], v[198:201], v[76:79]
	v_mfma_f32_16x16x32_bf16 v[72:75], v[166:169], v[202:205], v[72:75]
	v_mfma_f32_16x16x32_bf16 v[68:71], v[140:143], v[222:225], v[68:71]
	v_mfma_f32_16x16x32_bf16 v[64:67], v[166:169], v[222:225], v[64:67]
	v_mfma_f32_16x16x32_bf16 v[226:229], v[140:143], v[186:189], v[92:95]
	v_mfma_f32_16x16x32_bf16 v[182:185], v[166:169], v[186:189], v[88:91]
	v_mfma_f32_16x16x32_bf16 v[186:189], v[140:143], v[194:197], v[84:87]
	v_mfma_f32_16x16x32_bf16 v[190:193], v[140:143], v[202:205], v[76:79]
	s_barrier
	s_nop 0
	ds_read_b128 v[76:79], v162 offset:16384
	ds_read_b128 v[84:87], v162 offset:17408
	ds_read_b128 v[88:91], v161 offset:16384
	ds_read_b128 v[92:95], v161 offset:17408
	ds_read_b128 v[194:197], v160 offset:16384
	ds_read_b128 v[198:201], v160 offset:17408
	ds_read_b128 v[202:205], v159 offset:16384
	ds_read_b128 v[218:221], v159 offset:17408
	s_waitcnt vmcnt(4)
	s_barrier
	s_waitcnt lgkmcnt(0)
	s_waitcnt lgkmcnt(0)
	v_mfma_f32_16x16x32_bf16 v[48:51], v[174:177], v[88:91], v[48:51]
	v_mfma_f32_16x16x32_bf16 v[40:43], v[174:177], v[194:197], v[40:43]
	v_mfma_f32_16x16x32_bf16 v[36:39], v[144:147], v[202:205], v[36:39]
	v_mfma_f32_16x16x32_bf16 v[32:35], v[174:177], v[202:205], v[32:35]
	v_mfma_f32_16x16x32_bf16 v[60:63], v[144:147], v[76:79], v[60:63]
	v_mfma_f32_16x16x32_bf16 v[56:59], v[174:177], v[76:79], v[56:59]
	v_mfma_f32_16x16x32_bf16 v[52:55], v[144:147], v[88:91], v[52:55]
	v_mfma_f32_16x16x32_bf16 v[48:51], v[178:181], v[92:95], v[48:51]
	v_mfma_f32_16x16x32_bf16 v[44:47], v[144:147], v[194:197], v[44:47]
	v_mfma_f32_16x16x32_bf16 v[40:43], v[178:181], v[198:201], v[40:43]
	v_mfma_f32_16x16x32_bf16 v[36:39], v[148:151], v[218:221], v[36:39]
	v_mfma_f32_16x16x32_bf16 v[32:35], v[178:181], v[218:221], v[32:35]
	v_mfma_f32_16x16x32_bf16 v[222:225], v[148:151], v[84:87], v[60:63]
	v_mfma_f32_16x16x32_bf16 v[230:233], v[178:181], v[84:87], v[56:59]
	v_mfma_f32_16x16x32_bf16 v[234:237], v[148:151], v[92:95], v[52:55]
	v_mfma_f32_16x16x32_bf16 v[238:241], v[148:151], v[198:201], v[44:47]
	v_mfma_f32_16x16x32_bf16 v[0:3], v[170:173], v[202:205], v[0:3]
	v_mfma_f32_16x16x32_bf16 v[28:31], v[128:131], v[76:79], v[28:31]
	v_mfma_f32_16x16x32_bf16 v[24:27], v[170:173], v[76:79], v[24:27]
	v_mfma_f32_16x16x32_bf16 v[20:23], v[128:131], v[88:91], v[20:23]
	v_mfma_f32_16x16x32_bf16 v[16:19], v[170:173], v[88:91], v[16:19]
	v_mfma_f32_16x16x32_bf16 v[12:15], v[128:131], v[194:197], v[12:15]
	v_mfma_f32_16x16x32_bf16 v[8:11], v[170:173], v[194:197], v[8:11]
	v_mfma_f32_16x16x32_bf16 v[4:7], v[128:131], v[202:205], v[4:7]
	v_mfma_f32_16x16x32_bf16 v[0:3], v[166:169], v[218:221], v[0:3]
	v_mfma_f32_16x16x32_bf16 v[144:147], v[140:143], v[84:87], v[28:31]
	v_mfma_f32_16x16x32_bf16 v[148:151], v[166:169], v[84:87], v[24:27]
	v_mfma_f32_16x16x32_bf16 v[174:177], v[140:143], v[92:95], v[20:23]
	v_mfma_f32_16x16x32_bf16 v[178:181], v[166:169], v[92:95], v[16:19]
	v_mfma_f32_16x16x32_bf16 v[242:245], v[140:143], v[198:201], v[12:15]
	v_mfma_f32_16x16x32_bf16 v[194:197], v[166:169], v[198:201], v[8:11]
	v_mfma_f32_16x16x32_bf16 v[128:131], v[140:143], v[218:221], v[4:7]
	s_barrier
	s_nop 0
	ds_read_b128 v[4:7], v165
	ds_read_b128 v[8:11], v165 offset:1024
	ds_read_b128 v[16:19], v165 offset:2048
	ds_read_b128 v[140:143], v165 offset:3072
	ds_read_b128 v[12:15], v162 offset:32768
	ds_read_b128 v[20:23], v162 offset:33792
	ds_read_b128 v[24:27], v161 offset:32768
	ds_read_b128 v[44:47], v161 offset:33792
	ds_read_b128 v[164:167], v160 offset:32768
	ds_read_b128 v[168:171], v160 offset:33792
	ds_read_b128 v[198:201], v159 offset:32768
	ds_read_b128 v[202:205], v159 offset:33792
	s_waitcnt vmcnt(2)
	s_barrier
; #define LDA(dst, b, h) UFOR(m, 4) UFOR(k, 2) \
;     dst[m][k] = *reinterpret_cast<const bf16x8*>((char*)SA(b, h) + lds_byte(wr * 64 + m * 16 + fr, k * 32 + fq * 8))
; #define LDB(dst, b, h) UFOR(n, 2) UFOR(k, 2) \
;     dst[n][k] = *reinterpret_cast<const bf16x8*>((char*)SB(b, h) + lds_byte(wc * 32 + n * 16 + fr, k * 32 + fq * 8))
; #define MMA(ai, bj, At, Bq) do { __builtin_amdgcn_s_setprio(1); \
;     UFOR(m, 4) UFOR(n, 2) UFOR(k, 2) \
;       acc[ai][bj][m][n] = __builtin_amdgcn_mfma_f32_16x16x32_bf16(Bq[n][k], At[m][k], acc[ai][bj][m][n], 0, 0, 0); \
;     __builtin_amdgcn_s_setprio(0); } while (0)
; #define WAIT_V(n) asm volatile("s_waitcnt vmcnt(" #n ")" ::: "memory")
; #define WAIT_L(n) asm volatile("s_waitcnt lgkmcnt(" #n ")" ::: "memory")
; #define BAR __builtin_amdgcn_s_barrier()
; template <int EPI, int K, int KL> ...
;     ...
;   { LDB(B0, 1, 0); LDA(At, 1, 0); WAIT_V(2); BAR; WAIT_L(0); MMA(0, 0, At, B0); BAR;
;     LDB(B1, 1, 1); WAIT_V(0); BAR; WAIT_L(0); MMA(0, 1, At, B1); BAR;
;     LDA(At, 1, 1); BAR; WAIT_L(0); MMA(1, 0, At, B0); MMA(1, 1, At, B1); BAR; }
;   if (wr == 0) BAR;
	s_waitcnt lgkmcnt(0)
	s_waitcnt lgkmcnt(0)
	v_mfma_f32_16x16x32_bf16 v[28:31], v[4:7], v[12:15], v[124:127]
	v_mfma_f32_16x16x32_bf16 v[124:127], v[8:11], v[20:23], v[28:31]
	v_mfma_f32_16x16x32_bf16 v[28:31], v[16:19], v[12:15], v[120:123]
	v_mfma_f32_16x16x32_bf16 v[92:95], v[140:143], v[20:23], v[28:31]
	v_mfma_f32_16x16x32_bf16 v[28:31], v[4:7], v[24:27], v[116:119]
	v_mfma_f32_16x16x32_bf16 v[120:123], v[8:11], v[44:47], v[28:31]
	v_mfma_f32_16x16x32_bf16 v[28:31], v[16:19], v[24:27], v[112:115]
	v_mfma_f32_16x16x32_bf16 v[88:91], v[140:143], v[44:47], v[28:31]
	v_mfma_f32_16x16x32_bf16 v[28:31], v[4:7], v[164:167], v[108:111]
	v_mfma_f32_16x16x32_bf16 v[116:119], v[8:11], v[168:171], v[28:31]
	v_mfma_f32_16x16x32_bf16 v[28:31], v[16:19], v[164:167], v[104:107]
	v_mfma_f32_16x16x32_bf16 v[84:87], v[140:143], v[168:171], v[28:31]
	v_mfma_f32_16x16x32_bf16 v[28:31], v[4:7], v[198:201], v[100:103]
	v_mfma_f32_16x16x32_bf16 v[108:111], v[8:11], v[202:205], v[28:31]
	v_mfma_f32_16x16x32_bf16 v[28:31], v[16:19], v[198:201], v[96:99]
	v_mfma_f32_16x16x32_bf16 v[76:79], v[140:143], v[202:205], v[28:31]
	s_barrier
	ds_read_b128 v[218:221], v163
	ds_read_b128 v[246:249], v163 offset:1024
	ds_read_b128 v[136:139], v163 offset:2048
	ds_read_b128 v[208:211], v163 offset:3072
	s_waitcnt vmcnt(0)
	s_barrier
	s_waitcnt lgkmcnt(0)
	s_waitcnt lgkmcnt(0)
	v_mfma_f32_16x16x32_bf16 v[28:31], v[218:221], v[12:15], v[226:229]
	v_mfma_f32_16x16x32_bf16 v[12:15], v[136:139], v[12:15], v[182:185]
	v_mfma_f32_16x16x32_bf16 v[60:63], v[246:249], v[20:23], v[28:31]
	v_mfma_f32_16x16x32_bf16 v[28:31], v[208:211], v[20:23], v[12:15]
	v_mfma_f32_16x16x32_bf16 v[12:15], v[218:221], v[24:27], v[186:189]
	v_mfma_f32_16x16x32_bf16 v[56:59], v[246:249], v[44:47], v[12:15]
	v_mfma_f32_16x16x32_bf16 v[12:15], v[136:139], v[24:27], v[80:83]
	v_mfma_f32_16x16x32_bf16 v[24:27], v[208:211], v[44:47], v[12:15]
	v_mfma_f32_16x16x32_bf16 v[12:15], v[218:221], v[164:167], v[190:193]
	v_mfma_f32_16x16x32_bf16 v[52:55], v[246:249], v[168:171], v[12:15]
	v_mfma_f32_16x16x32_bf16 v[12:15], v[136:139], v[164:167], v[72:75]
	v_mfma_f32_16x16x32_bf16 v[20:23], v[208:211], v[168:171], v[12:15]
	v_mfma_f32_16x16x32_bf16 v[12:15], v[218:221], v[198:201], v[68:71]
	v_mfma_f32_16x16x32_bf16 v[44:47], v[246:249], v[202:205], v[12:15]
	v_mfma_f32_16x16x32_bf16 v[12:15], v[136:139], v[198:201], v[64:67]
	v_mfma_f32_16x16x32_bf16 v[12:15], v[208:211], v[202:205], v[12:15]
	s_barrier
	ds_read_b128 v[164:167], v162 offset:49152
	ds_read_b128 v[168:171], v162 offset:50176
	ds_read_b128 v[182:185], v161 offset:49152
	ds_read_b128 v[186:189], v161 offset:50176
	ds_read_b128 v[190:193], v160 offset:49152
	ds_read_b128 v[160:163], v160 offset:50176
	ds_read_b128 v[198:201], v159 offset:49152
	ds_read_b128 v[156:159], v159 offset:50176
	s_barrier
	s_waitcnt lgkmcnt(0)
	s_waitcnt lgkmcnt(0)
	v_mfma_f32_16x16x32_bf16 v[64:67], v[4:7], v[164:167], v[222:225]
	v_mfma_f32_16x16x32_bf16 v[112:115], v[8:11], v[168:171], v[64:67]
	v_mfma_f32_16x16x32_bf16 v[64:67], v[16:19], v[164:167], v[230:233]
	v_mfma_f32_16x16x32_bf16 v[48:51], v[16:19], v[182:185], v[48:51]
	v_mfma_f32_16x16x32_bf16 v[80:83], v[140:143], v[168:171], v[64:67]
	v_mfma_f32_16x16x32_bf16 v[64:67], v[4:7], v[182:185], v[234:237]
	v_mfma_f32_16x16x32_bf16 v[72:75], v[140:143], v[186:189], v[48:51]
	v_mfma_f32_16x16x32_bf16 v[48:51], v[4:7], v[190:193], v[238:241]
	v_mfma_f32_16x16x32_bf16 v[4:7], v[4:7], v[198:201], v[36:39]
	v_mfma_f32_16x16x32_bf16 v[40:43], v[16:19], v[190:193], v[40:43]
	v_mfma_f32_16x16x32_bf16 v[96:99], v[8:11], v[156:159], v[4:7]
	v_mfma_f32_16x16x32_bf16 v[4:7], v[16:19], v[198:201], v[32:35]
	v_mfma_f32_16x16x32_bf16 v[104:107], v[8:11], v[186:189], v[64:67]
	v_mfma_f32_16x16x32_bf16 v[100:103], v[8:11], v[160:163], v[48:51]
	v_mfma_f32_16x16x32_bf16 v[68:71], v[140:143], v[160:163], v[40:43]
	v_mfma_f32_16x16x32_bf16 v[64:67], v[140:143], v[156:159], v[4:7]
	v_mfma_f32_16x16x32_bf16 v[4:7], v[218:221], v[164:167], v[144:147]
	v_mfma_f32_16x16x32_bf16 v[48:51], v[246:249], v[168:171], v[4:7]
	v_mfma_f32_16x16x32_bf16 v[4:7], v[136:139], v[164:167], v[148:151]
	v_mfma_f32_16x16x32_bf16 v[16:19], v[208:211], v[168:171], v[4:7]
	v_mfma_f32_16x16x32_bf16 v[4:7], v[218:221], v[182:185], v[174:177]
	v_mfma_f32_16x16x32_bf16 v[40:43], v[246:249], v[186:189], v[4:7]
	v_mfma_f32_16x16x32_bf16 v[4:7], v[136:139], v[182:185], v[178:181]
	v_mfma_f32_16x16x32_bf16 v[8:11], v[208:211], v[186:189], v[4:7]
	v_mfma_f32_16x16x32_bf16 v[4:7], v[218:221], v[190:193], v[242:245]
	v_mfma_f32_16x16x32_bf16 v[36:39], v[246:249], v[160:163], v[4:7]
	v_mfma_f32_16x16x32_bf16 v[4:7], v[136:139], v[190:193], v[194:197]
	v_mfma_f32_16x16x32_bf16 v[32:35], v[218:221], v[198:201], v[128:131]
	v_mfma_f32_16x16x32_bf16 v[0:3], v[136:139], v[198:201], v[0:3]
	v_mfma_f32_16x16x32_bf16 v[4:7], v[208:211], v[160:163], v[4:7]
	v_mfma_f32_16x16x32_bf16 v[32:35], v[246:249], v[156:159], v[32:35]
	v_mfma_f32_16x16x32_bf16 v[0:3], v[208:211], v[156:159], v[0:3]
	s_movk_i32 s55, 0x100
	v_cmp_gt_u32_e32 vcc, s55, v154
	s_barrier
	s_and_saveexec_b64 s[58:59], vcc
	s_cbranch_execz .LBB0_943
	s_barrier

; #define STAGE(P, BASE, br, kt) STAGET(tid_, P, BASE, br, kt)
; #define LDA(dst, b, h) UFOR(m, 4) UFOR(k, 2) \
;     dst[m][k] = *reinterpret_cast<const bf16x8*>((char*)SA(b, h) + lds_byte(wr * 64 + m * 16 + fr, k * 32 + fq * 8))
; #define LDB(dst, b, h) UFOR(n, 2) UFOR(k, 2) \
;     dst[n][k] = *reinterpret_cast<const bf16x8*>((char*)SB(b, h) + lds_byte(wc * 32 + n * 16 + fr, k * 32 + fq * 8))
; #define MMA(ai, bj, At, Bq) do { __builtin_amdgcn_s_setprio(1); \
;     UFOR(m, 4) UFOR(n, 2) UFOR(k, 2) \
;       acc[ai][bj][m][n] = __builtin_amdgcn_mfma_f32_16x16x32_bf16(Bq[n][k], At[m][k], acc[ai][bj][m][n], 0, 0, 0); \
;     __builtin_amdgcn_s_setprio(0); } while (0)
; #define WAIT_V(n) asm volatile("s_waitcnt vmcnt(" #n ")" ::: "memory")
; #define WAIT_L(n) asm volatile("s_waitcnt lgkmcnt(" #n ")" ::: "memory")
; #define BAR __builtin_amdgcn_s_barrier()
; #define SCHED __builtin_amdgcn_sched_barrier(0)
; template <int EPI, int K, int KL> ...
;     ...
;     LDB(B0, 0, 0); SCHED; LDA(At, 0, 0); STAGE(SA(1, 1), A, brow + HALF, t + 1);
;     WAIT_L(8); BAR; WAIT_L(0); MMA(0, 0, At, B0); BAR; SCHED;
;     LDB(B1, 0, 1); STAGE(SB(0, 0), Bt, bcol, t + 2);
;     BAR; WAIT_L(0); MMA(0, 1, At, B1); BAR;
;     LDA(At, 0, 1); STAGE(SA(0, 0), A, brow, t + 2);
;     BAR; WAIT_L(0); MMA(1, 0, At, B0); BAR; SCHED;
;     STAGE(SB(0, 1), Bt, bcol + HALF, t + 2);
;     WAIT_V(6); BAR; MMA(1, 1, At, B1); BAR;
.LBB0_1107:
	ds_read_b128 v[136:139], v171
	ds_read_b128 v[174:177], v171 offset:1024
	ds_read_b128 v[178:181], v171 offset:2048
	ds_read_b128 v[182:185], v171 offset:3072
	ds_read_b128 v[186:189], v163
	ds_read_b128 v[190:193], v163 offset:1024
	ds_read_b128 v[194:197], v162
	ds_read_b128 v[198:201], v162 offset:1024
	ds_read_b128 v[202:205], v161
	ds_read_b128 v[208:211], v161 offset:1024
	ds_read_b128 v[218:221], v160
	ds_read_b128 v[222:225], v160 offset:1024
	v_add_u32_e32 v172, 0xc000, v158
	v_lshl_add_u64 v[214:215], s[92:93], 0, v[148:149]
	v_readfirstlane_b32 s56, v172
	v_lshl_add_u64 v[216:217], v[214:215], 0, s[88:89]
	s_mov_b32 m0, s56
	v_add_u32_e32 v173, 0xe000, v158
	global_load_lds_dwordx4 v[216:217], off
	v_lshl_add_u64 v[216:217], s[92:93], 0, v[150:151]
	v_readfirstlane_b32 s56, v173
	v_lshl_add_u64 v[226:227], v[216:217], 0, s[88:89]
	s_mov_b32 m0, s56
	s_nop 0
	global_load_lds_dwordx4 v[226:227], off
	s_waitcnt lgkmcnt(8)
	s_barrier
	s_waitcnt lgkmcnt(0)
	s_waitcnt lgkmcnt(0)
	v_mfma_f32_16x16x32_bf16 v[0:3], v[136:139], v[186:189], v[0:3]
	v_mfma_f32_16x16x32_bf16 v[4:7], v[178:181], v[186:189], v[4:7]
	v_mfma_f32_16x16x32_bf16 v[8:11], v[136:139], v[194:197], v[8:11]
	v_mfma_f32_16x16x32_bf16 v[16:19], v[178:181], v[194:197], v[16:19]
	v_mfma_f32_16x16x32_bf16 v[28:31], v[136:139], v[202:205], v[28:31]
	v_mfma_f32_16x16x32_bf16 v[40:43], v[178:181], v[202:205], v[40:43]
	v_mfma_f32_16x16x32_bf16 v[52:55], v[136:139], v[218:221], v[52:55]
	v_mfma_f32_16x16x32_bf16 v[64:67], v[178:181], v[218:221], v[64:67]
	v_mfma_f32_16x16x32_bf16 v[0:3], v[174:177], v[190:193], v[0:3]
	v_mfma_f32_16x16x32_bf16 v[4:7], v[182:185], v[190:193], v[4:7]
	v_mfma_f32_16x16x32_bf16 v[8:11], v[174:177], v[198:201], v[8:11]
	v_mfma_f32_16x16x32_bf16 v[16:19], v[182:185], v[198:201], v[16:19]
	v_mfma_f32_16x16x32_bf16 v[28:31], v[174:177], v[208:211], v[28:31]
	v_mfma_f32_16x16x32_bf16 v[40:43], v[182:185], v[208:211], v[40:43]
	v_mfma_f32_16x16x32_bf16 v[52:55], v[174:177], v[222:225], v[52:55]
	v_mfma_f32_16x16x32_bf16 v[64:67], v[182:185], v[222:225], v[64:67]
	s_barrier
	ds_read_b128 v[226:229], v169
	ds_read_b128 v[230:233], v169 offset:1024
	ds_read_b128 v[234:237], v169 offset:2048
	ds_read_b128 v[238:241], v169 offset:3072
	v_lshl_add_u64 v[242:243], s[92:93], 0, v[144:145]
	v_readfirstlane_b32 s56, v157
	v_lshl_add_u64 v[244:245], v[242:243], 0, s[2:3]
	s_mov_b32 m0, s56
	v_add_u32_e32 v134, 0x2000, v157
	global_load_lds_dwordx4 v[244:245], off
	v_lshl_add_u64 v[244:245], s[92:93], 0, v[146:147]
	v_readfirstlane_b32 s56, v134
	v_lshl_add_u64 v[246:247], v[244:245], 0, s[2:3]
	s_mov_b32 m0, s56
	s_nop 0
	global_load_lds_dwordx4 v[246:247], off
	s_barrier
	s_waitcnt lgkmcnt(0)
	s_waitcnt lgkmcnt(0)
	v_mfma_f32_16x16x32_bf16 v[12:15], v[226:229], v[186:189], v[12:15]
	v_mfma_f32_16x16x32_bf16 v[24:27], v[234:237], v[186:189], v[24:27]
	v_mfma_f32_16x16x32_bf16 v[36:39], v[226:229], v[194:197], v[36:39]
	v_mfma_f32_16x16x32_bf16 v[48:51], v[234:237], v[194:197], v[48:51]
	v_mfma_f32_16x16x32_bf16 v[60:63], v[226:229], v[202:205], v[60:63]
	v_mfma_f32_16x16x32_bf16 v[72:75], v[234:237], v[202:205], v[72:75]
	v_mfma_f32_16x16x32_bf16 v[80:83], v[226:229], v[218:221], v[80:83]
	v_mfma_f32_16x16x32_bf16 v[88:91], v[234:237], v[218:221], v[88:91]
	v_mfma_f32_16x16x32_bf16 v[12:15], v[230:233], v[190:193], v[12:15]
	v_mfma_f32_16x16x32_bf16 v[24:27], v[238:241], v[190:193], v[24:27]
	v_mfma_f32_16x16x32_bf16 v[36:39], v[230:233], v[198:201], v[36:39]
	v_mfma_f32_16x16x32_bf16 v[48:51], v[238:241], v[198:201], v[48:51]
	v_mfma_f32_16x16x32_bf16 v[60:63], v[230:233], v[208:211], v[60:63]
	v_mfma_f32_16x16x32_bf16 v[72:75], v[238:241], v[208:211], v[72:75]
	v_mfma_f32_16x16x32_bf16 v[80:83], v[230:233], v[222:225], v[80:83]
	v_mfma_f32_16x16x32_bf16 v[88:91], v[238:241], v[222:225], v[88:91]
	v_readfirstlane_b32 s56, v158
	v_add_u32_e32 v134, 0x2000, v158
	v_lshl_add_u64 v[246:247], v[214:215], 0, s[8:9]
	s_mov_b32 m0, s56
	v_readfirstlane_b32 s56, v134
	s_barrier
	ds_read_b128 v[186:189], v163 offset:16384
	ds_read_b128 v[190:193], v163 offset:17408
	ds_read_b128 v[194:197], v162 offset:16384
	ds_read_b128 v[198:201], v162 offset:17408
	ds_read_b128 v[202:205], v161 offset:16384
	ds_read_b128 v[208:211], v161 offset:17408
	ds_read_b128 v[218:221], v160 offset:16384
	ds_read_b128 v[222:225], v160 offset:17408
	global_load_lds_dwordx4 v[246:247], off
	v_lshl_add_u64 v[246:247], v[216:217], 0, s[8:9]
	s_mov_b32 m0, s56
	s_nop 0
	global_load_lds_dwordx4 v[246:247], off
	s_barrier
	s_waitcnt lgkmcnt(0)
	s_waitcnt lgkmcnt(0)
	v_mfma_f32_16x16x32_bf16 v[20:23], v[136:139], v[186:189], v[20:23]
	v_mfma_f32_16x16x32_bf16 v[32:35], v[178:181], v[186:189], v[32:35]
	v_mfma_f32_16x16x32_bf16 v[44:47], v[136:139], v[194:197], v[44:47]
	v_mfma_f32_16x16x32_bf16 v[56:59], v[178:181], v[194:197], v[56:59]
	v_mfma_f32_16x16x32_bf16 v[68:71], v[136:139], v[202:205], v[68:71]
	v_mfma_f32_16x16x32_bf16 v[76:79], v[178:181], v[202:205], v[76:79]
	v_mfma_f32_16x16x32_bf16 v[84:87], v[136:139], v[218:221], v[84:87]
	v_mfma_f32_16x16x32_bf16 v[92:95], v[178:181], v[218:221], v[92:95]
	v_mfma_f32_16x16x32_bf16 v[20:23], v[174:177], v[190:193], v[20:23]
	v_mfma_f32_16x16x32_bf16 v[32:35], v[182:185], v[190:193], v[32:35]
	v_mfma_f32_16x16x32_bf16 v[44:47], v[174:177], v[198:201], v[44:47]
	v_mfma_f32_16x16x32_bf16 v[56:59], v[182:185], v[198:201], v[56:59]
	v_mfma_f32_16x16x32_bf16 v[68:71], v[174:177], v[208:211], v[68:71]
	v_mfma_f32_16x16x32_bf16 v[76:79], v[182:185], v[208:211], v[76:79]
	v_mfma_f32_16x16x32_bf16 v[84:87], v[174:177], v[222:225], v[84:87]
	v_mfma_f32_16x16x32_bf16 v[92:95], v[182:185], v[222:225], v[92:95]
	v_readfirstlane_b32 s56, v159
	v_add_u32_e32 v134, 0x2000, v159
	s_mov_b32 m0, s56
	v_readfirstlane_b32 s56, v134
	s_barrier
; #define STAGE(P, BASE, br, kt) STAGET(tid_, P, BASE, br, kt)
; #define LDA(dst, b, h) UFOR(m, 4) UFOR(k, 2) \
;     dst[m][k] = *reinterpret_cast<const bf16x8*>((char*)SA(b, h) + lds_byte(wr * 64 + m * 16 + fr, k * 32 + fq * 8))
; #define LDB(dst, b, h) UFOR(n, 2) UFOR(k, 2) \
;     dst[n][k] = *reinterpret_cast<const bf16x8*>((char*)SB(b, h) + lds_byte(wc * 32 + n * 16 + fr, k * 32 + fq * 8))
; #define MMA(ai, bj, At, Bq) do { __builtin_amdgcn_s_setprio(1); \
;     UFOR(m, 4) UFOR(n, 2) UFOR(k, 2) \
;       acc[ai][bj][m][n] = __builtin_amdgcn_mfma_f32_16x16x32_bf16(Bq[n][k], At[m][k], acc[ai][bj][m][n], 0, 0, 0); \
;     __builtin_amdgcn_s_setprio(0); } while (0)
; #define WAIT_V(n) asm volatile("s_waitcnt vmcnt(" #n ")" ::: "memory")
; #define WAIT_L(n) asm volatile("s_waitcnt lgkmcnt(" #n ")" ::: "memory")
; #define BAR __builtin_amdgcn_s_barrier()
; #define SCHED __builtin_amdgcn_sched_barrier(0)
; template <int EPI, int K, int KL> ...
;     ...
;     STAGE(SB(0, 1), Bt, bcol + HALF, t + 2);
;     WAIT_V(6); BAR; MMA(1, 1, At, B1); BAR;
;     LDB(B0, 1, 0); SCHED; LDA(At, 1, 0); STAGE(SA(0, 1), A, brow + HALF, t + 2);
;     WAIT_L(8); BAR; WAIT_L(0); MMA(0, 0, At, B0); BAR; SCHED;
;     LDB(B1, 1, 1); STAGE(SB(1, 0), Bt, bcol, t + 3);
;     BAR; WAIT_L(0); MMA(0, 1, At, B1); BAR;
;     LDA(At, 1, 1); STAGE(SA(1, 0), A, brow, t + 3);
;     BAR; WAIT_L(0); MMA(1, 0, At, B0); BAR; SCHED;
;     STAGE(SB(1, 1), Bt, bcol + HALF, t + 3);
;     WAIT_V(6); BAR; MMA(1, 1, At, B1); BAR;
	v_lshl_add_u64 v[136:137], v[242:243], 0, s[96:97]
	global_load_lds_dwordx4 v[136:137], off
	v_lshl_add_u64 v[136:137], v[244:245], 0, s[96:97]
	s_mov_b32 m0, s56
	s_nop 0
	global_load_lds_dwordx4 v[136:137], off
	s_waitcnt vmcnt(6)
	s_barrier
	v_mfma_f32_16x16x32_bf16 v[96:99], v[226:229], v[186:189], v[96:99]
	v_mfma_f32_16x16x32_bf16 v[100:103], v[234:237], v[186:189], v[100:103]
	v_mfma_f32_16x16x32_bf16 v[104:107], v[226:229], v[194:197], v[104:107]
	v_mfma_f32_16x16x32_bf16 v[108:111], v[234:237], v[194:197], v[108:111]
	v_mfma_f32_16x16x32_bf16 v[112:115], v[226:229], v[202:205], v[112:115]
	v_mfma_f32_16x16x32_bf16 v[116:119], v[234:237], v[202:205], v[116:119]
	v_mfma_f32_16x16x32_bf16 v[120:123], v[226:229], v[218:221], v[120:123]
	v_mfma_f32_16x16x32_bf16 v[124:127], v[234:237], v[218:221], v[124:127]
	v_mfma_f32_16x16x32_bf16 v[96:99], v[230:233], v[190:193], v[96:99]
	v_mfma_f32_16x16x32_bf16 v[100:103], v[238:241], v[190:193], v[100:103]
	v_mfma_f32_16x16x32_bf16 v[104:107], v[230:233], v[198:201], v[104:107]
	v_mfma_f32_16x16x32_bf16 v[108:111], v[238:241], v[198:201], v[108:111]
	v_mfma_f32_16x16x32_bf16 v[112:115], v[230:233], v[208:211], v[112:115]
	v_mfma_f32_16x16x32_bf16 v[116:119], v[238:241], v[208:211], v[116:119]
	v_mfma_f32_16x16x32_bf16 v[120:123], v[230:233], v[222:225], v[120:123]
	v_mfma_f32_16x16x32_bf16 v[124:127], v[238:241], v[222:225], v[124:127]
	s_barrier
	ds_read_b128 v[136:139], v166
	ds_read_b128 v[174:177], v166 offset:1024
	ds_read_b128 v[178:181], v166 offset:2048
	ds_read_b128 v[182:185], v166 offset:3072
	ds_read_b128 v[186:189], v163 offset:32768
	ds_read_b128 v[190:193], v163 offset:33792
	ds_read_b128 v[194:197], v162 offset:32768
	ds_read_b128 v[198:201], v162 offset:33792
	ds_read_b128 v[202:205], v161 offset:32768
	ds_read_b128 v[208:211], v161 offset:33792
	ds_read_b128 v[218:221], v160 offset:32768
	ds_read_b128 v[222:225], v160 offset:33792
	v_add_u32_e32 v134, 0x4000, v158
	v_lshl_add_u64 v[226:227], v[214:215], 0, s[12:13]
	v_readfirstlane_b32 s56, v134
	v_add_u32_e32 v134, 0x6000, v158
	s_mov_b32 m0, s56
	v_readfirstlane_b32 s56, v134
	global_load_lds_dwordx4 v[226:227], off
	v_lshl_add_u64 v[226:227], v[216:217], 0, s[12:13]
	s_mov_b32 m0, s56
	s_nop 0
	global_load_lds_dwordx4 v[226:227], off
	s_waitcnt lgkmcnt(8)
	s_barrier
	s_waitcnt lgkmcnt(0)
	s_waitcnt lgkmcnt(0)
	v_mfma_f32_16x16x32_bf16 v[0:3], v[136:139], v[186:189], v[0:3]
	v_mfma_f32_16x16x32_bf16 v[4:7], v[178:181], v[186:189], v[4:7]
	v_mfma_f32_16x16x32_bf16 v[8:11], v[136:139], v[194:197], v[8:11]
	v_mfma_f32_16x16x32_bf16 v[16:19], v[178:181], v[194:197], v[16:19]
	v_mfma_f32_16x16x32_bf16 v[28:31], v[136:139], v[202:205], v[28:31]
	v_mfma_f32_16x16x32_bf16 v[40:43], v[178:181], v[202:205], v[40:43]
	v_mfma_f32_16x16x32_bf16 v[52:55], v[136:139], v[218:221], v[52:55]
	v_mfma_f32_16x16x32_bf16 v[64:67], v[178:181], v[218:221], v[64:67]
	v_mfma_f32_16x16x32_bf16 v[0:3], v[174:177], v[190:193], v[0:3]
	v_mfma_f32_16x16x32_bf16 v[4:7], v[182:185], v[190:193], v[4:7]
	v_mfma_f32_16x16x32_bf16 v[8:11], v[174:177], v[198:201], v[8:11]
	v_mfma_f32_16x16x32_bf16 v[16:19], v[182:185], v[198:201], v[16:19]
	v_mfma_f32_16x16x32_bf16 v[28:31], v[174:177], v[208:211], v[28:31]
	v_mfma_f32_16x16x32_bf16 v[40:43], v[182:185], v[208:211], v[40:43]
	v_mfma_f32_16x16x32_bf16 v[52:55], v[174:177], v[222:225], v[52:55]
	v_mfma_f32_16x16x32_bf16 v[64:67], v[182:185], v[222:225], v[64:67]
	s_barrier
	ds_read_b128 v[226:229], v164
	ds_read_b128 v[230:233], v164 offset:1024
	ds_read_b128 v[234:237], v164 offset:2048
	ds_read_b128 v[238:241], v164 offset:3072
	v_readfirstlane_b32 s56, v165
	v_add_u32_e32 v134, 0x2000, v165
	v_lshl_add_u64 v[246:247], v[242:243], 0, s[80:81]
	s_mov_b32 m0, s56
	v_readfirstlane_b32 s56, v134
	global_load_lds_dwordx4 v[246:247], off
	v_lshl_add_u64 v[246:247], v[244:245], 0, s[80:81]
	s_mov_b32 m0, s56
	s_nop 0
	global_load_lds_dwordx4 v[246:247], off
	s_barrier
	s_waitcnt lgkmcnt(0)
	s_waitcnt lgkmcnt(0)
	v_mfma_f32_16x16x32_bf16 v[12:15], v[226:229], v[186:189], v[12:15]
	v_mfma_f32_16x16x32_bf16 v[24:27], v[234:237], v[186:189], v[24:27]
	v_mfma_f32_16x16x32_bf16 v[36:39], v[226:229], v[194:197], v[36:39]
	v_mfma_f32_16x16x32_bf16 v[48:51], v[234:237], v[194:197], v[48:51]
	v_mfma_f32_16x16x32_bf16 v[60:63], v[226:229], v[202:205], v[60:63]
	v_mfma_f32_16x16x32_bf16 v[72:75], v[234:237], v[202:205], v[72:75]
	v_mfma_f32_16x16x32_bf16 v[80:83], v[226:229], v[218:221], v[80:83]
	v_mfma_f32_16x16x32_bf16 v[88:91], v[234:237], v[218:221], v[88:91]
	v_mfma_f32_16x16x32_bf16 v[12:15], v[230:233], v[190:193], v[12:15]
	v_mfma_f32_16x16x32_bf16 v[24:27], v[238:241], v[190:193], v[24:27]
	v_mfma_f32_16x16x32_bf16 v[36:39], v[230:233], v[198:201], v[36:39]
	v_mfma_f32_16x16x32_bf16 v[48:51], v[238:241], v[198:201], v[48:51]
	v_mfma_f32_16x16x32_bf16 v[60:63], v[230:233], v[208:211], v[60:63]
	v_mfma_f32_16x16x32_bf16 v[72:75], v[238:241], v[208:211], v[72:75]
	v_mfma_f32_16x16x32_bf16 v[80:83], v[230:233], v[222:225], v[80:83]
	v_mfma_f32_16x16x32_bf16 v[88:91], v[238:241], v[222:225], v[88:91]
	v_readfirstlane_b32 s56, v167
	v_lshl_add_u64 v[214:215], v[214:215], 0, s[16:17]
	s_mov_b32 m0, s56
	v_readfirstlane_b32 s56, v168
	s_barrier
	ds_read_b128 v[186:189], v163 offset:49152
	ds_read_b128 v[190:193], v163 offset:50176
	ds_read_b128 v[194:197], v162 offset:49152
	ds_read_b128 v[198:201], v162 offset:50176
	ds_read_b128 v[202:205], v161 offset:49152
	ds_read_b128 v[208:211], v161 offset:50176
	ds_read_b128 v[218:221], v160 offset:49152
	ds_read_b128 v[222:225], v160 offset:50176
	global_load_lds_dwordx4 v[214:215], off
	v_lshl_add_u64 v[214:215], v[216:217], 0, s[16:17]
	s_mov_b32 m0, s56
	s_nop 0
	global_load_lds_dwordx4 v[214:215], off
	s_barrier
; #define STAGE(P, BASE, br, kt) STAGET(tid_, P, BASE, br, kt)
; #define LDA(dst, b, h) UFOR(m, 4) UFOR(k, 2) \
;     dst[m][k] = *reinterpret_cast<const bf16x8*>((char*)SA(b, h) + lds_byte(wr * 64 + m * 16 + fr, k * 32 + fq * 8))
; #define LDB(dst, b, h) UFOR(n, 2) UFOR(k, 2) \
;     dst[n][k] = *reinterpret_cast<const bf16x8*>((char*)SB(b, h) + lds_byte(wc * 32 + n * 16 + fr, k * 32 + fq * 8))
; #define MMA(ai, bj, At, Bq) do { __builtin_amdgcn_s_setprio(1); \
;     UFOR(m, 4) UFOR(n, 2) UFOR(k, 2) \
;       acc[ai][bj][m][n] = __builtin_amdgcn_mfma_f32_16x16x32_bf16(Bq[n][k], At[m][k], acc[ai][bj][m][n], 0, 0, 0); \
;     __builtin_amdgcn_s_setprio(0); } while (0)
; #define WAIT_V(n) asm volatile("s_waitcnt vmcnt(" #n ")" ::: "memory")
; #define WAIT_L(n) asm volatile("s_waitcnt lgkmcnt(" #n ")" ::: "memory")
; #define BAR __builtin_amdgcn_s_barrier()
; template <int EPI, int K, int KL> ...
;     ...
;     STAGE(SB(1, 1), Bt, bcol + HALF, t + 3);
;     WAIT_V(6); BAR; MMA(1, 1, At, B1); BAR;
;   }
;   { LDB(B0, 0, 0); LDA(At, 0, 0); STAGE(SA(1, 1), A, brow + HALF, nt - 1);
;     BAR; WAIT_L(0); MMA(0, 0, At, B0); BAR;
;     LDB(B1, 0, 1); BAR; WAIT_L(0); MMA(0, 1, At, B1); BAR;
	s_waitcnt lgkmcnt(0)
	s_waitcnt lgkmcnt(0)
	v_mfma_f32_16x16x32_bf16 v[20:23], v[136:139], v[186:189], v[20:23]
	v_mfma_f32_16x16x32_bf16 v[32:35], v[178:181], v[186:189], v[32:35]
	v_mfma_f32_16x16x32_bf16 v[44:47], v[136:139], v[194:197], v[44:47]
	v_mfma_f32_16x16x32_bf16 v[56:59], v[178:181], v[194:197], v[56:59]
	v_mfma_f32_16x16x32_bf16 v[68:71], v[136:139], v[202:205], v[68:71]
	v_mfma_f32_16x16x32_bf16 v[76:79], v[178:181], v[202:205], v[76:79]
	v_mfma_f32_16x16x32_bf16 v[84:87], v[136:139], v[218:221], v[84:87]
	v_mfma_f32_16x16x32_bf16 v[92:95], v[178:181], v[218:221], v[92:95]
	v_mfma_f32_16x16x32_bf16 v[20:23], v[174:177], v[190:193], v[20:23]
	v_mfma_f32_16x16x32_bf16 v[32:35], v[182:185], v[190:193], v[32:35]
	v_mfma_f32_16x16x32_bf16 v[44:47], v[174:177], v[198:201], v[44:47]
	v_mfma_f32_16x16x32_bf16 v[56:59], v[182:185], v[198:201], v[56:59]
	v_mfma_f32_16x16x32_bf16 v[68:71], v[174:177], v[208:211], v[68:71]
	v_mfma_f32_16x16x32_bf16 v[76:79], v[182:185], v[208:211], v[76:79]
	v_mfma_f32_16x16x32_bf16 v[84:87], v[174:177], v[222:225], v[84:87]
	v_mfma_f32_16x16x32_bf16 v[92:95], v[182:185], v[222:225], v[92:95]
	v_readfirstlane_b32 s56, v170
	v_add_u32_e32 v134, 0x2000, v170
	s_mov_b32 m0, s56
	v_readfirstlane_b32 s56, v134
	s_barrier
	v_lshl_add_u64 v[136:137], v[242:243], 0, s[90:91]
	global_load_lds_dwordx4 v[136:137], off
	v_lshl_add_u64 v[136:137], v[244:245], 0, s[90:91]
	s_mov_b32 m0, s56
	s_nop 0
	global_load_lds_dwordx4 v[136:137], off
	s_waitcnt vmcnt(6)
	s_barrier
	v_mfma_f32_16x16x32_bf16 v[96:99], v[226:229], v[186:189], v[96:99]
	v_mfma_f32_16x16x32_bf16 v[100:103], v[234:237], v[186:189], v[100:103]
	v_mfma_f32_16x16x32_bf16 v[104:107], v[226:229], v[194:197], v[104:107]
	v_mfma_f32_16x16x32_bf16 v[108:111], v[234:237], v[194:197], v[108:111]
	v_mfma_f32_16x16x32_bf16 v[112:115], v[226:229], v[202:205], v[112:115]
	v_mfma_f32_16x16x32_bf16 v[116:119], v[234:237], v[202:205], v[116:119]
	v_mfma_f32_16x16x32_bf16 v[120:123], v[226:229], v[218:221], v[120:123]
	v_mfma_f32_16x16x32_bf16 v[124:127], v[234:237], v[218:221], v[124:127]
	v_mfma_f32_16x16x32_bf16 v[96:99], v[230:233], v[190:193], v[96:99]
	v_mfma_f32_16x16x32_bf16 v[100:103], v[238:241], v[190:193], v[100:103]
	v_mfma_f32_16x16x32_bf16 v[104:107], v[230:233], v[198:201], v[104:107]
	v_mfma_f32_16x16x32_bf16 v[108:111], v[238:241], v[198:201], v[108:111]
	v_mfma_f32_16x16x32_bf16 v[112:115], v[230:233], v[208:211], v[112:115]
	v_mfma_f32_16x16x32_bf16 v[116:119], v[238:241], v[208:211], v[116:119]
	v_mfma_f32_16x16x32_bf16 v[120:123], v[230:233], v[222:225], v[120:123]
	v_mfma_f32_16x16x32_bf16 v[124:127], v[238:241], v[222:225], v[124:127]
	s_add_i32 s53, s53, 2
	v_lshl_add_u64 v[144:145], v[144:145], 0, s[20:21]
	v_lshl_add_u64 v[146:147], v[146:147], 0, s[20:21]
	v_lshl_add_u64 v[148:149], v[148:149], 0, s[20:21]
	s_cmp_lt_u32 s53, 28
	v_lshl_add_u64 v[150:151], v[150:151], 0, s[20:21]
	s_cbranch_scc1 .Lkrot_1107
	s_barrier
	s_add_u32 s40, s40, 0x80f80
	s_addc_u32 s41, s41, 0
	v_lshl_add_u64 v[130:131], s[40:41], 0, v[130:131]
	v_readfirstlane_b32 s53, v172
	v_lshl_add_u64 v[128:129], v[128:129], 1, v[130:131]
	s_mov_b32 m0, s53
	ds_read_b128 v[136:139], v171
	ds_read_b128 v[144:147], v171 offset:1024
	ds_read_b128 v[148:151], v171 offset:2048
	ds_read_b128 v[174:177], v171 offset:3072
	ds_read_b128 v[178:181], v163
	ds_read_b128 v[182:185], v163 offset:1024
	ds_read_b128 v[186:189], v162
	ds_read_b128 v[190:193], v162 offset:1024
	ds_read_b128 v[194:197], v161
	ds_read_b128 v[198:201], v161 offset:1024
	ds_read_b128 v[202:205], v160
	ds_read_b128 v[208:211], v160 offset:1024
	global_load_lds_dwordx4 v[128:129], off
	v_lshl_add_u64 v[128:129], s[40:41], 0, v[142:143]
	v_readfirstlane_b32 s40, v173
	v_lshl_add_u64 v[128:129], v[140:141], 1, v[128:129]
	s_mov_b32 m0, s40
	s_nop 0
	global_load_lds_dwordx4 v[128:129], off
	s_barrier
	s_waitcnt lgkmcnt(0)
	s_waitcnt lgkmcnt(0)
	v_mfma_f32_16x16x32_bf16 v[0:3], v[136:139], v[178:181], v[0:3]
	v_mfma_f32_16x16x32_bf16 v[4:7], v[148:151], v[178:181], v[4:7]
	v_mfma_f32_16x16x32_bf16 v[8:11], v[136:139], v[186:189], v[8:11]
	v_mfma_f32_16x16x32_bf16 v[16:19], v[148:151], v[186:189], v[16:19]
	v_mfma_f32_16x16x32_bf16 v[28:31], v[136:139], v[194:197], v[28:31]
	v_mfma_f32_16x16x32_bf16 v[40:43], v[148:151], v[194:197], v[40:43]
	v_mfma_f32_16x16x32_bf16 v[52:55], v[136:139], v[202:205], v[52:55]
	v_mfma_f32_16x16x32_bf16 v[64:67], v[148:151], v[202:205], v[64:67]
	v_mfma_f32_16x16x32_bf16 v[0:3], v[144:147], v[182:185], v[0:3]
	v_mfma_f32_16x16x32_bf16 v[4:7], v[174:177], v[182:185], v[4:7]
	v_mfma_f32_16x16x32_bf16 v[8:11], v[144:147], v[190:193], v[8:11]
	v_mfma_f32_16x16x32_bf16 v[16:19], v[174:177], v[190:193], v[16:19]
	v_mfma_f32_16x16x32_bf16 v[28:31], v[144:147], v[198:201], v[28:31]
	v_mfma_f32_16x16x32_bf16 v[40:43], v[174:177], v[198:201], v[40:43]
	v_mfma_f32_16x16x32_bf16 v[52:55], v[144:147], v[208:211], v[52:55]
	v_mfma_f32_16x16x32_bf16 v[64:67], v[174:177], v[208:211], v[64:67]
	s_barrier
	ds_read_b128 v[128:131], v169
	ds_read_b128 v[140:143], v169 offset:1024
	ds_read_b128 v[170:173], v169 offset:2048
	ds_read_b128 v[218:221], v169 offset:3072
	s_barrier
; #define LDA(dst, b, h) UFOR(m, 4) UFOR(k, 2) \
;     dst[m][k] = *reinterpret_cast<const bf16x8*>((char*)SA(b, h) + lds_byte(wr * 64 + m * 16 + fr, k * 32 + fq * 8))
; #define LDB(dst, b, h) UFOR(n, 2) UFOR(k, 2) \
;     dst[n][k] = *reinterpret_cast<const bf16x8*>((char*)SB(b, h) + lds_byte(wc * 32 + n * 16 + fr, k * 32 + fq * 8))
; #define MMA(ai, bj, At, Bq) do { __builtin_amdgcn_s_setprio(1); \
;     UFOR(m, 4) UFOR(n, 2) UFOR(k, 2) \
;       acc[ai][bj][m][n] = __builtin_amdgcn_mfma_f32_16x16x32_bf16(Bq[n][k], At[m][k], acc[ai][bj][m][n], 0, 0, 0); \
;     __builtin_amdgcn_s_setprio(0); } while (0)
; #define WAIT_V(n) asm volatile("s_waitcnt vmcnt(" #n ")" ::: "memory")
; #define WAIT_L(n) asm volatile("s_waitcnt lgkmcnt(" #n ")" ::: "memory")
; #define BAR __builtin_amdgcn_s_barrier()
; template <int EPI, int K, int KL> ...
;     ...
;     LDB(B1, 0, 1); BAR; WAIT_L(0); MMA(0, 1, At, B1); BAR;
;     LDA(At, 0, 1); WAIT_V(4); BAR; WAIT_L(0); MMA(1, 0, At, B0); MMA(1, 1, At, B1); BAR; }
;   { LDB(B0, 1, 0); LDA(At, 1, 0); WAIT_V(2); BAR; WAIT_L(0); MMA(0, 0, At, B0); BAR;
;     LDB(B1, 1, 1); WAIT_V(0); BAR; WAIT_L(0); MMA(0, 1, At, B1); BAR;
	s_waitcnt lgkmcnt(0)
	s_waitcnt lgkmcnt(0)
	v_mfma_f32_16x16x32_bf16 v[12:15], v[128:131], v[178:181], v[12:15]
	v_mfma_f32_16x16x32_bf16 v[24:27], v[170:173], v[178:181], v[24:27]
	v_mfma_f32_16x16x32_bf16 v[36:39], v[128:131], v[186:189], v[36:39]
	v_mfma_f32_16x16x32_bf16 v[48:51], v[170:173], v[186:189], v[48:51]
	v_mfma_f32_16x16x32_bf16 v[60:63], v[128:131], v[194:197], v[60:63]
	v_mfma_f32_16x16x32_bf16 v[72:75], v[170:173], v[194:197], v[72:75]
	v_mfma_f32_16x16x32_bf16 v[80:83], v[128:131], v[202:205], v[80:83]
	v_mfma_f32_16x16x32_bf16 v[12:15], v[140:143], v[182:185], v[12:15]
	v_mfma_f32_16x16x32_bf16 v[24:27], v[218:221], v[182:185], v[24:27]
	v_mfma_f32_16x16x32_bf16 v[36:39], v[140:143], v[190:193], v[36:39]
	v_mfma_f32_16x16x32_bf16 v[48:51], v[218:221], v[190:193], v[48:51]
	v_mfma_f32_16x16x32_bf16 v[60:63], v[140:143], v[198:201], v[60:63]
	v_mfma_f32_16x16x32_bf16 v[72:75], v[218:221], v[198:201], v[72:75]
	v_mfma_f32_16x16x32_bf16 v[178:181], v[140:143], v[208:211], v[80:83]
	v_mfma_f32_16x16x32_bf16 v[80:83], v[170:173], v[202:205], v[88:91]
	v_mfma_f32_16x16x32_bf16 v[182:185], v[218:221], v[208:211], v[80:83]
	s_barrier
	s_nop 5
	ds_read_b128 v[80:83], v163 offset:16384
	ds_read_b128 v[88:91], v163 offset:17408
	ds_read_b128 v[186:189], v162 offset:16384
	ds_read_b128 v[190:193], v162 offset:17408
	ds_read_b128 v[194:197], v161 offset:16384
	ds_read_b128 v[198:201], v161 offset:17408
	ds_read_b128 v[202:205], v160 offset:16384
	ds_read_b128 v[208:211], v160 offset:17408
	s_waitcnt vmcnt(4)
	s_barrier
	s_waitcnt lgkmcnt(0)
	s_waitcnt lgkmcnt(0)
	v_mfma_f32_16x16x32_bf16 v[56:59], v[148:151], v[186:189], v[56:59]
	v_mfma_f32_16x16x32_bf16 v[222:225], v[174:177], v[190:193], v[56:59]
	v_mfma_f32_16x16x32_bf16 v[56:59], v[136:139], v[194:197], v[68:71]
	v_mfma_f32_16x16x32_bf16 v[226:229], v[144:147], v[198:201], v[56:59]
	v_mfma_f32_16x16x32_bf16 v[56:59], v[148:151], v[194:197], v[76:79]
	v_mfma_f32_16x16x32_bf16 v[20:23], v[136:139], v[80:83], v[20:23]
	v_mfma_f32_16x16x32_bf16 v[32:35], v[148:151], v[80:83], v[32:35]
	v_mfma_f32_16x16x32_bf16 v[44:47], v[136:139], v[186:189], v[44:47]
	v_mfma_f32_16x16x32_bf16 v[230:233], v[174:177], v[198:201], v[56:59]
	v_mfma_f32_16x16x32_bf16 v[56:59], v[136:139], v[202:205], v[84:87]
	v_mfma_f32_16x16x32_bf16 v[20:23], v[144:147], v[88:91], v[20:23]
	v_mfma_f32_16x16x32_bf16 v[32:35], v[174:177], v[88:91], v[32:35]
	v_mfma_f32_16x16x32_bf16 v[44:47], v[144:147], v[190:193], v[44:47]
	v_mfma_f32_16x16x32_bf16 v[136:139], v[144:147], v[208:211], v[56:59]
	v_mfma_f32_16x16x32_bf16 v[56:59], v[148:151], v[202:205], v[92:95]
	v_mfma_f32_16x16x32_bf16 v[144:147], v[174:177], v[208:211], v[56:59]
	v_mfma_f32_16x16x32_bf16 v[56:59], v[128:131], v[80:83], v[96:99]
	v_mfma_f32_16x16x32_bf16 v[148:151], v[140:143], v[88:91], v[56:59]
	v_mfma_f32_16x16x32_bf16 v[56:59], v[170:173], v[80:83], v[100:103]
	v_mfma_f32_16x16x32_bf16 v[174:177], v[218:221], v[88:91], v[56:59]
	v_mfma_f32_16x16x32_bf16 v[56:59], v[128:131], v[186:189], v[104:107]
	v_mfma_f32_16x16x32_bf16 v[234:237], v[140:143], v[190:193], v[56:59]
	v_mfma_f32_16x16x32_bf16 v[56:59], v[170:173], v[186:189], v[108:111]
	v_mfma_f32_16x16x32_bf16 v[186:189], v[218:221], v[190:193], v[56:59]
	v_mfma_f32_16x16x32_bf16 v[56:59], v[128:131], v[194:197], v[112:115]
	v_mfma_f32_16x16x32_bf16 v[190:193], v[140:143], v[198:201], v[56:59]
	v_mfma_f32_16x16x32_bf16 v[56:59], v[170:173], v[194:197], v[116:119]
	v_mfma_f32_16x16x32_bf16 v[194:197], v[218:221], v[198:201], v[56:59]
	v_mfma_f32_16x16x32_bf16 v[56:59], v[128:131], v[202:205], v[120:123]
	v_mfma_f32_16x16x32_bf16 v[128:131], v[140:143], v[208:211], v[56:59]
	v_mfma_f32_16x16x32_bf16 v[56:59], v[170:173], v[202:205], v[124:127]
	v_mfma_f32_16x16x32_bf16 v[140:143], v[218:221], v[208:211], v[56:59]
	s_barrier
	ds_read_b128 v[168:171], v166
	ds_read_b128 v[198:201], v166 offset:1024
	ds_read_b128 v[202:205], v166 offset:2048
	ds_read_b128 v[208:211], v166 offset:3072
	s_nop 1
	ds_read_b128 v[56:59], v163 offset:32768
	ds_read_b128 v[68:71], v163 offset:33792
	ds_read_b128 v[76:79], v162 offset:32768
	ds_read_b128 v[80:83], v162 offset:33792
	ds_read_b128 v[218:221], v161 offset:32768
	ds_read_b128 v[238:241], v161 offset:33792
	ds_read_b128 v[242:245], v160 offset:32768
	ds_read_b128 v[246:249], v160 offset:33792
	s_waitcnt vmcnt(2)
	s_barrier
	s_waitcnt lgkmcnt(0)
	s_waitcnt lgkmcnt(0)
	v_mfma_f32_16x16x32_bf16 v[0:3], v[168:171], v[56:59], v[0:3]
	v_mfma_f32_16x16x32_bf16 v[124:127], v[198:201], v[68:71], v[0:3]
	v_mfma_f32_16x16x32_bf16 v[0:3], v[202:205], v[56:59], v[4:7]
	v_mfma_f32_16x16x32_bf16 v[120:123], v[208:211], v[68:71], v[0:3]
	v_mfma_f32_16x16x32_bf16 v[0:3], v[168:171], v[76:79], v[8:11]
	v_mfma_f32_16x16x32_bf16 v[116:119], v[198:201], v[80:83], v[0:3]
	v_mfma_f32_16x16x32_bf16 v[0:3], v[202:205], v[76:79], v[16:19]
	v_mfma_f32_16x16x32_bf16 v[112:115], v[208:211], v[80:83], v[0:3]
	v_mfma_f32_16x16x32_bf16 v[0:3], v[168:171], v[218:221], v[28:31]
	v_mfma_f32_16x16x32_bf16 v[108:111], v[198:201], v[238:241], v[0:3]
	v_mfma_f32_16x16x32_bf16 v[0:3], v[202:205], v[218:221], v[40:43]
	v_mfma_f32_16x16x32_bf16 v[104:107], v[208:211], v[238:241], v[0:3]
	v_mfma_f32_16x16x32_bf16 v[0:3], v[168:171], v[242:245], v[52:55]
	v_mfma_f32_16x16x32_bf16 v[100:103], v[198:201], v[246:249], v[0:3]
	v_mfma_f32_16x16x32_bf16 v[0:3], v[202:205], v[242:245], v[64:67]
	v_mfma_f32_16x16x32_bf16 v[96:99], v[208:211], v[246:249], v[0:3]
	s_barrier
; #define UFOR(v, n) _Pragma("unroll") for (int v = 0; v < (n); ++v)
; #define LDA(dst, b, h) UFOR(m, 4) UFOR(k, 2) \
;     dst[m][k] = *reinterpret_cast<const bf16x8*>((char*)SA(b, h) + lds_byte(wr * 64 + m * 16 + fr, k * 32 + fq * 8))
; #define LDB(dst, b, h) UFOR(n, 2) UFOR(k, 2) \
;     dst[n][k] = *reinterpret_cast<const bf16x8*>((char*)SB(b, h) + lds_byte(wc * 32 + n * 16 + fr, k * 32 + fq * 8))
; #define MMA(ai, bj, At, Bq) do { __builtin_amdgcn_s_setprio(1); \
;     UFOR(m, 4) UFOR(n, 2) UFOR(k, 2) \
;       acc[ai][bj][m][n] = __builtin_amdgcn_mfma_f32_16x16x32_bf16(Bq[n][k], At[m][k], acc[ai][bj][m][n], 0, 0, 0); \
;     __builtin_amdgcn_s_setprio(0); } while (0)
; #define WAIT_V(n) asm volatile("s_waitcnt vmcnt(" #n ")" ::: "memory")
; #define WAIT_L(n) asm volatile("s_waitcnt lgkmcnt(" #n ")" ::: "memory")
; #define BAR __builtin_amdgcn_s_barrier()
; template <int EPI, int K, int KL> ...
;     ...
;   { LDB(B0, 1, 0); LDA(At, 1, 0); WAIT_V(2); BAR; WAIT_L(0); MMA(0, 0, At, B0); BAR;
;     LDB(B1, 1, 1); WAIT_V(0); BAR; WAIT_L(0); MMA(0, 1, At, B1); BAR;
;     LDA(At, 1, 1); BAR; WAIT_L(0); MMA(1, 0, At, B0); MMA(1, 1, At, B1); BAR; }
;   if (wr == 0) BAR;
;     ...
;       const int c4 = (tid_ & 31) * 4, rb = tid_ >> 5;
;       const int gc = pn * 128 + c4;
;       float wg[4][3], wv[4][3];
;       UFOR(q, 4) UFOR(x, 3) { wg[q][x] = e.cw[(size_t)(gc + q) * 3 + x]; wv[q][x] = e.cw[(size_t)(DFF + gc + q) * 3 + x]; }
	s_nop 5
	ds_read_b128 v[0:3], v164
	ds_read_b128 v[4:7], v164 offset:1024
	ds_read_b128 v[214:217], v164 offset:2048
	ds_read_b128 v[164:167], v164 offset:3072
	s_waitcnt vmcnt(0)
	s_barrier
	s_waitcnt lgkmcnt(0)
	s_waitcnt lgkmcnt(0)
	v_mfma_f32_16x16x32_bf16 v[8:11], v[0:3], v[56:59], v[12:15]
	v_mfma_f32_16x16x32_bf16 v[92:95], v[4:7], v[68:71], v[8:11]
	v_mfma_f32_16x16x32_bf16 v[8:11], v[214:217], v[56:59], v[24:27]
	v_mfma_f32_16x16x32_bf16 v[88:91], v[164:167], v[68:71], v[8:11]
	v_mfma_f32_16x16x32_bf16 v[8:11], v[0:3], v[76:79], v[36:39]
	v_mfma_f32_16x16x32_bf16 v[84:87], v[4:7], v[80:83], v[8:11]
	v_mfma_f32_16x16x32_bf16 v[8:11], v[214:217], v[76:79], v[48:51]
	v_mfma_f32_16x16x32_bf16 v[80:83], v[164:167], v[80:83], v[8:11]
	v_mfma_f32_16x16x32_bf16 v[8:11], v[0:3], v[218:221], v[60:63]
	v_mfma_f32_16x16x32_bf16 v[76:79], v[4:7], v[238:241], v[8:11]
	v_mfma_f32_16x16x32_bf16 v[8:11], v[214:217], v[218:221], v[72:75]
	v_mfma_f32_16x16x32_bf16 v[72:75], v[164:167], v[238:241], v[8:11]
	v_mfma_f32_16x16x32_bf16 v[8:11], v[0:3], v[242:245], v[178:181]
	v_mfma_f32_16x16x32_bf16 v[68:71], v[4:7], v[246:249], v[8:11]
	v_mfma_f32_16x16x32_bf16 v[8:11], v[214:217], v[242:245], v[182:185]
	v_mfma_f32_16x16x32_bf16 v[64:67], v[164:167], v[246:249], v[8:11]
	s_barrier
	s_nop 5
	ds_read_b128 v[8:11], v163 offset:49152
	ds_read_b128 v[12:15], v163 offset:50176
	ds_read_b128 v[16:19], v162 offset:49152
	ds_read_b128 v[178:181], v162 offset:50176
	ds_read_b128 v[182:185], v161 offset:49152
	ds_read_b128 v[218:221], v161 offset:50176
	ds_read_b128 v[238:241], v160 offset:49152
	ds_read_b128 v[158:161], v160 offset:50176
	s_barrier
	s_waitcnt lgkmcnt(0)
	s_waitcnt lgkmcnt(0)
	v_mfma_f32_16x16x32_bf16 v[20:23], v[168:171], v[8:11], v[20:23]
	v_mfma_f32_16x16x32_bf16 v[60:63], v[198:201], v[12:15], v[20:23]
	v_mfma_f32_16x16x32_bf16 v[20:23], v[202:205], v[8:11], v[32:35]
	v_mfma_f32_16x16x32_bf16 v[56:59], v[208:211], v[12:15], v[20:23]
	v_mfma_f32_16x16x32_bf16 v[20:23], v[168:171], v[16:19], v[44:47]
	v_mfma_f32_16x16x32_bf16 v[52:55], v[198:201], v[178:181], v[20:23]
	v_mfma_f32_16x16x32_bf16 v[20:23], v[202:205], v[16:19], v[222:225]
	v_mfma_f32_16x16x32_bf16 v[48:51], v[208:211], v[178:181], v[20:23]
	v_mfma_f32_16x16x32_bf16 v[20:23], v[168:171], v[182:185], v[226:229]
	v_mfma_f32_16x16x32_bf16 v[44:47], v[198:201], v[218:221], v[20:23]
	v_mfma_f32_16x16x32_bf16 v[20:23], v[202:205], v[182:185], v[230:233]
	v_mfma_f32_16x16x32_bf16 v[40:43], v[208:211], v[218:221], v[20:23]
	v_mfma_f32_16x16x32_bf16 v[20:23], v[168:171], v[238:241], v[136:139]
	v_mfma_f32_16x16x32_bf16 v[36:39], v[198:201], v[158:161], v[20:23]
	v_mfma_f32_16x16x32_bf16 v[20:23], v[202:205], v[238:241], v[144:147]
	v_mfma_f32_16x16x32_bf16 v[32:35], v[208:211], v[158:161], v[20:23]
	v_mfma_f32_16x16x32_bf16 v[20:23], v[0:3], v[8:11], v[148:151]
	v_mfma_f32_16x16x32_bf16 v[8:11], v[214:217], v[8:11], v[174:177]
	v_mfma_f32_16x16x32_bf16 v[24:27], v[164:167], v[12:15], v[8:11]
	v_mfma_f32_16x16x32_bf16 v[8:11], v[0:3], v[16:19], v[234:237]
	v_mfma_f32_16x16x32_bf16 v[28:31], v[4:7], v[12:15], v[20:23]
	v_mfma_f32_16x16x32_bf16 v[20:23], v[4:7], v[178:181], v[8:11]
	v_mfma_f32_16x16x32_bf16 v[8:11], v[214:217], v[16:19], v[186:189]
	v_mfma_f32_16x16x32_bf16 v[16:19], v[164:167], v[178:181], v[8:11]
	v_mfma_f32_16x16x32_bf16 v[8:11], v[0:3], v[182:185], v[190:193]
	v_mfma_f32_16x16x32_bf16 v[0:3], v[0:3], v[238:241], v[128:131]
	v_mfma_f32_16x16x32_bf16 v[12:15], v[4:7], v[218:221], v[8:11]
	v_mfma_f32_16x16x32_bf16 v[8:11], v[214:217], v[182:185], v[194:197]
	v_mfma_f32_16x16x32_bf16 v[4:7], v[4:7], v[158:161], v[0:3]
	v_mfma_f32_16x16x32_bf16 v[0:3], v[214:217], v[238:241], v[140:143]
	v_mfma_f32_16x16x32_bf16 v[8:11], v[164:167], v[218:221], v[8:11]
	v_mfma_f32_16x16x32_bf16 v[0:3], v[164:167], v[158:161], v[0:3]
	v_lshlrev_b32_e32 v242, 2, v152
	v_and_b32_e32 v242, 0x7c, v242
	v_lshl_or_b32 v242, s51, 7, v242
	v_add_u32_e32 v243, 0x1600, v242
	v_mad_i64_i32 v[244:245], vcc, v243, 12, s[46:47]
	v_mad_i64_i32 v[246:247], vcc, v242, 12, s[46:47]
	global_load_dwordx4 v[218:221], v[244:245], off offset:16
	global_load_dwordx4 v[222:225], v[244:245], off offset:32
	global_load_dwordx4 v[226:229], v[244:245], off
	global_load_dwordx4 v[230:233], v[246:247], off offset:16
	global_load_dwordx4 v[234:237], v[246:247], off offset:32
	global_load_dwordx4 v[238:241], v[246:247], off
	s_movk_i32 s40, 0x100
	v_cmp_gt_u32_e32 vcc, s40, v152
	s_barrier
	s_and_saveexec_b64 s[40:41], vcc
	s_cbranch_execz .LBB0_1110
	s_barrier

; #define STAGE(P, BASE, br, kt) STAGET(tid_, P, BASE, br, kt)
; #define LDA(dst, b, h) UFOR(m, 4) UFOR(k, 2) \
;     dst[m][k] = *reinterpret_cast<const bf16x8*>((char*)SA(b, h) + lds_byte(wr * 64 + m * 16 + fr, k * 32 + fq * 8))
; #define LDB(dst, b, h) UFOR(n, 2) UFOR(k, 2) \
;     dst[n][k] = *reinterpret_cast<const bf16x8*>((char*)SB(b, h) + lds_byte(wc * 32 + n * 16 + fr, k * 32 + fq * 8))
; #define MMA(ai, bj, At, Bq) do { __builtin_amdgcn_s_setprio(1); \
;     UFOR(m, 4) UFOR(n, 2) UFOR(k, 2) \
;       acc[ai][bj][m][n] = __builtin_amdgcn_mfma_f32_16x16x32_bf16(Bq[n][k], At[m][k], acc[ai][bj][m][n], 0, 0, 0); \
;     __builtin_amdgcn_s_setprio(0); } while (0)
; #define WAIT_V(n) asm volatile("s_waitcnt vmcnt(" #n ")" ::: "memory")
; #define WAIT_L(n) asm volatile("s_waitcnt lgkmcnt(" #n ")" ::: "memory")
; #define BAR __builtin_amdgcn_s_barrier()
; #define SCHED __builtin_amdgcn_sched_barrier(0)
; template <int EPI, int K, int KL> ...
;     ...
;     LDB(B0, 0, 0); SCHED; LDA(At, 0, 0); STAGE(SA(1, 1), A, brow + HALF, t + 1);
;     WAIT_L(8); BAR; WAIT_L(0); MMA(0, 0, At, B0); BAR; SCHED;
;     LDB(B1, 0, 1); STAGE(SB(0, 0), Bt, bcol, t + 2);
;     BAR; WAIT_L(0); MMA(0, 1, At, B1); BAR;
;     LDA(At, 0, 1); STAGE(SA(0, 0), A, brow, t + 2);
;     BAR; WAIT_L(0); MMA(1, 0, At, B0); BAR; SCHED;
;     STAGE(SB(0, 1), Bt, bcol + HALF, t + 2);
;     WAIT_V(6); BAR; MMA(1, 1, At, B1); BAR;
.LBB0_1184:
	ds_read_b128 v[136:139], v170
	ds_read_b128 v[174:177], v170 offset:1024
	ds_read_b128 v[178:181], v170 offset:2048
	ds_read_b128 v[182:185], v170 offset:3072
	ds_read_b128 v[186:189], v162
	ds_read_b128 v[190:193], v162 offset:1024
	ds_read_b128 v[194:197], v161
	ds_read_b128 v[198:201], v161 offset:1024
	ds_read_b128 v[202:205], v160
	ds_read_b128 v[208:211], v160 offset:1024
	ds_read_b128 v[214:217], v159
	ds_read_b128 v[218:221], v159 offset:1024
	v_add_u32_e32 v171, 0xc000, v157
	v_lshl_add_u64 v[238:239], s[92:93], 0, v[148:149]
	v_readfirstlane_b32 s54, v171
	v_lshl_add_u64 v[172:173], v[238:239], 0, s[86:87]
	s_mov_b32 m0, s54
	s_nop 0
	global_load_lds_dwordx4 v[172:173], off
	v_add_u32_e32 v172, 0xe000, v157
	v_lshl_add_u64 v[240:241], s[92:93], 0, v[150:151]
	v_readfirstlane_b32 s54, v172
	v_lshl_add_u64 v[222:223], v[240:241], 0, s[86:87]
	s_mov_b32 m0, s54
	s_nop 0
	global_load_lds_dwordx4 v[222:223], off
	s_waitcnt lgkmcnt(8)
	s_barrier
	s_waitcnt lgkmcnt(0)
	s_waitcnt lgkmcnt(0)
	v_mfma_f32_16x16x32_bf16 v[124:127], v[136:139], v[186:189], v[124:127]
	v_mfma_f32_16x16x32_bf16 v[120:123], v[178:181], v[186:189], v[120:123]
	v_mfma_f32_16x16x32_bf16 v[116:119], v[136:139], v[194:197], v[116:119]
	v_mfma_f32_16x16x32_bf16 v[112:115], v[178:181], v[194:197], v[112:115]
	v_mfma_f32_16x16x32_bf16 v[108:111], v[136:139], v[202:205], v[108:111]
	v_mfma_f32_16x16x32_bf16 v[104:107], v[178:181], v[202:205], v[104:107]
	v_mfma_f32_16x16x32_bf16 v[100:103], v[136:139], v[214:217], v[100:103]
	v_mfma_f32_16x16x32_bf16 v[96:99], v[178:181], v[214:217], v[96:99]
	v_mfma_f32_16x16x32_bf16 v[124:127], v[174:177], v[190:193], v[124:127]
	v_mfma_f32_16x16x32_bf16 v[120:123], v[182:185], v[190:193], v[120:123]
	v_mfma_f32_16x16x32_bf16 v[116:119], v[174:177], v[198:201], v[116:119]
	v_mfma_f32_16x16x32_bf16 v[112:115], v[182:185], v[198:201], v[112:115]
	v_mfma_f32_16x16x32_bf16 v[108:111], v[174:177], v[208:211], v[108:111]
	v_mfma_f32_16x16x32_bf16 v[104:107], v[182:185], v[208:211], v[104:107]
	v_mfma_f32_16x16x32_bf16 v[100:103], v[174:177], v[218:221], v[100:103]
	v_mfma_f32_16x16x32_bf16 v[96:99], v[182:185], v[218:221], v[96:99]
	s_barrier
	ds_read_b128 v[222:225], v169
	ds_read_b128 v[226:229], v169 offset:1024
	ds_read_b128 v[230:233], v169 offset:2048
	ds_read_b128 v[234:237], v169 offset:3072
	v_lshl_add_u64 v[242:243], s[92:93], 0, v[144:145]
	v_readfirstlane_b32 s54, v156
	v_lshl_add_u64 v[244:245], v[242:243], 0, s[22:23]
	s_mov_b32 m0, s54
	v_add_u32_e32 v134, 0x2000, v156
	global_load_lds_dwordx4 v[244:245], off
	v_lshl_add_u64 v[244:245], s[92:93], 0, v[146:147]
	v_readfirstlane_b32 s54, v134
	v_lshl_add_u64 v[246:247], v[244:245], 0, s[22:23]
	s_mov_b32 m0, s54
	s_nop 0
	global_load_lds_dwordx4 v[246:247], off
	s_barrier
	s_waitcnt lgkmcnt(0)
	s_waitcnt lgkmcnt(0)
	v_mfma_f32_16x16x32_bf16 v[92:95], v[222:225], v[186:189], v[92:95]
	v_mfma_f32_16x16x32_bf16 v[88:91], v[230:233], v[186:189], v[88:91]
	v_mfma_f32_16x16x32_bf16 v[84:87], v[222:225], v[194:197], v[84:87]
	v_mfma_f32_16x16x32_bf16 v[80:83], v[230:233], v[194:197], v[80:83]
	v_mfma_f32_16x16x32_bf16 v[76:79], v[222:225], v[202:205], v[76:79]
	v_mfma_f32_16x16x32_bf16 v[72:75], v[230:233], v[202:205], v[72:75]
	v_mfma_f32_16x16x32_bf16 v[68:71], v[222:225], v[214:217], v[68:71]
	v_mfma_f32_16x16x32_bf16 v[64:67], v[230:233], v[214:217], v[64:67]
	v_mfma_f32_16x16x32_bf16 v[92:95], v[226:229], v[190:193], v[92:95]
	v_mfma_f32_16x16x32_bf16 v[88:91], v[234:237], v[190:193], v[88:91]
	v_mfma_f32_16x16x32_bf16 v[84:87], v[226:229], v[198:201], v[84:87]
	v_mfma_f32_16x16x32_bf16 v[80:83], v[234:237], v[198:201], v[80:83]
	v_mfma_f32_16x16x32_bf16 v[76:79], v[226:229], v[208:211], v[76:79]
	v_mfma_f32_16x16x32_bf16 v[72:75], v[234:237], v[208:211], v[72:75]
	v_mfma_f32_16x16x32_bf16 v[68:71], v[226:229], v[218:221], v[68:71]
	v_mfma_f32_16x16x32_bf16 v[64:67], v[234:237], v[218:221], v[64:67]
	v_readfirstlane_b32 s54, v157
	v_add_u32_e32 v134, 0x2000, v157
	v_lshl_add_u64 v[246:247], v[238:239], 0, s[34:35]
	s_mov_b32 m0, s54
	v_readfirstlane_b32 s54, v134
	s_barrier
	ds_read_b128 v[186:189], v162 offset:16384
	ds_read_b128 v[190:193], v162 offset:17408
	ds_read_b128 v[194:197], v161 offset:16384
	ds_read_b128 v[198:201], v161 offset:17408
	ds_read_b128 v[202:205], v160 offset:16384
	ds_read_b128 v[208:211], v160 offset:17408
	ds_read_b128 v[214:217], v159 offset:16384
	ds_read_b128 v[218:221], v159 offset:17408
	global_load_lds_dwordx4 v[246:247], off
	v_lshl_add_u64 v[246:247], v[240:241], 0, s[34:35]
	s_mov_b32 m0, s54
	s_nop 0
	global_load_lds_dwordx4 v[246:247], off
	s_barrier
	s_waitcnt lgkmcnt(0)
	s_waitcnt lgkmcnt(0)
	v_mfma_f32_16x16x32_bf16 v[60:63], v[136:139], v[186:189], v[60:63]
	v_mfma_f32_16x16x32_bf16 v[56:59], v[178:181], v[186:189], v[56:59]
	v_mfma_f32_16x16x32_bf16 v[52:55], v[136:139], v[194:197], v[52:55]
	v_mfma_f32_16x16x32_bf16 v[48:51], v[178:181], v[194:197], v[48:51]
	v_mfma_f32_16x16x32_bf16 v[44:47], v[136:139], v[202:205], v[44:47]
	v_mfma_f32_16x16x32_bf16 v[40:43], v[178:181], v[202:205], v[40:43]
	v_mfma_f32_16x16x32_bf16 v[36:39], v[136:139], v[214:217], v[36:39]
	v_mfma_f32_16x16x32_bf16 v[32:35], v[178:181], v[214:217], v[32:35]
	v_mfma_f32_16x16x32_bf16 v[60:63], v[174:177], v[190:193], v[60:63]
	v_mfma_f32_16x16x32_bf16 v[56:59], v[182:185], v[190:193], v[56:59]
	v_mfma_f32_16x16x32_bf16 v[52:55], v[174:177], v[198:201], v[52:55]
	v_mfma_f32_16x16x32_bf16 v[48:51], v[182:185], v[198:201], v[48:51]
	v_mfma_f32_16x16x32_bf16 v[44:47], v[174:177], v[208:211], v[44:47]
	v_mfma_f32_16x16x32_bf16 v[40:43], v[182:185], v[208:211], v[40:43]
	v_mfma_f32_16x16x32_bf16 v[36:39], v[174:177], v[218:221], v[36:39]
	v_mfma_f32_16x16x32_bf16 v[32:35], v[182:185], v[218:221], v[32:35]
	v_readfirstlane_b32 s54, v158
	v_add_u32_e32 v134, 0x2000, v158
	s_mov_b32 m0, s54
	v_readfirstlane_b32 s54, v134
	s_barrier
; #define STAGE(P, BASE, br, kt) STAGET(tid_, P, BASE, br, kt)
; #define LDA(dst, b, h) UFOR(m, 4) UFOR(k, 2) \
;     dst[m][k] = *reinterpret_cast<const bf16x8*>((char*)SA(b, h) + lds_byte(wr * 64 + m * 16 + fr, k * 32 + fq * 8))
; #define LDB(dst, b, h) UFOR(n, 2) UFOR(k, 2) \
;     dst[n][k] = *reinterpret_cast<const bf16x8*>((char*)SB(b, h) + lds_byte(wc * 32 + n * 16 + fr, k * 32 + fq * 8))
; #define MMA(ai, bj, At, Bq) do { __builtin_amdgcn_s_setprio(1); \
;     UFOR(m, 4) UFOR(n, 2) UFOR(k, 2) \
;       acc[ai][bj][m][n] = __builtin_amdgcn_mfma_f32_16x16x32_bf16(Bq[n][k], At[m][k], acc[ai][bj][m][n], 0, 0, 0); \
;     __builtin_amdgcn_s_setprio(0); } while (0)
; #define WAIT_V(n) asm volatile("s_waitcnt vmcnt(" #n ")" ::: "memory")
; #define WAIT_L(n) asm volatile("s_waitcnt lgkmcnt(" #n ")" ::: "memory")
; #define BAR __builtin_amdgcn_s_barrier()
; #define SCHED __builtin_amdgcn_sched_barrier(0)
; template <int EPI, int K, int KL> ...
;     ...
;     STAGE(SB(0, 1), Bt, bcol + HALF, t + 2);
;     WAIT_V(6); BAR; MMA(1, 1, At, B1); BAR;
;     LDB(B0, 1, 0); SCHED; LDA(At, 1, 0); STAGE(SA(0, 1), A, brow + HALF, t + 2);
;     WAIT_L(8); BAR; WAIT_L(0); MMA(0, 0, At, B0); BAR; SCHED;
;     LDB(B1, 1, 1); STAGE(SB(1, 0), Bt, bcol, t + 3);
;     BAR; WAIT_L(0); MMA(0, 1, At, B1); BAR;
;     LDA(At, 1, 1); STAGE(SA(1, 0), A, brow, t + 3);
;     BAR; WAIT_L(0); MMA(1, 0, At, B0); BAR; SCHED;
;     STAGE(SB(1, 1), Bt, bcol + HALF, t + 3);
;     WAIT_V(6); BAR; MMA(1, 1, At, B1); BAR;
	v_lshl_add_u64 v[136:137], v[242:243], 0, s[24:25]
	global_load_lds_dwordx4 v[136:137], off
	v_lshl_add_u64 v[136:137], v[244:245], 0, s[24:25]
	s_mov_b32 m0, s54
	s_nop 0
	global_load_lds_dwordx4 v[136:137], off
	s_waitcnt vmcnt(6)
	s_barrier
	v_mfma_f32_16x16x32_bf16 v[28:31], v[222:225], v[186:189], v[28:31]
	v_mfma_f32_16x16x32_bf16 v[24:27], v[230:233], v[186:189], v[24:27]
	v_mfma_f32_16x16x32_bf16 v[20:23], v[222:225], v[194:197], v[20:23]
	v_mfma_f32_16x16x32_bf16 v[16:19], v[230:233], v[194:197], v[16:19]
	v_mfma_f32_16x16x32_bf16 v[12:15], v[222:225], v[202:205], v[12:15]
	v_mfma_f32_16x16x32_bf16 v[8:11], v[230:233], v[202:205], v[8:11]
	v_mfma_f32_16x16x32_bf16 v[4:7], v[222:225], v[214:217], v[4:7]
	v_mfma_f32_16x16x32_bf16 v[0:3], v[230:233], v[214:217], v[0:3]
	v_mfma_f32_16x16x32_bf16 v[28:31], v[226:229], v[190:193], v[28:31]
	v_mfma_f32_16x16x32_bf16 v[24:27], v[234:237], v[190:193], v[24:27]
	v_mfma_f32_16x16x32_bf16 v[20:23], v[226:229], v[198:201], v[20:23]
	v_mfma_f32_16x16x32_bf16 v[16:19], v[234:237], v[198:201], v[16:19]
	v_mfma_f32_16x16x32_bf16 v[12:15], v[226:229], v[208:211], v[12:15]
	v_mfma_f32_16x16x32_bf16 v[8:11], v[234:237], v[208:211], v[8:11]
	v_mfma_f32_16x16x32_bf16 v[4:7], v[226:229], v[218:221], v[4:7]
	v_mfma_f32_16x16x32_bf16 v[0:3], v[234:237], v[218:221], v[0:3]
	s_barrier
	ds_read_b128 v[136:139], v165
	ds_read_b128 v[174:177], v165 offset:1024
	ds_read_b128 v[178:181], v165 offset:2048
	ds_read_b128 v[182:185], v165 offset:3072
	ds_read_b128 v[186:189], v162 offset:32768
	ds_read_b128 v[190:193], v162 offset:33792
	ds_read_b128 v[194:197], v161 offset:32768
	ds_read_b128 v[198:201], v161 offset:33792
	ds_read_b128 v[202:205], v160 offset:32768
	ds_read_b128 v[208:211], v160 offset:33792
	ds_read_b128 v[214:217], v159 offset:32768
	ds_read_b128 v[218:221], v159 offset:33792
	v_add_u32_e32 v134, 0x4000, v157
	v_lshl_add_u64 v[222:223], v[238:239], 0, s[28:29]
	v_readfirstlane_b32 s54, v134
	v_add_u32_e32 v134, 0x6000, v157
	s_mov_b32 m0, s54
	v_readfirstlane_b32 s54, v134
	global_load_lds_dwordx4 v[222:223], off
	v_lshl_add_u64 v[222:223], v[240:241], 0, s[28:29]
	s_mov_b32 m0, s54
	s_nop 0
	global_load_lds_dwordx4 v[222:223], off
	s_waitcnt lgkmcnt(8)
	s_barrier
	s_waitcnt lgkmcnt(0)
	s_waitcnt lgkmcnt(0)
	v_mfma_f32_16x16x32_bf16 v[124:127], v[136:139], v[186:189], v[124:127]
	v_mfma_f32_16x16x32_bf16 v[120:123], v[178:181], v[186:189], v[120:123]
	v_mfma_f32_16x16x32_bf16 v[116:119], v[136:139], v[194:197], v[116:119]
	v_mfma_f32_16x16x32_bf16 v[112:115], v[178:181], v[194:197], v[112:115]
	v_mfma_f32_16x16x32_bf16 v[108:111], v[136:139], v[202:205], v[108:111]
	v_mfma_f32_16x16x32_bf16 v[104:107], v[178:181], v[202:205], v[104:107]
	v_mfma_f32_16x16x32_bf16 v[100:103], v[136:139], v[214:217], v[100:103]
	v_mfma_f32_16x16x32_bf16 v[96:99], v[178:181], v[214:217], v[96:99]
	v_mfma_f32_16x16x32_bf16 v[124:127], v[174:177], v[190:193], v[124:127]
	v_mfma_f32_16x16x32_bf16 v[120:123], v[182:185], v[190:193], v[120:123]
	v_mfma_f32_16x16x32_bf16 v[116:119], v[174:177], v[198:201], v[116:119]
	v_mfma_f32_16x16x32_bf16 v[112:115], v[182:185], v[198:201], v[112:115]
	v_mfma_f32_16x16x32_bf16 v[108:111], v[174:177], v[208:211], v[108:111]
	v_mfma_f32_16x16x32_bf16 v[104:107], v[182:185], v[208:211], v[104:107]
	v_mfma_f32_16x16x32_bf16 v[100:103], v[174:177], v[218:221], v[100:103]
	v_mfma_f32_16x16x32_bf16 v[96:99], v[182:185], v[218:221], v[96:99]
	s_barrier
	ds_read_b128 v[222:225], v163
	ds_read_b128 v[226:229], v163 offset:1024
	ds_read_b128 v[230:233], v163 offset:2048
	ds_read_b128 v[234:237], v163 offset:3072
	v_readfirstlane_b32 s54, v164
	v_add_u32_e32 v134, 0x2000, v164
	v_lshl_add_u64 v[246:247], v[242:243], 0, s[94:95]
	s_mov_b32 m0, s54
	v_readfirstlane_b32 s54, v134
	global_load_lds_dwordx4 v[246:247], off
	v_lshl_add_u64 v[246:247], v[244:245], 0, s[94:95]
	s_mov_b32 m0, s54
	s_nop 0
	global_load_lds_dwordx4 v[246:247], off
	s_barrier
	s_waitcnt lgkmcnt(0)
	s_waitcnt lgkmcnt(0)
	v_mfma_f32_16x16x32_bf16 v[92:95], v[222:225], v[186:189], v[92:95]
	v_mfma_f32_16x16x32_bf16 v[88:91], v[230:233], v[186:189], v[88:91]
	v_mfma_f32_16x16x32_bf16 v[84:87], v[222:225], v[194:197], v[84:87]
	v_mfma_f32_16x16x32_bf16 v[80:83], v[230:233], v[194:197], v[80:83]
	v_mfma_f32_16x16x32_bf16 v[76:79], v[222:225], v[202:205], v[76:79]
	v_mfma_f32_16x16x32_bf16 v[72:75], v[230:233], v[202:205], v[72:75]
	v_mfma_f32_16x16x32_bf16 v[68:71], v[222:225], v[214:217], v[68:71]
	v_mfma_f32_16x16x32_bf16 v[64:67], v[230:233], v[214:217], v[64:67]
	v_mfma_f32_16x16x32_bf16 v[92:95], v[226:229], v[190:193], v[92:95]
	v_mfma_f32_16x16x32_bf16 v[88:91], v[234:237], v[190:193], v[88:91]
	v_mfma_f32_16x16x32_bf16 v[84:87], v[226:229], v[198:201], v[84:87]
	v_mfma_f32_16x16x32_bf16 v[80:83], v[234:237], v[198:201], v[80:83]
	v_mfma_f32_16x16x32_bf16 v[76:79], v[226:229], v[208:211], v[76:79]
	v_mfma_f32_16x16x32_bf16 v[72:75], v[234:237], v[208:211], v[72:75]
	v_mfma_f32_16x16x32_bf16 v[68:71], v[226:229], v[218:221], v[68:71]
	v_mfma_f32_16x16x32_bf16 v[64:67], v[234:237], v[218:221], v[64:67]
	v_readfirstlane_b32 s54, v166
	v_lshl_add_u64 v[238:239], v[238:239], 0, s[4:5]
	s_mov_b32 m0, s54
	v_readfirstlane_b32 s54, v167
	s_barrier
	ds_read_b128 v[186:189], v162 offset:49152
	ds_read_b128 v[190:193], v162 offset:50176
	ds_read_b128 v[194:197], v161 offset:49152
	ds_read_b128 v[198:201], v161 offset:50176
	ds_read_b128 v[202:205], v160 offset:49152
	ds_read_b128 v[208:211], v160 offset:50176
	ds_read_b128 v[214:217], v159 offset:49152
	ds_read_b128 v[218:221], v159 offset:50176
	global_load_lds_dwordx4 v[238:239], off
	v_lshl_add_u64 v[238:239], v[240:241], 0, s[4:5]
	s_mov_b32 m0, s54
	s_nop 0
	global_load_lds_dwordx4 v[238:239], off
	s_barrier
; #define STAGE(P, BASE, br, kt) STAGET(tid_, P, BASE, br, kt)
; #define LDA(dst, b, h) UFOR(m, 4) UFOR(k, 2) \
;     dst[m][k] = *reinterpret_cast<const bf16x8*>((char*)SA(b, h) + lds_byte(wr * 64 + m * 16 + fr, k * 32 + fq * 8))
; #define LDB(dst, b, h) UFOR(n, 2) UFOR(k, 2) \
;     dst[n][k] = *reinterpret_cast<const bf16x8*>((char*)SB(b, h) + lds_byte(wc * 32 + n * 16 + fr, k * 32 + fq * 8))
; #define MMA(ai, bj, At, Bq) do { __builtin_amdgcn_s_setprio(1); \
;     UFOR(m, 4) UFOR(n, 2) UFOR(k, 2) \
;       acc[ai][bj][m][n] = __builtin_amdgcn_mfma_f32_16x16x32_bf16(Bq[n][k], At[m][k], acc[ai][bj][m][n], 0, 0, 0); \
;     __builtin_amdgcn_s_setprio(0); } while (0)
; #define WAIT_V(n) asm volatile("s_waitcnt vmcnt(" #n ")" ::: "memory")
; #define WAIT_L(n) asm volatile("s_waitcnt lgkmcnt(" #n ")" ::: "memory")
; #define BAR __builtin_amdgcn_s_barrier()
; template <int EPI, int K, int KL> ...
;     ...
;     STAGE(SB(1, 1), Bt, bcol + HALF, t + 3);
;     WAIT_V(6); BAR; MMA(1, 1, At, B1); BAR;
;   }
;   { LDB(B0, 0, 0); LDA(At, 0, 0); STAGE(SA(1, 1), A, brow + HALF, nt - 1);
;     BAR; WAIT_L(0); MMA(0, 0, At, B0); BAR;
;     LDB(B1, 0, 1); BAR; WAIT_L(0); MMA(0, 1, At, B1); BAR;
	s_waitcnt lgkmcnt(0)
	s_waitcnt lgkmcnt(0)
	v_mfma_f32_16x16x32_bf16 v[60:63], v[136:139], v[186:189], v[60:63]
	v_mfma_f32_16x16x32_bf16 v[56:59], v[178:181], v[186:189], v[56:59]
	v_mfma_f32_16x16x32_bf16 v[52:55], v[136:139], v[194:197], v[52:55]
	v_mfma_f32_16x16x32_bf16 v[48:51], v[178:181], v[194:197], v[48:51]
	v_mfma_f32_16x16x32_bf16 v[44:47], v[136:139], v[202:205], v[44:47]
	v_mfma_f32_16x16x32_bf16 v[40:43], v[178:181], v[202:205], v[40:43]
	v_mfma_f32_16x16x32_bf16 v[36:39], v[136:139], v[214:217], v[36:39]
	v_mfma_f32_16x16x32_bf16 v[32:35], v[178:181], v[214:217], v[32:35]
	v_mfma_f32_16x16x32_bf16 v[60:63], v[174:177], v[190:193], v[60:63]
	v_mfma_f32_16x16x32_bf16 v[56:59], v[182:185], v[190:193], v[56:59]
	v_mfma_f32_16x16x32_bf16 v[52:55], v[174:177], v[198:201], v[52:55]
	v_mfma_f32_16x16x32_bf16 v[48:51], v[182:185], v[198:201], v[48:51]
	v_mfma_f32_16x16x32_bf16 v[44:47], v[174:177], v[208:211], v[44:47]
	v_mfma_f32_16x16x32_bf16 v[40:43], v[182:185], v[208:211], v[40:43]
	v_mfma_f32_16x16x32_bf16 v[36:39], v[174:177], v[218:221], v[36:39]
	v_mfma_f32_16x16x32_bf16 v[32:35], v[182:185], v[218:221], v[32:35]
	v_readfirstlane_b32 s54, v168
	v_add_u32_e32 v134, 0x2000, v168
	s_mov_b32 m0, s54
	v_readfirstlane_b32 s54, v134
	s_barrier
	v_lshl_add_u64 v[136:137], v[242:243], 0, s[10:11]
	global_load_lds_dwordx4 v[136:137], off
	v_lshl_add_u64 v[136:137], v[244:245], 0, s[10:11]
	s_mov_b32 m0, s54
	s_nop 0
	global_load_lds_dwordx4 v[136:137], off
	s_waitcnt vmcnt(6)
	s_barrier
	v_mfma_f32_16x16x32_bf16 v[28:31], v[222:225], v[186:189], v[28:31]
	v_mfma_f32_16x16x32_bf16 v[24:27], v[230:233], v[186:189], v[24:27]
	v_mfma_f32_16x16x32_bf16 v[20:23], v[222:225], v[194:197], v[20:23]
	v_mfma_f32_16x16x32_bf16 v[16:19], v[230:233], v[194:197], v[16:19]
	v_mfma_f32_16x16x32_bf16 v[12:15], v[222:225], v[202:205], v[12:15]
	v_mfma_f32_16x16x32_bf16 v[8:11], v[230:233], v[202:205], v[8:11]
	v_mfma_f32_16x16x32_bf16 v[4:7], v[222:225], v[214:217], v[4:7]
	v_mfma_f32_16x16x32_bf16 v[0:3], v[230:233], v[214:217], v[0:3]
	v_mfma_f32_16x16x32_bf16 v[28:31], v[226:229], v[190:193], v[28:31]
	v_mfma_f32_16x16x32_bf16 v[24:27], v[234:237], v[190:193], v[24:27]
	v_mfma_f32_16x16x32_bf16 v[20:23], v[226:229], v[198:201], v[20:23]
	v_mfma_f32_16x16x32_bf16 v[16:19], v[234:237], v[198:201], v[16:19]
	v_mfma_f32_16x16x32_bf16 v[12:15], v[226:229], v[208:211], v[12:15]
	v_mfma_f32_16x16x32_bf16 v[8:11], v[234:237], v[208:211], v[8:11]
	v_mfma_f32_16x16x32_bf16 v[4:7], v[226:229], v[218:221], v[4:7]
	v_mfma_f32_16x16x32_bf16 v[0:3], v[234:237], v[218:221], v[0:3]
	s_add_i32 s19, s19, 2
	v_lshl_add_u64 v[144:145], v[144:145], 0, s[20:21]
	v_lshl_add_u64 v[146:147], v[146:147], 0, s[20:21]
	v_lshl_add_u64 v[148:149], v[148:149], 0, s[20:21]
	s_cmpk_lt_u32 s19, 0x54
	v_lshl_add_u64 v[150:151], v[150:151], 0, s[20:21]
	s_cbranch_scc1 .Lkrot_1184
	s_barrier
	s_add_u32 s52, s52, 0x162b80
	s_addc_u32 s53, s53, 0
	v_lshl_add_u64 v[130:131], s[52:53], 0, v[130:131]
	v_readfirstlane_b32 s19, v171
	v_lshl_add_u64 v[128:129], v[128:129], 1, v[130:131]
	s_mov_b32 m0, s19
	ds_read_b128 v[136:139], v170
	ds_read_b128 v[144:147], v170 offset:1024
	ds_read_b128 v[148:151], v170 offset:2048
	ds_read_b128 v[174:177], v170 offset:3072
	ds_read_b128 v[178:181], v162
	ds_read_b128 v[182:185], v162 offset:1024
	ds_read_b128 v[186:189], v161
	ds_read_b128 v[190:193], v161 offset:1024
	ds_read_b128 v[194:197], v160
	ds_read_b128 v[198:201], v160 offset:1024
	ds_read_b128 v[202:205], v159
	ds_read_b128 v[208:211], v159 offset:1024
	global_load_lds_dwordx4 v[128:129], off
	v_lshl_add_u64 v[128:129], s[52:53], 0, v[142:143]
	v_readfirstlane_b32 s19, v172
	v_lshl_add_u64 v[128:129], v[140:141], 1, v[128:129]
	s_mov_b32 m0, s19
	s_nop 0
	global_load_lds_dwordx4 v[128:129], off
	s_barrier
	s_waitcnt lgkmcnt(0)
	s_waitcnt lgkmcnt(0)
	v_mfma_f32_16x16x32_bf16 v[120:123], v[148:151], v[178:181], v[120:123]
	v_mfma_f32_16x16x32_bf16 v[116:119], v[136:139], v[186:189], v[116:119]
	v_mfma_f32_16x16x32_bf16 v[112:115], v[148:151], v[186:189], v[112:115]
	v_mfma_f32_16x16x32_bf16 v[108:111], v[136:139], v[194:197], v[108:111]
	v_mfma_f32_16x16x32_bf16 v[104:107], v[148:151], v[194:197], v[104:107]
	v_mfma_f32_16x16x32_bf16 v[100:103], v[136:139], v[202:205], v[100:103]
	v_mfma_f32_16x16x32_bf16 v[96:99], v[148:151], v[202:205], v[96:99]
	v_mfma_f32_16x16x32_bf16 v[124:127], v[136:139], v[178:181], v[124:127]
	v_mfma_f32_16x16x32_bf16 v[120:123], v[174:177], v[182:185], v[120:123]
	v_mfma_f32_16x16x32_bf16 v[116:119], v[144:147], v[190:193], v[116:119]
	v_mfma_f32_16x16x32_bf16 v[112:115], v[174:177], v[190:193], v[112:115]
	v_mfma_f32_16x16x32_bf16 v[108:111], v[144:147], v[198:201], v[108:111]
	v_mfma_f32_16x16x32_bf16 v[104:107], v[174:177], v[198:201], v[104:107]
	v_mfma_f32_16x16x32_bf16 v[100:103], v[144:147], v[208:211], v[100:103]
	v_mfma_f32_16x16x32_bf16 v[96:99], v[174:177], v[208:211], v[96:99]
	v_mfma_f32_16x16x32_bf16 v[124:127], v[144:147], v[182:185], v[124:127]
	s_barrier
	ds_read_b128 v[128:131], v169
	ds_read_b128 v[140:143], v169 offset:1024
	ds_read_b128 v[170:173], v169 offset:2048
	ds_read_b128 v[166:169], v169 offset:3072
	s_barrier
; #define LDA(dst, b, h) UFOR(m, 4) UFOR(k, 2) \
;     dst[m][k] = *reinterpret_cast<const bf16x8*>((char*)SA(b, h) + lds_byte(wr * 64 + m * 16 + fr, k * 32 + fq * 8))
; #define LDB(dst, b, h) UFOR(n, 2) UFOR(k, 2) \
;     dst[n][k] = *reinterpret_cast<const bf16x8*>((char*)SB(b, h) + lds_byte(wc * 32 + n * 16 + fr, k * 32 + fq * 8))
; #define MMA(ai, bj, At, Bq) do { __builtin_amdgcn_s_setprio(1); \
;     UFOR(m, 4) UFOR(n, 2) UFOR(k, 2) \
;       acc[ai][bj][m][n] = __builtin_amdgcn_mfma_f32_16x16x32_bf16(Bq[n][k], At[m][k], acc[ai][bj][m][n], 0, 0, 0); \
;     __builtin_amdgcn_s_setprio(0); } while (0)
; #define WAIT_V(n) asm volatile("s_waitcnt vmcnt(" #n ")" ::: "memory")
; #define WAIT_L(n) asm volatile("s_waitcnt lgkmcnt(" #n ")" ::: "memory")
; #define BAR __builtin_amdgcn_s_barrier()
; template <int EPI, int K, int KL> ...
;     ...
;     LDB(B1, 0, 1); BAR; WAIT_L(0); MMA(0, 1, At, B1); BAR;
;     LDA(At, 0, 1); WAIT_V(4); BAR; WAIT_L(0); MMA(1, 0, At, B0); MMA(1, 1, At, B1); BAR; }
;   { LDB(B0, 1, 0); LDA(At, 1, 0); WAIT_V(2); BAR; WAIT_L(0); MMA(0, 0, At, B0); BAR;
;     LDB(B1, 1, 1); WAIT_V(0); BAR; WAIT_L(0); MMA(0, 1, At, B1); BAR;
	s_waitcnt lgkmcnt(0)
	s_waitcnt lgkmcnt(0)
	v_mfma_f32_16x16x32_bf16 v[80:83], v[170:173], v[186:189], v[80:83]
	v_mfma_f32_16x16x32_bf16 v[76:79], v[128:131], v[194:197], v[76:79]
	v_mfma_f32_16x16x32_bf16 v[68:71], v[128:131], v[202:205], v[68:71]
	v_mfma_f32_16x16x32_bf16 v[64:67], v[170:173], v[202:205], v[64:67]
	v_mfma_f32_16x16x32_bf16 v[92:95], v[128:131], v[178:181], v[92:95]
	v_mfma_f32_16x16x32_bf16 v[88:91], v[170:173], v[178:181], v[88:91]
	v_mfma_f32_16x16x32_bf16 v[84:87], v[128:131], v[186:189], v[84:87]
	v_mfma_f32_16x16x32_bf16 v[80:83], v[166:169], v[190:193], v[80:83]
	v_mfma_f32_16x16x32_bf16 v[76:79], v[140:143], v[198:201], v[76:79]
	v_mfma_f32_16x16x32_bf16 v[72:75], v[170:173], v[194:197], v[72:75]
	v_mfma_f32_16x16x32_bf16 v[68:71], v[140:143], v[208:211], v[68:71]
	v_mfma_f32_16x16x32_bf16 v[64:67], v[166:169], v[208:211], v[64:67]
	v_mfma_f32_16x16x32_bf16 v[214:217], v[140:143], v[182:185], v[92:95]
	v_mfma_f32_16x16x32_bf16 v[178:181], v[166:169], v[182:185], v[88:91]
	v_mfma_f32_16x16x32_bf16 v[182:185], v[140:143], v[190:193], v[84:87]
	v_mfma_f32_16x16x32_bf16 v[186:189], v[166:169], v[198:201], v[72:75]
	s_barrier
	s_nop 0
	ds_read_b128 v[72:75], v162 offset:16384
	ds_read_b128 v[84:87], v162 offset:17408
	ds_read_b128 v[88:91], v161 offset:16384
	ds_read_b128 v[92:95], v161 offset:17408
	ds_read_b128 v[190:193], v160 offset:16384
	ds_read_b128 v[194:197], v160 offset:17408
	ds_read_b128 v[198:201], v159 offset:16384
	ds_read_b128 v[202:205], v159 offset:17408
	s_waitcnt vmcnt(4)
	s_barrier
	s_waitcnt lgkmcnt(0)
	s_waitcnt lgkmcnt(0)
	v_mfma_f32_16x16x32_bf16 v[48:51], v[148:151], v[88:91], v[48:51]
	v_mfma_f32_16x16x32_bf16 v[40:43], v[148:151], v[190:193], v[40:43]
	v_mfma_f32_16x16x32_bf16 v[36:39], v[136:139], v[198:201], v[36:39]
	v_mfma_f32_16x16x32_bf16 v[32:35], v[148:151], v[198:201], v[32:35]
	v_mfma_f32_16x16x32_bf16 v[60:63], v[136:139], v[72:75], v[60:63]
	v_mfma_f32_16x16x32_bf16 v[56:59], v[148:151], v[72:75], v[56:59]
	v_mfma_f32_16x16x32_bf16 v[52:55], v[136:139], v[88:91], v[52:55]
	v_mfma_f32_16x16x32_bf16 v[48:51], v[174:177], v[92:95], v[48:51]
	v_mfma_f32_16x16x32_bf16 v[44:47], v[136:139], v[190:193], v[44:47]
	v_mfma_f32_16x16x32_bf16 v[40:43], v[174:177], v[194:197], v[40:43]
	v_mfma_f32_16x16x32_bf16 v[36:39], v[144:147], v[202:205], v[36:39]
	v_mfma_f32_16x16x32_bf16 v[32:35], v[174:177], v[202:205], v[32:35]
	v_mfma_f32_16x16x32_bf16 v[208:211], v[144:147], v[84:87], v[60:63]
	v_mfma_f32_16x16x32_bf16 v[218:221], v[174:177], v[84:87], v[56:59]
	v_mfma_f32_16x16x32_bf16 v[222:225], v[144:147], v[92:95], v[52:55]
	v_mfma_f32_16x16x32_bf16 v[226:229], v[144:147], v[194:197], v[44:47]
	v_mfma_f32_16x16x32_bf16 v[0:3], v[170:173], v[198:201], v[0:3]
	v_mfma_f32_16x16x32_bf16 v[28:31], v[128:131], v[72:75], v[28:31]
	v_mfma_f32_16x16x32_bf16 v[24:27], v[170:173], v[72:75], v[24:27]
	v_mfma_f32_16x16x32_bf16 v[20:23], v[128:131], v[88:91], v[20:23]
	v_mfma_f32_16x16x32_bf16 v[16:19], v[170:173], v[88:91], v[16:19]
	v_mfma_f32_16x16x32_bf16 v[12:15], v[128:131], v[190:193], v[12:15]
	v_mfma_f32_16x16x32_bf16 v[8:11], v[170:173], v[190:193], v[8:11]
	v_mfma_f32_16x16x32_bf16 v[4:7], v[128:131], v[198:201], v[4:7]
	v_mfma_f32_16x16x32_bf16 v[0:3], v[166:169], v[202:205], v[0:3]
	v_mfma_f32_16x16x32_bf16 v[136:139], v[140:143], v[84:87], v[28:31]
	v_mfma_f32_16x16x32_bf16 v[144:147], v[166:169], v[84:87], v[24:27]
	v_mfma_f32_16x16x32_bf16 v[148:151], v[140:143], v[92:95], v[20:23]
	v_mfma_f32_16x16x32_bf16 v[174:177], v[166:169], v[92:95], v[16:19]
	v_mfma_f32_16x16x32_bf16 v[230:233], v[140:143], v[194:197], v[12:15]
	v_mfma_f32_16x16x32_bf16 v[190:193], v[166:169], v[194:197], v[8:11]
	v_mfma_f32_16x16x32_bf16 v[140:143], v[140:143], v[202:205], v[4:7]
	s_barrier
	s_nop 0
	ds_read_b128 v[4:7], v165
	ds_read_b128 v[8:11], v165 offset:1024
	ds_read_b128 v[16:19], v165 offset:2048
	ds_read_b128 v[164:167], v165 offset:3072
	ds_read_b128 v[12:15], v162 offset:32768
	ds_read_b128 v[20:23], v162 offset:33792
	ds_read_b128 v[24:27], v161 offset:32768
	ds_read_b128 v[44:47], v161 offset:33792
	ds_read_b128 v[168:171], v160 offset:32768
	ds_read_b128 v[194:197], v160 offset:33792
	ds_read_b128 v[198:201], v159 offset:32768
	ds_read_b128 v[202:205], v159 offset:33792
	s_waitcnt vmcnt(2)
	s_barrier
; #define LDA(dst, b, h) UFOR(m, 4) UFOR(k, 2) \
;     dst[m][k] = *reinterpret_cast<const bf16x8*>((char*)SA(b, h) + lds_byte(wr * 64 + m * 16 + fr, k * 32 + fq * 8))
; #define LDB(dst, b, h) UFOR(n, 2) UFOR(k, 2) \
;     dst[n][k] = *reinterpret_cast<const bf16x8*>((char*)SB(b, h) + lds_byte(wc * 32 + n * 16 + fr, k * 32 + fq * 8))
; #define MMA(ai, bj, At, Bq) do { __builtin_amdgcn_s_setprio(1); \
;     UFOR(m, 4) UFOR(n, 2) UFOR(k, 2) \
;       acc[ai][bj][m][n] = __builtin_amdgcn_mfma_f32_16x16x32_bf16(Bq[n][k], At[m][k], acc[ai][bj][m][n], 0, 0, 0); \
;     __builtin_amdgcn_s_setprio(0); } while (0)
; #define WAIT_V(n) asm volatile("s_waitcnt vmcnt(" #n ")" ::: "memory")
; #define WAIT_L(n) asm volatile("s_waitcnt lgkmcnt(" #n ")" ::: "memory")
; #define BAR __builtin_amdgcn_s_barrier()
; template <int EPI, int K, int KL> ...
;     ...
;   { LDB(B0, 1, 0); LDA(At, 1, 0); WAIT_V(2); BAR; WAIT_L(0); MMA(0, 0, At, B0); BAR;
;     LDB(B1, 1, 1); WAIT_V(0); BAR; WAIT_L(0); MMA(0, 1, At, B1); BAR;
;     LDA(At, 1, 1); BAR; WAIT_L(0); MMA(1, 0, At, B0); MMA(1, 1, At, B1); BAR; }
;   if (wr == 0) BAR;
;   if (EPI != EPI_UPG && EPI != EPI_PART && has_next) {
;     int t2 = tid_; asm volatile("" : "+v"(t2));
;     STAGET(t2, SB(0, 0), Bt, nbcol, 0); STAGET(t2, SA(0, 0), A, nbrow, 0);
;     STAGET(t2, SB(0, 1), Bt, nbcol + HALF, 0); STAGET(t2, SA(0, 1), A, nbrow + HALF, 0);
;   }
	s_waitcnt lgkmcnt(0)
	s_waitcnt lgkmcnt(0)
	v_mfma_f32_16x16x32_bf16 v[28:31], v[4:7], v[12:15], v[124:127]
	v_mfma_f32_16x16x32_bf16 v[128:131], v[8:11], v[20:23], v[28:31]
	v_mfma_f32_16x16x32_bf16 v[28:31], v[16:19], v[12:15], v[120:123]
	v_mfma_f32_16x16x32_bf16 v[92:95], v[164:167], v[20:23], v[28:31]
	v_mfma_f32_16x16x32_bf16 v[28:31], v[4:7], v[24:27], v[116:119]
	v_mfma_f32_16x16x32_bf16 v[120:123], v[8:11], v[44:47], v[28:31]
	v_mfma_f32_16x16x32_bf16 v[28:31], v[16:19], v[24:27], v[112:115]
	v_mfma_f32_16x16x32_bf16 v[88:91], v[164:167], v[44:47], v[28:31]
	v_mfma_f32_16x16x32_bf16 v[28:31], v[4:7], v[168:171], v[108:111]
	v_mfma_f32_16x16x32_bf16 v[116:119], v[8:11], v[194:197], v[28:31]
	v_mfma_f32_16x16x32_bf16 v[28:31], v[16:19], v[168:171], v[104:107]
	v_mfma_f32_16x16x32_bf16 v[84:87], v[164:167], v[194:197], v[28:31]
	v_mfma_f32_16x16x32_bf16 v[28:31], v[4:7], v[198:201], v[100:103]
	v_mfma_f32_16x16x32_bf16 v[108:111], v[8:11], v[202:205], v[28:31]
	v_mfma_f32_16x16x32_bf16 v[28:31], v[16:19], v[198:201], v[96:99]
	v_mfma_f32_16x16x32_bf16 v[72:75], v[164:167], v[202:205], v[28:31]
	s_barrier
	ds_read_b128 v[124:127], v163
	ds_read_b128 v[234:237], v163 offset:1024
	ds_read_b128 v[238:241], v163 offset:2048
	ds_read_b128 v[242:245], v163 offset:3072
	s_waitcnt vmcnt(0)
	s_barrier
	s_waitcnt lgkmcnt(0)
	s_waitcnt lgkmcnt(0)
	v_mfma_f32_16x16x32_bf16 v[28:31], v[124:127], v[12:15], v[214:217]
	v_mfma_f32_16x16x32_bf16 v[12:15], v[238:241], v[12:15], v[178:181]
	v_mfma_f32_16x16x32_bf16 v[60:63], v[234:237], v[20:23], v[28:31]
	v_mfma_f32_16x16x32_bf16 v[28:31], v[242:245], v[20:23], v[12:15]
	v_mfma_f32_16x16x32_bf16 v[12:15], v[124:127], v[24:27], v[182:185]
	v_mfma_f32_16x16x32_bf16 v[56:59], v[234:237], v[44:47], v[12:15]
	v_mfma_f32_16x16x32_bf16 v[12:15], v[238:241], v[24:27], v[80:83]
	v_mfma_f32_16x16x32_bf16 v[24:27], v[242:245], v[44:47], v[12:15]
	v_mfma_f32_16x16x32_bf16 v[12:15], v[124:127], v[168:171], v[76:79]
	v_mfma_f32_16x16x32_bf16 v[52:55], v[234:237], v[194:197], v[12:15]
	v_mfma_f32_16x16x32_bf16 v[12:15], v[238:241], v[168:171], v[186:189]
	v_mfma_f32_16x16x32_bf16 v[20:23], v[242:245], v[194:197], v[12:15]
	v_mfma_f32_16x16x32_bf16 v[12:15], v[124:127], v[198:201], v[68:71]
	v_mfma_f32_16x16x32_bf16 v[44:47], v[234:237], v[202:205], v[12:15]
	v_mfma_f32_16x16x32_bf16 v[12:15], v[238:241], v[198:201], v[64:67]
	v_mfma_f32_16x16x32_bf16 v[12:15], v[242:245], v[202:205], v[12:15]
	s_barrier
	ds_read_b128 v[168:171], v162 offset:49152
	ds_read_b128 v[178:181], v162 offset:50176
	ds_read_b128 v[182:185], v161 offset:49152
	ds_read_b128 v[186:189], v161 offset:50176
	ds_read_b128 v[194:197], v160 offset:49152
	ds_read_b128 v[160:163], v160 offset:50176
	ds_read_b128 v[198:201], v159 offset:49152
	ds_read_b128 v[156:159], v159 offset:50176
	s_barrier
	s_waitcnt lgkmcnt(0)
	s_waitcnt lgkmcnt(0)
	v_mfma_f32_16x16x32_bf16 v[64:67], v[4:7], v[168:171], v[208:211]
	v_mfma_f32_16x16x32_bf16 v[112:115], v[8:11], v[178:181], v[64:67]
	v_mfma_f32_16x16x32_bf16 v[64:67], v[16:19], v[168:171], v[218:221]
	v_mfma_f32_16x16x32_bf16 v[48:51], v[16:19], v[182:185], v[48:51]
	v_mfma_f32_16x16x32_bf16 v[80:83], v[164:167], v[178:181], v[64:67]
	v_mfma_f32_16x16x32_bf16 v[64:67], v[4:7], v[182:185], v[222:225]
	v_mfma_f32_16x16x32_bf16 v[76:79], v[164:167], v[186:189], v[48:51]
	v_mfma_f32_16x16x32_bf16 v[48:51], v[4:7], v[194:197], v[226:229]
	v_mfma_f32_16x16x32_bf16 v[4:7], v[4:7], v[198:201], v[36:39]
	v_mfma_f32_16x16x32_bf16 v[40:43], v[16:19], v[194:197], v[40:43]
	v_mfma_f32_16x16x32_bf16 v[96:99], v[8:11], v[156:159], v[4:7]
	v_mfma_f32_16x16x32_bf16 v[4:7], v[16:19], v[198:201], v[32:35]
	v_mfma_f32_16x16x32_bf16 v[104:107], v[8:11], v[186:189], v[64:67]
	v_mfma_f32_16x16x32_bf16 v[100:103], v[8:11], v[160:163], v[48:51]
	v_mfma_f32_16x16x32_bf16 v[68:71], v[164:167], v[160:163], v[40:43]
	v_mfma_f32_16x16x32_bf16 v[64:67], v[164:167], v[156:159], v[4:7]
	v_mfma_f32_16x16x32_bf16 v[4:7], v[124:127], v[168:171], v[136:139]
	v_mfma_f32_16x16x32_bf16 v[48:51], v[234:237], v[178:181], v[4:7]
	v_mfma_f32_16x16x32_bf16 v[4:7], v[238:241], v[168:171], v[144:147]
	v_mfma_f32_16x16x32_bf16 v[16:19], v[242:245], v[178:181], v[4:7]
	v_mfma_f32_16x16x32_bf16 v[4:7], v[124:127], v[182:185], v[148:151]
	v_mfma_f32_16x16x32_bf16 v[40:43], v[234:237], v[186:189], v[4:7]
	v_mfma_f32_16x16x32_bf16 v[4:7], v[238:241], v[182:185], v[174:177]
	v_mfma_f32_16x16x32_bf16 v[8:11], v[242:245], v[186:189], v[4:7]
	v_mfma_f32_16x16x32_bf16 v[4:7], v[124:127], v[194:197], v[230:233]
	v_mfma_f32_16x16x32_bf16 v[36:39], v[234:237], v[160:163], v[4:7]
	v_mfma_f32_16x16x32_bf16 v[4:7], v[238:241], v[194:197], v[190:193]
	v_mfma_f32_16x16x32_bf16 v[32:35], v[124:127], v[198:201], v[140:143]
	v_mfma_f32_16x16x32_bf16 v[0:3], v[238:241], v[198:201], v[0:3]
	v_mfma_f32_16x16x32_bf16 v[4:7], v[242:245], v[160:163], v[4:7]
	v_mfma_f32_16x16x32_bf16 v[32:35], v[234:237], v[156:159], v[32:35]
	v_mfma_f32_16x16x32_bf16 v[0:3], v[242:245], v[156:159], v[0:3]
	s_movk_i32 s19, 0x100
	v_cmp_gt_u32_e32 vcc, s19, v154
	s_barrier
	s_and_saveexec_b64 s[52:53], vcc
	s_cbranch_execnz .LBB0_1189
	s_or_b64 exec, exec, s[52:53]
	s_andn2_b64 vcc, exec, s[50:51]
	s_cbranch_vccz .LBB0_1190

; #define STAGE(P, BASE, br, kt) STAGET(tid_, P, BASE, br, kt)
; #define LDA(dst, b, h) UFOR(m, 4) UFOR(k, 2) \
;     dst[m][k] = *reinterpret_cast<const bf16x8*>((char*)SA(b, h) + lds_byte(wr * 64 + m * 16 + fr, k * 32 + fq * 8))
; #define LDB(dst, b, h) UFOR(n, 2) UFOR(k, 2) \
;     dst[n][k] = *reinterpret_cast<const bf16x8*>((char*)SB(b, h) + lds_byte(wc * 32 + n * 16 + fr, k * 32 + fq * 8))
; #define MMA(ai, bj, At, Bq) do { __builtin_amdgcn_s_setprio(1); \
;     UFOR(m, 4) UFOR(n, 2) UFOR(k, 2) \
;       acc[ai][bj][m][n] = __builtin_amdgcn_mfma_f32_16x16x32_bf16(Bq[n][k], At[m][k], acc[ai][bj][m][n], 0, 0, 0); \
;     __builtin_amdgcn_s_setprio(0); } while (0)
; #define WAIT_V(n) asm volatile("s_waitcnt vmcnt(" #n ")" ::: "memory")
; #define WAIT_L(n) asm volatile("s_waitcnt lgkmcnt(" #n ")" ::: "memory")
; #define BAR __builtin_amdgcn_s_barrier()
; #define SCHED __builtin_amdgcn_sched_barrier(0)
; template <int EPI, int K, int KL> ...
;     ...
;     LDB(B0, 0, 0); SCHED; LDA(At, 0, 0); STAGE(SA(1, 1), A, brow + HALF, t + 1);
;     WAIT_L(8); BAR; WAIT_L(0); MMA(0, 0, At, B0); BAR; SCHED;
;     LDB(B1, 0, 1); STAGE(SB(0, 0), Bt, bcol, t + 2);
;     BAR; WAIT_L(0); MMA(0, 1, At, B1); BAR;
;     LDA(At, 0, 1); STAGE(SA(0, 0), A, brow, t + 2);
;     BAR; WAIT_L(0); MMA(1, 0, At, B0); BAR; SCHED;
;     STAGE(SB(0, 1), Bt, bcol + HALF, t + 2);
;     WAIT_V(6); BAR; MMA(1, 1, At, B1); BAR;
.LBB0_1204:
	ds_read_b128 v[136:139], v175
	ds_read_b128 v[178:181], v175 offset:1024
	ds_read_b128 v[182:185], v175 offset:2048
	ds_read_b128 v[186:189], v175 offset:3072
	ds_read_b128 v[190:193], v160
	ds_read_b128 v[194:197], v160 offset:1024
	ds_read_b128 v[198:201], v159
	ds_read_b128 v[202:205], v159 offset:1024
	ds_read_b128 v[208:211], v158
	ds_read_b128 v[214:217], v158 offset:1024
	ds_read_b128 v[218:221], v157
	ds_read_b128 v[222:225], v157 offset:1024
	v_add_u32_e32 v176, 0xc000, v161
	v_lshl_add_u64 v[152:153], v[148:149], 0, s[44:45]
	v_readfirstlane_b32 s15, v176
	v_lshl_add_u64 v[154:155], v[152:153], 0, s[58:59]
	s_mov_b32 m0, s15
	v_add_u32_e32 v177, 0xe000, v161
	global_load_lds_dwordx4 v[154:155], off
	v_lshl_add_u64 v[154:155], v[150:151], 0, s[44:45]
	v_readfirstlane_b32 s15, v177
	v_lshl_add_u64 v[226:227], v[154:155], 0, s[58:59]
	s_mov_b32 m0, s15
	s_nop 0
	global_load_lds_dwordx4 v[226:227], off
	s_waitcnt lgkmcnt(8)
	s_barrier
	s_waitcnt lgkmcnt(0)
	s_waitcnt lgkmcnt(0)
	v_mfma_f32_16x16x32_bf16 v[124:127], v[136:139], v[190:193], v[124:127]
	v_mfma_f32_16x16x32_bf16 v[120:123], v[182:185], v[190:193], v[120:123]
	v_mfma_f32_16x16x32_bf16 v[116:119], v[136:139], v[198:201], v[116:119]
	v_mfma_f32_16x16x32_bf16 v[112:115], v[182:185], v[198:201], v[112:115]
	v_mfma_f32_16x16x32_bf16 v[108:111], v[136:139], v[208:211], v[108:111]
	v_mfma_f32_16x16x32_bf16 v[104:107], v[182:185], v[208:211], v[104:107]
	v_mfma_f32_16x16x32_bf16 v[100:103], v[136:139], v[218:221], v[100:103]
	v_mfma_f32_16x16x32_bf16 v[96:99], v[182:185], v[218:221], v[96:99]
	v_mfma_f32_16x16x32_bf16 v[124:127], v[178:181], v[194:197], v[124:127]
	v_mfma_f32_16x16x32_bf16 v[120:123], v[186:189], v[194:197], v[120:123]
	v_mfma_f32_16x16x32_bf16 v[116:119], v[178:181], v[202:205], v[116:119]
	v_mfma_f32_16x16x32_bf16 v[112:115], v[186:189], v[202:205], v[112:115]
	v_mfma_f32_16x16x32_bf16 v[108:111], v[178:181], v[214:217], v[108:111]
	v_mfma_f32_16x16x32_bf16 v[104:107], v[186:189], v[214:217], v[104:107]
	v_mfma_f32_16x16x32_bf16 v[100:103], v[178:181], v[222:225], v[100:103]
	v_mfma_f32_16x16x32_bf16 v[96:99], v[186:189], v[222:225], v[96:99]
	s_barrier
	ds_read_b128 v[226:229], v173
	ds_read_b128 v[230:233], v173 offset:1024
	ds_read_b128 v[234:237], v173 offset:2048
	ds_read_b128 v[238:241], v173 offset:3072
	v_lshl_add_u64 v[242:243], v[144:145], 0, s[44:45]
	v_readfirstlane_b32 s15, v156
	v_lshl_add_u64 v[244:245], v[242:243], 0, s[22:23]
	s_mov_b32 m0, s15
	v_add_u32_e32 v248, 0x2000, v156
	global_load_lds_dwordx4 v[244:245], off
	v_lshl_add_u64 v[244:245], v[146:147], 0, s[44:45]
	v_readfirstlane_b32 s15, v248
	v_lshl_add_u64 v[246:247], v[244:245], 0, s[22:23]
	s_mov_b32 m0, s15
	s_nop 0
	global_load_lds_dwordx4 v[246:247], off
	s_barrier
	s_waitcnt lgkmcnt(0)
	s_waitcnt lgkmcnt(0)
	v_mfma_f32_16x16x32_bf16 v[92:95], v[226:229], v[190:193], v[92:95]
	v_mfma_f32_16x16x32_bf16 v[88:91], v[234:237], v[190:193], v[88:91]
	v_mfma_f32_16x16x32_bf16 v[84:87], v[226:229], v[198:201], v[84:87]
	v_mfma_f32_16x16x32_bf16 v[80:83], v[234:237], v[198:201], v[80:83]
	v_mfma_f32_16x16x32_bf16 v[76:79], v[226:229], v[208:211], v[76:79]
	v_mfma_f32_16x16x32_bf16 v[72:75], v[234:237], v[208:211], v[72:75]
	v_mfma_f32_16x16x32_bf16 v[68:71], v[226:229], v[218:221], v[68:71]
	v_mfma_f32_16x16x32_bf16 v[64:67], v[234:237], v[218:221], v[64:67]
	v_mfma_f32_16x16x32_bf16 v[92:95], v[230:233], v[194:197], v[92:95]
	v_mfma_f32_16x16x32_bf16 v[88:91], v[238:241], v[194:197], v[88:91]
	v_mfma_f32_16x16x32_bf16 v[84:87], v[230:233], v[202:205], v[84:87]
	v_mfma_f32_16x16x32_bf16 v[80:83], v[238:241], v[202:205], v[80:83]
	v_mfma_f32_16x16x32_bf16 v[76:79], v[230:233], v[214:217], v[76:79]
	v_mfma_f32_16x16x32_bf16 v[72:75], v[238:241], v[214:217], v[72:75]
	v_mfma_f32_16x16x32_bf16 v[68:71], v[230:233], v[222:225], v[68:71]
	v_mfma_f32_16x16x32_bf16 v[64:67], v[238:241], v[222:225], v[64:67]
	v_readfirstlane_b32 s15, v161
	v_lshl_add_u64 v[246:247], v[152:153], 0, s[60:61]
	s_mov_b32 m0, s15
	v_readfirstlane_b32 s15, v162
	s_barrier
	ds_read_b128 v[190:193], v160 offset:16384
	ds_read_b128 v[194:197], v160 offset:17408
	ds_read_b128 v[198:201], v159 offset:16384
	ds_read_b128 v[202:205], v159 offset:17408
	ds_read_b128 v[208:211], v158 offset:16384
	ds_read_b128 v[214:217], v158 offset:17408
	ds_read_b128 v[218:221], v157 offset:16384
	ds_read_b128 v[222:225], v157 offset:17408
	global_load_lds_dwordx4 v[246:247], off
	v_lshl_add_u64 v[246:247], v[154:155], 0, s[60:61]
	s_mov_b32 m0, s15
	s_nop 0
	global_load_lds_dwordx4 v[246:247], off
	s_barrier
	s_waitcnt lgkmcnt(0)
	s_waitcnt lgkmcnt(0)
	v_mfma_f32_16x16x32_bf16 v[60:63], v[136:139], v[190:193], v[60:63]
	v_mfma_f32_16x16x32_bf16 v[56:59], v[182:185], v[190:193], v[56:59]
	v_mfma_f32_16x16x32_bf16 v[52:55], v[136:139], v[198:201], v[52:55]
	v_mfma_f32_16x16x32_bf16 v[48:51], v[182:185], v[198:201], v[48:51]
	v_mfma_f32_16x16x32_bf16 v[44:47], v[136:139], v[208:211], v[44:47]
	v_mfma_f32_16x16x32_bf16 v[40:43], v[182:185], v[208:211], v[40:43]
	v_mfma_f32_16x16x32_bf16 v[36:39], v[136:139], v[218:221], v[36:39]
	v_mfma_f32_16x16x32_bf16 v[32:35], v[182:185], v[218:221], v[32:35]
	v_mfma_f32_16x16x32_bf16 v[60:63], v[178:181], v[194:197], v[60:63]
	v_mfma_f32_16x16x32_bf16 v[56:59], v[186:189], v[194:197], v[56:59]
	v_mfma_f32_16x16x32_bf16 v[52:55], v[178:181], v[202:205], v[52:55]
	v_mfma_f32_16x16x32_bf16 v[48:51], v[186:189], v[202:205], v[48:51]
	v_mfma_f32_16x16x32_bf16 v[44:47], v[178:181], v[214:217], v[44:47]
	v_mfma_f32_16x16x32_bf16 v[40:43], v[186:189], v[214:217], v[40:43]
	v_mfma_f32_16x16x32_bf16 v[36:39], v[178:181], v[222:225], v[36:39]
	v_mfma_f32_16x16x32_bf16 v[32:35], v[186:189], v[222:225], v[32:35]
	s_barrier
; #define STAGE(P, BASE, br, kt) STAGET(tid_, P, BASE, br, kt)
; #define LDA(dst, b, h) UFOR(m, 4) UFOR(k, 2) \
;     dst[m][k] = *reinterpret_cast<const bf16x8*>((char*)SA(b, h) + lds_byte(wr * 64 + m * 16 + fr, k * 32 + fq * 8))
; #define LDB(dst, b, h) UFOR(n, 2) UFOR(k, 2) \
;     dst[n][k] = *reinterpret_cast<const bf16x8*>((char*)SB(b, h) + lds_byte(wc * 32 + n * 16 + fr, k * 32 + fq * 8))
; #define MMA(ai, bj, At, Bq) do { __builtin_amdgcn_s_setprio(1); \
;     UFOR(m, 4) UFOR(n, 2) UFOR(k, 2) \
;       acc[ai][bj][m][n] = __builtin_amdgcn_mfma_f32_16x16x32_bf16(Bq[n][k], At[m][k], acc[ai][bj][m][n], 0, 0, 0); \
;     __builtin_amdgcn_s_setprio(0); } while (0)
; #define WAIT_V(n) asm volatile("s_waitcnt vmcnt(" #n ")" ::: "memory")
; #define WAIT_L(n) asm volatile("s_waitcnt lgkmcnt(" #n ")" ::: "memory")
; #define BAR __builtin_amdgcn_s_barrier()
; #define SCHED __builtin_amdgcn_sched_barrier(0)
; template <int EPI, int K, int KL> ...
;     ...
;     STAGE(SB(0, 1), Bt, bcol + HALF, t + 2);
;     WAIT_V(6); BAR; MMA(1, 1, At, B1); BAR;
;     LDB(B0, 1, 0); SCHED; LDA(At, 1, 0); STAGE(SA(0, 1), A, brow + HALF, t + 2);
;     WAIT_L(8); BAR; WAIT_L(0); MMA(0, 0, At, B0); BAR; SCHED;
;     LDB(B1, 1, 1); STAGE(SB(1, 0), Bt, bcol, t + 3);
;     BAR; WAIT_L(0); MMA(0, 1, At, B1); BAR;
;     LDA(At, 1, 1); STAGE(SA(1, 0), A, brow, t + 3);
;     BAR; WAIT_L(0); MMA(1, 0, At, B0); BAR; SCHED;
;     STAGE(SB(1, 1), Bt, bcol + HALF, t + 3);
;     WAIT_V(6); BAR; MMA(1, 1, At, B1); BAR;
	v_readfirstlane_b32 s15, v164
	v_add_u32_e32 v138, 0x2000, v164
	v_lshl_add_u64 v[136:137], v[242:243], 0, s[24:25]
	s_mov_b32 m0, s15
	v_readfirstlane_b32 s15, v138
	global_load_lds_dwordx4 v[136:137], off
	v_lshl_add_u64 v[136:137], v[244:245], 0, s[24:25]
	s_mov_b32 m0, s15
	s_nop 0
	global_load_lds_dwordx4 v[136:137], off
	s_waitcnt vmcnt(6)
	s_barrier
	v_mfma_f32_16x16x32_bf16 v[28:31], v[226:229], v[190:193], v[28:31]
	v_mfma_f32_16x16x32_bf16 v[24:27], v[234:237], v[190:193], v[24:27]
	v_mfma_f32_16x16x32_bf16 v[20:23], v[226:229], v[198:201], v[20:23]
	v_mfma_f32_16x16x32_bf16 v[16:19], v[234:237], v[198:201], v[16:19]
	v_mfma_f32_16x16x32_bf16 v[12:15], v[226:229], v[208:211], v[12:15]
	v_mfma_f32_16x16x32_bf16 v[8:11], v[234:237], v[208:211], v[8:11]
	v_mfma_f32_16x16x32_bf16 v[4:7], v[226:229], v[218:221], v[4:7]
	v_mfma_f32_16x16x32_bf16 v[0:3], v[234:237], v[218:221], v[0:3]
	v_mfma_f32_16x16x32_bf16 v[28:31], v[230:233], v[194:197], v[28:31]
	v_mfma_f32_16x16x32_bf16 v[24:27], v[238:241], v[194:197], v[24:27]
	v_mfma_f32_16x16x32_bf16 v[20:23], v[230:233], v[202:205], v[20:23]
	v_mfma_f32_16x16x32_bf16 v[16:19], v[238:241], v[202:205], v[16:19]
	v_mfma_f32_16x16x32_bf16 v[12:15], v[230:233], v[214:217], v[12:15]
	v_mfma_f32_16x16x32_bf16 v[8:11], v[238:241], v[214:217], v[8:11]
	v_mfma_f32_16x16x32_bf16 v[4:7], v[230:233], v[222:225], v[4:7]
	v_mfma_f32_16x16x32_bf16 v[0:3], v[238:241], v[222:225], v[0:3]
	s_barrier
	ds_read_b128 v[136:139], v166
	ds_read_b128 v[178:181], v166 offset:1024
	ds_read_b128 v[182:185], v166 offset:2048
	ds_read_b128 v[186:189], v166 offset:3072
	ds_read_b128 v[190:193], v160 offset:32768
	ds_read_b128 v[194:197], v160 offset:33792
	ds_read_b128 v[198:201], v159 offset:32768
	ds_read_b128 v[202:205], v159 offset:33792
	ds_read_b128 v[208:211], v158 offset:32768
	ds_read_b128 v[214:217], v158 offset:33792
	ds_read_b128 v[218:221], v157 offset:32768
	ds_read_b128 v[222:225], v157 offset:33792
	v_readfirstlane_b32 s15, v165
	v_lshl_add_u64 v[226:227], v[152:153], 0, s[62:63]
	s_mov_b32 m0, s15
	v_readfirstlane_b32 s15, v167
	global_load_lds_dwordx4 v[226:227], off
	v_lshl_add_u64 v[226:227], v[154:155], 0, s[62:63]
	s_mov_b32 m0, s15
	s_nop 0
	global_load_lds_dwordx4 v[226:227], off
	s_waitcnt lgkmcnt(8)
	s_barrier
	s_waitcnt lgkmcnt(0)
	s_waitcnt lgkmcnt(0)
	v_mfma_f32_16x16x32_bf16 v[124:127], v[136:139], v[190:193], v[124:127]
	v_mfma_f32_16x16x32_bf16 v[120:123], v[182:185], v[190:193], v[120:123]
	v_mfma_f32_16x16x32_bf16 v[116:119], v[136:139], v[198:201], v[116:119]
	v_mfma_f32_16x16x32_bf16 v[112:115], v[182:185], v[198:201], v[112:115]
	v_mfma_f32_16x16x32_bf16 v[108:111], v[136:139], v[208:211], v[108:111]
	v_mfma_f32_16x16x32_bf16 v[104:107], v[182:185], v[208:211], v[104:107]
	v_mfma_f32_16x16x32_bf16 v[100:103], v[136:139], v[218:221], v[100:103]
	v_mfma_f32_16x16x32_bf16 v[96:99], v[182:185], v[218:221], v[96:99]
	v_mfma_f32_16x16x32_bf16 v[124:127], v[178:181], v[194:197], v[124:127]
	v_mfma_f32_16x16x32_bf16 v[120:123], v[186:189], v[194:197], v[120:123]
	v_mfma_f32_16x16x32_bf16 v[116:119], v[178:181], v[202:205], v[116:119]
	v_mfma_f32_16x16x32_bf16 v[112:115], v[186:189], v[202:205], v[112:115]
	v_mfma_f32_16x16x32_bf16 v[108:111], v[178:181], v[214:217], v[108:111]
	v_mfma_f32_16x16x32_bf16 v[104:107], v[186:189], v[214:217], v[104:107]
	v_mfma_f32_16x16x32_bf16 v[100:103], v[178:181], v[222:225], v[100:103]
	v_mfma_f32_16x16x32_bf16 v[96:99], v[186:189], v[222:225], v[96:99]
	s_barrier
	ds_read_b128 v[226:229], v163
	ds_read_b128 v[230:233], v163 offset:1024
	ds_read_b128 v[234:237], v163 offset:2048
	ds_read_b128 v[238:241], v163 offset:3072
	v_readfirstlane_b32 s15, v168
	v_lshl_add_u64 v[246:247], v[242:243], 0, s[94:95]
	s_mov_b32 m0, s15
	v_readfirstlane_b32 s15, v169
	global_load_lds_dwordx4 v[246:247], off
	v_lshl_add_u64 v[246:247], v[244:245], 0, s[94:95]
	s_mov_b32 m0, s15
	s_nop 0
	global_load_lds_dwordx4 v[246:247], off
	s_barrier
	s_waitcnt lgkmcnt(0)
	s_waitcnt lgkmcnt(0)
	v_mfma_f32_16x16x32_bf16 v[92:95], v[226:229], v[190:193], v[92:95]
	v_mfma_f32_16x16x32_bf16 v[88:91], v[234:237], v[190:193], v[88:91]
	v_mfma_f32_16x16x32_bf16 v[84:87], v[226:229], v[198:201], v[84:87]
	v_mfma_f32_16x16x32_bf16 v[80:83], v[234:237], v[198:201], v[80:83]
	v_mfma_f32_16x16x32_bf16 v[76:79], v[226:229], v[208:211], v[76:79]
	v_mfma_f32_16x16x32_bf16 v[72:75], v[234:237], v[208:211], v[72:75]
	v_mfma_f32_16x16x32_bf16 v[68:71], v[226:229], v[218:221], v[68:71]
	v_mfma_f32_16x16x32_bf16 v[64:67], v[234:237], v[218:221], v[64:67]
	v_mfma_f32_16x16x32_bf16 v[92:95], v[230:233], v[194:197], v[92:95]
	v_mfma_f32_16x16x32_bf16 v[88:91], v[238:241], v[194:197], v[88:91]
	v_mfma_f32_16x16x32_bf16 v[84:87], v[230:233], v[202:205], v[84:87]
	v_mfma_f32_16x16x32_bf16 v[80:83], v[238:241], v[202:205], v[80:83]
	v_mfma_f32_16x16x32_bf16 v[76:79], v[230:233], v[214:217], v[76:79]
	v_mfma_f32_16x16x32_bf16 v[72:75], v[238:241], v[214:217], v[72:75]
	v_mfma_f32_16x16x32_bf16 v[68:71], v[230:233], v[222:225], v[68:71]
	v_mfma_f32_16x16x32_bf16 v[64:67], v[238:241], v[222:225], v[64:67]
	v_readfirstlane_b32 s15, v170
	v_lshl_add_u64 v[152:153], v[152:153], 0, s[64:65]
	s_mov_b32 m0, s15
	v_readfirstlane_b32 s15, v171
	s_barrier
	ds_read_b128 v[190:193], v160 offset:49152
	ds_read_b128 v[194:197], v160 offset:50176
	ds_read_b128 v[198:201], v159 offset:49152
	ds_read_b128 v[202:205], v159 offset:50176
	ds_read_b128 v[208:211], v158 offset:49152
	ds_read_b128 v[214:217], v158 offset:50176
	ds_read_b128 v[218:221], v157 offset:49152
	ds_read_b128 v[222:225], v157 offset:50176
	global_load_lds_dwordx4 v[152:153], off
	v_lshl_add_u64 v[152:153], v[154:155], 0, s[64:65]
	s_mov_b32 m0, s15
	s_nop 0
	global_load_lds_dwordx4 v[152:153], off
	s_barrier
; #define STAGE(P, BASE, br, kt) STAGET(tid_, P, BASE, br, kt)
; #define LDA(dst, b, h) UFOR(m, 4) UFOR(k, 2) \
;     dst[m][k] = *reinterpret_cast<const bf16x8*>((char*)SA(b, h) + lds_byte(wr * 64 + m * 16 + fr, k * 32 + fq * 8))
; #define LDB(dst, b, h) UFOR(n, 2) UFOR(k, 2) \
;     dst[n][k] = *reinterpret_cast<const bf16x8*>((char*)SB(b, h) + lds_byte(wc * 32 + n * 16 + fr, k * 32 + fq * 8))
; #define MMA(ai, bj, At, Bq) do { __builtin_amdgcn_s_setprio(1); \
;     UFOR(m, 4) UFOR(n, 2) UFOR(k, 2) \
;       acc[ai][bj][m][n] = __builtin_amdgcn_mfma_f32_16x16x32_bf16(Bq[n][k], At[m][k], acc[ai][bj][m][n], 0, 0, 0); \
;     __builtin_amdgcn_s_setprio(0); } while (0)
; #define WAIT_V(n) asm volatile("s_waitcnt vmcnt(" #n ")" ::: "memory")
; #define WAIT_L(n) asm volatile("s_waitcnt lgkmcnt(" #n ")" ::: "memory")
; #define BAR __builtin_amdgcn_s_barrier()
; #define SCHED __builtin_amdgcn_sched_barrier(0)
; template <int EPI, int K, int KL> ...
;     ...
;     BAR; WAIT_L(0); MMA(1, 0, At, B0); BAR; SCHED;
;     STAGE(SB(1, 1), Bt, bcol + HALF, t + 3);
;     WAIT_V(6); BAR; MMA(1, 1, At, B1); BAR;
;   }
;   { LDB(B0, 0, 0); LDA(At, 0, 0); STAGE(SA(1, 1), A, brow + HALF, nt - 1);
;     BAR; WAIT_L(0); MMA(0, 0, At, B0); BAR;
;     LDB(B1, 0, 1); BAR; WAIT_L(0); MMA(0, 1, At, B1); BAR;
	s_waitcnt lgkmcnt(0)
	s_waitcnt lgkmcnt(0)
	v_mfma_f32_16x16x32_bf16 v[60:63], v[136:139], v[190:193], v[60:63]
	v_mfma_f32_16x16x32_bf16 v[56:59], v[182:185], v[190:193], v[56:59]
	v_mfma_f32_16x16x32_bf16 v[52:55], v[136:139], v[198:201], v[52:55]
	v_mfma_f32_16x16x32_bf16 v[48:51], v[182:185], v[198:201], v[48:51]
	v_mfma_f32_16x16x32_bf16 v[44:47], v[136:139], v[208:211], v[44:47]
	v_mfma_f32_16x16x32_bf16 v[40:43], v[182:185], v[208:211], v[40:43]
	v_mfma_f32_16x16x32_bf16 v[36:39], v[136:139], v[218:221], v[36:39]
	v_mfma_f32_16x16x32_bf16 v[32:35], v[182:185], v[218:221], v[32:35]
	v_mfma_f32_16x16x32_bf16 v[60:63], v[178:181], v[194:197], v[60:63]
	v_mfma_f32_16x16x32_bf16 v[56:59], v[186:189], v[194:197], v[56:59]
	v_mfma_f32_16x16x32_bf16 v[52:55], v[178:181], v[202:205], v[52:55]
	v_mfma_f32_16x16x32_bf16 v[48:51], v[186:189], v[202:205], v[48:51]
	v_mfma_f32_16x16x32_bf16 v[44:47], v[178:181], v[214:217], v[44:47]
	v_mfma_f32_16x16x32_bf16 v[40:43], v[186:189], v[214:217], v[40:43]
	v_mfma_f32_16x16x32_bf16 v[36:39], v[178:181], v[222:225], v[36:39]
	v_mfma_f32_16x16x32_bf16 v[32:35], v[186:189], v[222:225], v[32:35]
	v_readfirstlane_b32 s15, v172
	s_mov_b32 m0, s15
	v_readfirstlane_b32 s15, v174
	s_barrier
	v_lshl_add_u64 v[136:137], v[242:243], 0, s[10:11]
	global_load_lds_dwordx4 v[136:137], off
	v_lshl_add_u64 v[136:137], v[244:245], 0, s[10:11]
	s_mov_b32 m0, s15
	s_nop 0
	global_load_lds_dwordx4 v[136:137], off
	s_waitcnt vmcnt(6)
	s_barrier
	v_mfma_f32_16x16x32_bf16 v[28:31], v[226:229], v[190:193], v[28:31]
	v_mfma_f32_16x16x32_bf16 v[24:27], v[234:237], v[190:193], v[24:27]
	v_mfma_f32_16x16x32_bf16 v[20:23], v[226:229], v[198:201], v[20:23]
	v_mfma_f32_16x16x32_bf16 v[16:19], v[234:237], v[198:201], v[16:19]
	v_mfma_f32_16x16x32_bf16 v[12:15], v[226:229], v[208:211], v[12:15]
	v_mfma_f32_16x16x32_bf16 v[8:11], v[234:237], v[208:211], v[8:11]
	v_mfma_f32_16x16x32_bf16 v[4:7], v[226:229], v[218:221], v[4:7]
	v_mfma_f32_16x16x32_bf16 v[0:3], v[234:237], v[218:221], v[0:3]
	v_mfma_f32_16x16x32_bf16 v[28:31], v[230:233], v[194:197], v[28:31]
	v_mfma_f32_16x16x32_bf16 v[24:27], v[238:241], v[194:197], v[24:27]
	v_mfma_f32_16x16x32_bf16 v[20:23], v[230:233], v[202:205], v[20:23]
	v_mfma_f32_16x16x32_bf16 v[16:19], v[238:241], v[202:205], v[16:19]
	v_mfma_f32_16x16x32_bf16 v[12:15], v[230:233], v[214:217], v[12:15]
	v_mfma_f32_16x16x32_bf16 v[8:11], v[238:241], v[214:217], v[8:11]
	v_mfma_f32_16x16x32_bf16 v[4:7], v[230:233], v[222:225], v[4:7]
	v_mfma_f32_16x16x32_bf16 v[0:3], v[238:241], v[222:225], v[0:3]
	s_add_i32 s14, s14, 2
	v_lshl_add_u64 v[144:145], v[144:145], 0, s[20:21]
	v_lshl_add_u64 v[146:147], v[146:147], 0, s[20:21]
	v_lshl_add_u64 v[148:149], v[148:149], 0, s[20:21]
	s_cmp_lt_u32 s14, 4
	v_lshl_add_u64 v[150:151], v[150:151], 0, s[20:21]
	s_cbranch_scc1 .Lkrot_1204
	s_barrier
	s_add_u32 s14, s46, 0x160380
	s_addc_u32 s15, s47, 0
	v_lshl_add_u64 v[142:143], s[14:15], 0, v[142:143]
	v_readfirstlane_b32 s18, v176
	v_lshl_add_u64 v[128:129], v[128:129], 1, v[142:143]
	s_mov_b32 m0, s18
	ds_read_b128 v[136:139], v175
	ds_read_b128 v[144:147], v175 offset:1024
	ds_read_b128 v[148:151], v175 offset:2048
	ds_read_b128 v[168:171], v175 offset:3072
	ds_read_b128 v[178:181], v160
	ds_read_b128 v[182:185], v160 offset:1024
	ds_read_b128 v[186:189], v159
	ds_read_b128 v[190:193], v159 offset:1024
	ds_read_b128 v[194:197], v158
	ds_read_b128 v[198:201], v158 offset:1024
	ds_read_b128 v[202:205], v157
	ds_read_b128 v[208:211], v157 offset:1024
	global_load_lds_dwordx4 v[128:129], off
	v_lshl_add_u64 v[128:129], s[14:15], 0, v[140:141]
	v_readfirstlane_b32 s14, v177
	v_lshl_add_u64 v[128:129], v[130:131], 1, v[128:129]
	s_mov_b32 m0, s14
	s_nop 0
	global_load_lds_dwordx4 v[128:129], off
	s_barrier
	s_waitcnt lgkmcnt(0)
	s_waitcnt lgkmcnt(0)
	v_mfma_f32_16x16x32_bf16 v[124:127], v[136:139], v[178:181], v[124:127]
	v_mfma_f32_16x16x32_bf16 v[120:123], v[148:151], v[178:181], v[120:123]
	v_mfma_f32_16x16x32_bf16 v[116:119], v[136:139], v[186:189], v[116:119]
	v_mfma_f32_16x16x32_bf16 v[112:115], v[148:151], v[186:189], v[112:115]
	v_mfma_f32_16x16x32_bf16 v[108:111], v[136:139], v[194:197], v[108:111]
	v_mfma_f32_16x16x32_bf16 v[104:107], v[148:151], v[194:197], v[104:107]
	v_mfma_f32_16x16x32_bf16 v[100:103], v[136:139], v[202:205], v[100:103]
	v_mfma_f32_16x16x32_bf16 v[96:99], v[148:151], v[202:205], v[96:99]
	v_mfma_f32_16x16x32_bf16 v[124:127], v[144:147], v[182:185], v[124:127]
	v_mfma_f32_16x16x32_bf16 v[120:123], v[168:171], v[182:185], v[120:123]
	v_mfma_f32_16x16x32_bf16 v[116:119], v[144:147], v[190:193], v[116:119]
	v_mfma_f32_16x16x32_bf16 v[112:115], v[168:171], v[190:193], v[112:115]
	v_mfma_f32_16x16x32_bf16 v[108:111], v[144:147], v[198:201], v[108:111]
	v_mfma_f32_16x16x32_bf16 v[104:107], v[168:171], v[198:201], v[104:107]
	v_mfma_f32_16x16x32_bf16 v[100:103], v[144:147], v[208:211], v[100:103]
	v_mfma_f32_16x16x32_bf16 v[96:99], v[168:171], v[208:211], v[96:99]
	s_barrier
	ds_read_b128 v[128:131], v173
	ds_read_b128 v[140:143], v173 offset:1024
	ds_read_b128 v[174:177], v173 offset:2048
	ds_read_b128 v[214:217], v173 offset:3072
	s_barrier
; #define LDA(dst, b, h) UFOR(m, 4) UFOR(k, 2) \
;     dst[m][k] = *reinterpret_cast<const bf16x8*>((char*)SA(b, h) + lds_byte(wr * 64 + m * 16 + fr, k * 32 + fq * 8))
; #define LDB(dst, b, h) UFOR(n, 2) UFOR(k, 2) \
;     dst[n][k] = *reinterpret_cast<const bf16x8*>((char*)SB(b, h) + lds_byte(wc * 32 + n * 16 + fr, k * 32 + fq * 8))
; #define MMA(ai, bj, At, Bq) do { __builtin_amdgcn_s_setprio(1); \
;     UFOR(m, 4) UFOR(n, 2) UFOR(k, 2) \
;       acc[ai][bj][m][n] = __builtin_amdgcn_mfma_f32_16x16x32_bf16(Bq[n][k], At[m][k], acc[ai][bj][m][n], 0, 0, 0); \
;     __builtin_amdgcn_s_setprio(0); } while (0)
; #define WAIT_V(n) asm volatile("s_waitcnt vmcnt(" #n ")" ::: "memory")
; #define WAIT_L(n) asm volatile("s_waitcnt lgkmcnt(" #n ")" ::: "memory")
; #define BAR __builtin_amdgcn_s_barrier()
; template <int EPI, int K, int KL> ...
;     ...
;     LDB(B1, 0, 1); BAR; WAIT_L(0); MMA(0, 1, At, B1); BAR;
;     LDA(At, 0, 1); WAIT_V(4); BAR; WAIT_L(0); MMA(1, 0, At, B0); MMA(1, 1, At, B1); BAR; }
;   { LDB(B0, 1, 0); LDA(At, 1, 0); WAIT_V(2); BAR; WAIT_L(0); MMA(0, 0, At, B0); BAR;
	s_waitcnt lgkmcnt(0)
	s_waitcnt lgkmcnt(0)
	v_mfma_f32_16x16x32_bf16 v[92:95], v[128:131], v[178:181], v[92:95]
	v_mfma_f32_16x16x32_bf16 v[88:91], v[174:177], v[178:181], v[88:91]
	v_mfma_f32_16x16x32_bf16 v[84:87], v[128:131], v[186:189], v[84:87]
	v_mfma_f32_16x16x32_bf16 v[80:83], v[174:177], v[186:189], v[80:83]
	v_mfma_f32_16x16x32_bf16 v[76:79], v[128:131], v[194:197], v[76:79]
	v_mfma_f32_16x16x32_bf16 v[68:71], v[128:131], v[202:205], v[68:71]
	v_mfma_f32_16x16x32_bf16 v[64:67], v[174:177], v[202:205], v[64:67]
	v_mfma_f32_16x16x32_bf16 v[92:95], v[140:143], v[182:185], v[92:95]
	v_mfma_f32_16x16x32_bf16 v[88:91], v[214:217], v[182:185], v[88:91]
	v_mfma_f32_16x16x32_bf16 v[84:87], v[140:143], v[190:193], v[84:87]
	v_mfma_f32_16x16x32_bf16 v[80:83], v[214:217], v[190:193], v[80:83]
	v_mfma_f32_16x16x32_bf16 v[76:79], v[140:143], v[198:201], v[76:79]
	v_mfma_f32_16x16x32_bf16 v[72:75], v[174:177], v[194:197], v[72:75]
	v_mfma_f32_16x16x32_bf16 v[68:71], v[140:143], v[208:211], v[68:71]
	v_mfma_f32_16x16x32_bf16 v[64:67], v[214:217], v[208:211], v[64:67]
	v_mfma_f32_16x16x32_bf16 v[178:181], v[214:217], v[198:201], v[72:75]
	s_barrier
	s_nop 3
	ds_read_b128 v[72:75], v160 offset:16384
	ds_read_b128 v[182:185], v160 offset:17408
	ds_read_b128 v[186:189], v159 offset:16384
	ds_read_b128 v[190:193], v159 offset:17408
	ds_read_b128 v[194:197], v158 offset:16384
	ds_read_b128 v[198:201], v158 offset:17408
	ds_read_b128 v[202:205], v157 offset:16384
	ds_read_b128 v[208:211], v157 offset:17408
	s_waitcnt vmcnt(4)
	s_barrier
	s_waitcnt lgkmcnt(0)
	s_waitcnt lgkmcnt(0)
	v_mfma_f32_16x16x32_bf16 v[48:51], v[148:151], v[186:189], v[48:51]
	v_mfma_f32_16x16x32_bf16 v[60:63], v[136:139], v[72:75], v[60:63]
	v_mfma_f32_16x16x32_bf16 v[56:59], v[148:151], v[72:75], v[56:59]
	v_mfma_f32_16x16x32_bf16 v[52:55], v[136:139], v[186:189], v[52:55]
	v_mfma_f32_16x16x32_bf16 v[48:51], v[168:171], v[190:193], v[48:51]
	v_mfma_f32_16x16x32_bf16 v[44:47], v[136:139], v[194:197], v[44:47]
	v_mfma_f32_16x16x32_bf16 v[40:43], v[148:151], v[194:197], v[40:43]
	v_mfma_f32_16x16x32_bf16 v[36:39], v[136:139], v[202:205], v[36:39]
	v_mfma_f32_16x16x32_bf16 v[32:35], v[148:151], v[202:205], v[32:35]
	v_mfma_f32_16x16x32_bf16 v[218:221], v[144:147], v[182:185], v[60:63]
	v_mfma_f32_16x16x32_bf16 v[222:225], v[168:171], v[182:185], v[56:59]
	v_mfma_f32_16x16x32_bf16 v[226:229], v[144:147], v[190:193], v[52:55]
	v_mfma_f32_16x16x32_bf16 v[230:233], v[144:147], v[198:201], v[44:47]
	v_mfma_f32_16x16x32_bf16 v[234:237], v[168:171], v[198:201], v[40:43]
	v_mfma_f32_16x16x32_bf16 v[136:139], v[144:147], v[208:211], v[36:39]
	v_mfma_f32_16x16x32_bf16 v[144:147], v[168:171], v[208:211], v[32:35]
	v_mfma_f32_16x16x32_bf16 v[28:31], v[128:131], v[72:75], v[28:31]
	v_mfma_f32_16x16x32_bf16 v[24:27], v[174:177], v[72:75], v[24:27]
	v_mfma_f32_16x16x32_bf16 v[20:23], v[128:131], v[186:189], v[20:23]
	v_mfma_f32_16x16x32_bf16 v[16:19], v[174:177], v[186:189], v[16:19]
	v_mfma_f32_16x16x32_bf16 v[12:15], v[128:131], v[194:197], v[12:15]
	v_mfma_f32_16x16x32_bf16 v[8:11], v[174:177], v[194:197], v[8:11]
	v_mfma_f32_16x16x32_bf16 v[4:7], v[128:131], v[202:205], v[4:7]
	v_mfma_f32_16x16x32_bf16 v[0:3], v[174:177], v[202:205], v[0:3]
	v_mfma_f32_16x16x32_bf16 v[148:151], v[140:143], v[182:185], v[28:31]
	v_mfma_f32_16x16x32_bf16 v[168:171], v[214:217], v[182:185], v[24:27]
	v_mfma_f32_16x16x32_bf16 v[182:185], v[140:143], v[190:193], v[20:23]
	v_mfma_f32_16x16x32_bf16 v[186:189], v[214:217], v[190:193], v[16:19]
	v_mfma_f32_16x16x32_bf16 v[190:193], v[140:143], v[198:201], v[12:15]
	v_mfma_f32_16x16x32_bf16 v[194:197], v[214:217], v[198:201], v[8:11]
	v_mfma_f32_16x16x32_bf16 v[128:131], v[140:143], v[208:211], v[4:7]
	v_mfma_f32_16x16x32_bf16 v[140:143], v[214:217], v[208:211], v[0:3]
	s_barrier
	ds_read_b128 v[172:175], v166
	ds_read_b128 v[198:201], v166 offset:1024
	ds_read_b128 v[202:205], v166 offset:2048
	ds_read_b128 v[164:167], v166 offset:3072
	ds_read_b128 v[20:23], v160 offset:32768
	ds_read_b128 v[24:27], v160 offset:33792
	ds_read_b128 v[28:31], v159 offset:32768
	ds_read_b128 v[32:35], v159 offset:33792
	ds_read_b128 v[36:39], v158 offset:32768
	ds_read_b128 v[208:211], v158 offset:33792
	ds_read_b128 v[214:217], v157 offset:32768
	ds_read_b128 v[238:241], v157 offset:33792
	s_waitcnt vmcnt(2)
	s_barrier
; #define LDA(dst, b, h) UFOR(m, 4) UFOR(k, 2) \
;     dst[m][k] = *reinterpret_cast<const bf16x8*>((char*)SA(b, h) + lds_byte(wr * 64 + m * 16 + fr, k * 32 + fq * 8))
; #define LDB(dst, b, h) UFOR(n, 2) UFOR(k, 2) \
;     dst[n][k] = *reinterpret_cast<const bf16x8*>((char*)SB(b, h) + lds_byte(wc * 32 + n * 16 + fr, k * 32 + fq * 8))
; #define MMA(ai, bj, At, Bq) do { __builtin_amdgcn_s_setprio(1); \
;     UFOR(m, 4) UFOR(n, 2) UFOR(k, 2) \
;       acc[ai][bj][m][n] = __builtin_amdgcn_mfma_f32_16x16x32_bf16(Bq[n][k], At[m][k], acc[ai][bj][m][n], 0, 0, 0); \
;     __builtin_amdgcn_s_setprio(0); } while (0)
; #define WAIT_V(n) asm volatile("s_waitcnt vmcnt(" #n ")" ::: "memory")
; #define WAIT_L(n) asm volatile("s_waitcnt lgkmcnt(" #n ")" ::: "memory")
; #define BAR __builtin_amdgcn_s_barrier()
; template <int EPI, int K, int KL> ...
;     ...
;   { LDB(B0, 1, 0); LDA(At, 1, 0); WAIT_V(2); BAR; WAIT_L(0); MMA(0, 0, At, B0); BAR;
;     LDB(B1, 1, 1); WAIT_V(0); BAR; WAIT_L(0); MMA(0, 1, At, B1); BAR;
;     LDA(At, 1, 1); BAR; WAIT_L(0); MMA(1, 0, At, B0); MMA(1, 1, At, B1); BAR; }
;   if (wr == 0) BAR;
	s_waitcnt lgkmcnt(0)
	s_waitcnt lgkmcnt(0)
	v_mfma_f32_16x16x32_bf16 v[0:3], v[172:175], v[20:23], v[124:127]
	v_mfma_f32_16x16x32_bf16 v[44:47], v[198:201], v[24:27], v[0:3]
	v_mfma_f32_16x16x32_bf16 v[0:3], v[202:205], v[20:23], v[120:123]
	v_mfma_f32_16x16x32_bf16 v[52:55], v[164:167], v[24:27], v[0:3]
	v_mfma_f32_16x16x32_bf16 v[0:3], v[172:175], v[28:31], v[116:119]
	v_mfma_f32_16x16x32_bf16 v[40:43], v[198:201], v[32:35], v[0:3]
	v_mfma_f32_16x16x32_bf16 v[0:3], v[202:205], v[28:31], v[112:115]
	v_mfma_f32_16x16x32_bf16 v[16:19], v[164:167], v[32:35], v[0:3]
	v_mfma_f32_16x16x32_bf16 v[0:3], v[172:175], v[36:39], v[108:111]
	v_mfma_f32_16x16x32_bf16 v[8:11], v[198:201], v[208:211], v[0:3]
	v_mfma_f32_16x16x32_bf16 v[0:3], v[202:205], v[36:39], v[104:107]
	v_mfma_f32_16x16x32_bf16 v[12:15], v[164:167], v[208:211], v[0:3]
	v_mfma_f32_16x16x32_bf16 v[0:3], v[172:175], v[214:217], v[100:103]
	v_mfma_f32_16x16x32_bf16 v[4:7], v[202:205], v[214:217], v[96:99]
	v_mfma_f32_16x16x32_bf16 v[0:3], v[198:201], v[238:241], v[0:3]
	v_mfma_f32_16x16x32_bf16 v[4:7], v[164:167], v[238:241], v[4:7]
	s_barrier
	ds_read_b128 v[108:111], v163
	ds_read_b128 v[242:245], v163 offset:1024
	ds_read_b128 v[246:249], v163 offset:2048
	ds_read_b128 v[152:155], v163 offset:3072
	s_waitcnt vmcnt(0)
	s_barrier
	s_waitcnt lgkmcnt(0)
	s_waitcnt lgkmcnt(0)
	v_mfma_f32_16x16x32_bf16 v[56:59], v[108:111], v[20:23], v[92:95]
	v_mfma_f32_16x16x32_bf16 v[20:23], v[246:249], v[20:23], v[88:91]
	v_mfma_f32_16x16x32_bf16 v[72:75], v[152:155], v[24:27], v[20:23]
	v_mfma_f32_16x16x32_bf16 v[20:23], v[108:111], v[28:31], v[84:87]
	v_mfma_f32_16x16x32_bf16 v[60:63], v[242:245], v[24:27], v[56:59]
	v_mfma_f32_16x16x32_bf16 v[56:59], v[242:245], v[32:35], v[20:23]
	v_mfma_f32_16x16x32_bf16 v[20:23], v[246:249], v[28:31], v[80:83]
	v_mfma_f32_16x16x32_bf16 v[20:23], v[152:155], v[32:35], v[20:23]
	v_mfma_f32_16x16x32_bf16 v[24:27], v[108:111], v[36:39], v[76:79]
	v_mfma_f32_16x16x32_bf16 v[28:31], v[246:249], v[36:39], v[178:181]
	v_mfma_f32_16x16x32_bf16 v[32:35], v[108:111], v[214:217], v[68:71]
	v_mfma_f32_16x16x32_bf16 v[36:39], v[246:249], v[214:217], v[64:67]
	v_mfma_f32_16x16x32_bf16 v[24:27], v[242:245], v[208:211], v[24:27]
	v_mfma_f32_16x16x32_bf16 v[28:31], v[152:155], v[208:211], v[28:31]
	v_mfma_f32_16x16x32_bf16 v[32:35], v[242:245], v[238:241], v[32:35]
	v_mfma_f32_16x16x32_bf16 v[36:39], v[152:155], v[238:241], v[36:39]
	s_barrier
	ds_read_b128 v[88:91], v160 offset:49152
	ds_read_b128 v[92:95], v160 offset:50176
	ds_read_b128 v[96:99], v159 offset:49152
	ds_read_b128 v[100:103], v159 offset:50176
	ds_read_b128 v[104:107], v158 offset:49152
	ds_read_b128 v[158:161], v158 offset:50176
	ds_read_b128 v[176:179], v157 offset:49152
	ds_read_b128 v[208:211], v157 offset:50176
	s_barrier
	s_waitcnt lgkmcnt(0)
	s_waitcnt lgkmcnt(0)
	v_mfma_f32_16x16x32_bf16 v[48:51], v[202:205], v[96:99], v[48:51]
	v_mfma_f32_16x16x32_bf16 v[64:67], v[172:175], v[88:91], v[218:221]
	v_mfma_f32_16x16x32_bf16 v[116:119], v[164:167], v[100:103], v[48:51]
	v_mfma_f32_16x16x32_bf16 v[48:51], v[172:175], v[104:107], v[230:233]
	v_mfma_f32_16x16x32_bf16 v[120:123], v[198:201], v[92:95], v[64:67]
	v_mfma_f32_16x16x32_bf16 v[64:67], v[202:205], v[88:91], v[222:225]
	v_mfma_f32_16x16x32_bf16 v[76:79], v[198:201], v[158:161], v[48:51]
	v_mfma_f32_16x16x32_bf16 v[48:51], v[202:205], v[104:107], v[234:237]
	v_mfma_f32_16x16x32_bf16 v[124:127], v[164:167], v[92:95], v[64:67]
	v_mfma_f32_16x16x32_bf16 v[64:67], v[172:175], v[96:99], v[226:229]
	v_mfma_f32_16x16x32_bf16 v[80:83], v[164:167], v[158:161], v[48:51]
	v_mfma_f32_16x16x32_bf16 v[48:51], v[172:175], v[176:179], v[136:139]
	v_mfma_f32_16x16x32_bf16 v[112:115], v[198:201], v[100:103], v[64:67]
	v_mfma_f32_16x16x32_bf16 v[64:67], v[198:201], v[208:211], v[48:51]
	v_mfma_f32_16x16x32_bf16 v[48:51], v[202:205], v[176:179], v[144:147]
	v_mfma_f32_16x16x32_bf16 v[68:71], v[164:167], v[208:211], v[48:51]
	v_mfma_f32_16x16x32_bf16 v[48:51], v[108:111], v[88:91], v[148:151]
	v_mfma_f32_16x16x32_bf16 v[84:87], v[242:245], v[92:95], v[48:51]
	v_mfma_f32_16x16x32_bf16 v[48:51], v[246:249], v[88:91], v[168:171]
	v_mfma_f32_16x16x32_bf16 v[88:91], v[152:155], v[92:95], v[48:51]
	v_mfma_f32_16x16x32_bf16 v[48:51], v[108:111], v[96:99], v[182:185]
	v_mfma_f32_16x16x32_bf16 v[92:95], v[242:245], v[100:103], v[48:51]
	v_mfma_f32_16x16x32_bf16 v[48:51], v[246:249], v[96:99], v[186:189]
	v_mfma_f32_16x16x32_bf16 v[96:99], v[152:155], v[100:103], v[48:51]
	v_mfma_f32_16x16x32_bf16 v[48:51], v[108:111], v[104:107], v[190:193]
	v_mfma_f32_16x16x32_bf16 v[100:103], v[242:245], v[158:161], v[48:51]
	v_mfma_f32_16x16x32_bf16 v[48:51], v[246:249], v[104:107], v[194:197]
	v_mfma_f32_16x16x32_bf16 v[104:107], v[152:155], v[158:161], v[48:51]
	v_mfma_f32_16x16x32_bf16 v[48:51], v[108:111], v[176:179], v[128:131]
	v_mfma_f32_16x16x32_bf16 v[108:111], v[242:245], v[208:211], v[48:51]
	v_mfma_f32_16x16x32_bf16 v[48:51], v[246:249], v[176:179], v[140:143]
	v_mfma_f32_16x16x32_bf16 v[48:51], v[152:155], v[208:211], v[48:51]
	s_movk_i32 s14, 0x100
	v_cmp_gt_u32_e32 vcc, s14, v132
	s_barrier
	s_and_saveexec_b64 s[44:45], vcc
	s_cbranch_execz .LBB0_1200
	s_barrier
	s_branch .LBB0_1200
